# v15 seams plus GEMM loops: s_setprio moved outside the barrier-to-barrier MFMA window, redundant lgkmcnt wait and mid-block priority flips removed
# speedup vs baseline: 1.0101x; 1.0044x over previous
; #define PG8_STAGE(bufoff, gbase, voff) do { _Pragma("unroll") for (int _i = 0; _i < 2; ++_i) \
;         __builtin_amdgcn_global_load_lds((const unsigned*)((const char*)(gbase) + (voff)[_i]), (PG8_LAS unsigned*)(lds + (bufoff) + ldsw + _i * 8192), 16, 0, 0); } while (0)
; #define PG8_LDA(dst, b, h) do { _Pragma("unroll") for (int m = 0; m < 4; ++m) _Pragma("unroll") for (int k = 0; k < 2; ++k) dst[m][k] = *(const PG8_LAS bf16x8*)(lds + PG8_SA(b, h) + aoff + m * 2048 + k * 1024); } while (0)
; #define PG8_LDB(dst, b, h) do { _Pragma("unroll") for (int n = 0; n < 2; ++n) _Pragma("unroll") for (int k = 0; k < 2; ++k) dst[n][k] = *(const PG8_LAS bf16x8*)(lds + PG8_SB(b, h) + boff + n * 2048 + k * 1024); } while (0)
; #define PG8_WAIT_V(n) asm volatile("s_waitcnt vmcnt(" #n ")" ::: "memory")
; #define PG8_WAIT_L(n) asm volatile("s_waitcnt lgkmcnt(" #n ")" ::: "memory")
; #define PG8_BAR __builtin_amdgcn_s_barrier()
; #define PG8_SCHED __builtin_amdgcn_sched_barrier(0)
; template <class Epi, class Sched, bool ALIGN_EPI = false, bool SP2 = false>
; __device__ __forceinline__ void gemm_phase(PG8_LAS unsigned char* lds, const Gemm g, const Sched& S, const Epi& E) {
;     ...
;         const bool has_next = S.next(ui + 1, nxt);
;         const char* nA = has_next ? (const char*)g.A + (size_t)nxt.pm * tstep : cA; const char* nB = has_next ? (const char*)g.Bt + (size_t)nxt.pn * tstep : cB;
;         for (int t = 0; t < nt; t += 2) {
;             const bool last = (t == nt - 2);
;             const char* a1 = cA + (size_t)(t + 1) * kstep;
;             const char* a2 = last ? nA : cA + (size_t)(t + 2) * kstep; const char* b2 = last ? nB : cB + (size_t)(t + 2) * kstep;
;             const char* a3 = a2 + kstep; const char* b3 = b2 + kstep;
;             if (last && has_next) S.a_ready(nxt);
;             if constexpr (SP2) {
;             PG8_LDB(B0, 0, 0); PG8_LDB(B1, 0, 1); PG8_SCHED; PG8_LDA(At, 0, 0); PG8_STAGE(PG8_SA(1, 1), a1 + hstep, voffA);
;             PG8_WAIT_V(8); PG8_WAIT_L(0); PG8_BAR; PG8_MMA(0, 0, At, B0); PG8_MMA(0, 1, At, B1); PG8_BAR; PG8_SCHED;
;             PG8_LDA(At, 0, 1); PG8_STAGE(PG8_SB(0, 0), b2, voffB); PG8_STAGE(PG8_SB(0, 1), b2 + hstep, voffB); PG8_STAGE(PG8_SA(0, 0), a2, voffA);
;             PG8_WAIT_V(8); PG8_WAIT_L(0); PG8_BAR; PG8_MMA(1, 0, At, B0); PG8_MMA(1, 1, At, B1); PG8_BAR; PG8_SCHED;
.LBB0_127:
	ds_read_b128 v[146:149], v167
	ds_read_b128 v[150:153], v167 offset:1024
	ds_read_b128 v[168:171], v167 offset:2048
	ds_read_b128 v[178:181], v167 offset:3072
	ds_read_b128 v[182:185], v173
	ds_read_b128 v[186:189], v173 offset:1024
	ds_read_b128 v[190:193], v173 offset:2048
	ds_read_b128 v[194:197], v173 offset:3072
	s_add_u32 s67, s90, 0xfff80080
	s_addc_u32 s74, s91, -1
	s_cmp_eq_u32 s66, 28
	s_cselect_b32 s95, s12, s74
	s_cselect_b32 s94, s13, s67
	s_cselect_b32 s93, s71, vcc_hi
	s_cselect_b32 s92, s73, vcc_lo
	v_lshl_add_u64 v[156:157], s[90:91], 0, v[138:139]
	s_add_i32 m0, s15, 0xc000
	ds_read_b128 v[198:201], v175
	ds_read_b128 v[202:205], v175 offset:1024
	ds_read_b128 v[206:209], v175 offset:2048
	ds_read_b128 v[210:213], v175 offset:3072
	ds_read_b128 v[218:221], v175 offset:4096
	ds_read_b128 v[224:227], v175 offset:5120
	ds_read_b128 v[228:231], v175 offset:6144
	ds_read_b128 v[232:235], v175 offset:7168
	global_load_lds_dwordx4 v[156:157], off
	v_lshl_add_u64 v[156:157], s[90:91], 0, v[140:141]
	s_add_i32 m0, s15, 0xe000
	s_nop 0
	global_load_lds_dwordx4 v[156:157], off
	s_waitcnt vmcnt(8)
	s_waitcnt lgkmcnt(0)
	s_setprio 1
	s_barrier
	v_mfma_f32_16x16x32_bf16 v[124:127], v[146:149], v[198:201], v[124:127]
	v_mfma_f32_16x16x32_bf16 v[120:123], v[168:171], v[198:201], v[120:123]
	v_mfma_f32_16x16x32_bf16 v[108:111], v[146:149], v[206:209], v[108:111]
	v_mfma_f32_16x16x32_bf16 v[104:107], v[168:171], v[206:209], v[104:107]
	v_mfma_f32_16x16x32_bf16 v[92:95], v[146:149], v[218:221], v[92:95]
	v_mfma_f32_16x16x32_bf16 v[88:91], v[168:171], v[218:221], v[88:91]
	v_mfma_f32_16x16x32_bf16 v[76:79], v[146:149], v[228:231], v[76:79]
	v_mfma_f32_16x16x32_bf16 v[72:75], v[168:171], v[228:231], v[72:75]
	v_mfma_f32_16x16x32_bf16 v[124:127], v[150:153], v[202:205], v[124:127]
	v_mfma_f32_16x16x32_bf16 v[120:123], v[178:181], v[202:205], v[120:123]
	v_mfma_f32_16x16x32_bf16 v[108:111], v[150:153], v[210:213], v[108:111]
	v_mfma_f32_16x16x32_bf16 v[104:107], v[178:181], v[210:213], v[104:107]
	v_mfma_f32_16x16x32_bf16 v[92:95], v[150:153], v[224:227], v[92:95]
	v_mfma_f32_16x16x32_bf16 v[88:91], v[178:181], v[224:227], v[88:91]
	v_mfma_f32_16x16x32_bf16 v[76:79], v[150:153], v[232:235], v[76:79]
	v_mfma_f32_16x16x32_bf16 v[72:75], v[178:181], v[232:235], v[72:75]
	v_mfma_f32_16x16x32_bf16 v[116:119], v[182:185], v[198:201], v[116:119]
	v_mfma_f32_16x16x32_bf16 v[112:115], v[190:193], v[198:201], v[112:115]
	v_mfma_f32_16x16x32_bf16 v[100:103], v[182:185], v[206:209], v[100:103]
	v_mfma_f32_16x16x32_bf16 v[96:99], v[190:193], v[206:209], v[96:99]
	v_mfma_f32_16x16x32_bf16 v[84:87], v[182:185], v[218:221], v[84:87]
	v_mfma_f32_16x16x32_bf16 v[80:83], v[190:193], v[218:221], v[80:83]
	v_mfma_f32_16x16x32_bf16 v[68:71], v[182:185], v[228:231], v[68:71]
	v_mfma_f32_16x16x32_bf16 v[64:67], v[190:193], v[228:231], v[64:67]
	v_mfma_f32_16x16x32_bf16 v[116:119], v[186:189], v[202:205], v[116:119]
	v_mfma_f32_16x16x32_bf16 v[112:115], v[194:197], v[202:205], v[112:115]
	v_mfma_f32_16x16x32_bf16 v[100:103], v[186:189], v[210:213], v[100:103]
	v_mfma_f32_16x16x32_bf16 v[96:99], v[194:197], v[210:213], v[96:99]
	v_mfma_f32_16x16x32_bf16 v[84:87], v[186:189], v[224:227], v[84:87]
	v_mfma_f32_16x16x32_bf16 v[80:83], v[194:197], v[224:227], v[80:83]
	v_mfma_f32_16x16x32_bf16 v[68:71], v[186:189], v[232:235], v[68:71]
	v_mfma_f32_16x16x32_bf16 v[64:67], v[194:197], v[232:235], v[64:67]
	s_barrier
	s_setprio 0
	s_add_i32 s67, s81, s3
	v_lshl_add_u64 v[156:157], s[92:93], 0, v[132:133]
	s_mov_b32 m0, s67
	ds_read_b128 v[198:201], v175 offset:16384
	ds_read_b128 v[202:205], v175 offset:17408
	ds_read_b128 v[206:209], v175 offset:18432
	ds_read_b128 v[210:213], v175 offset:19456
	ds_read_b128 v[218:221], v175 offset:20480
	ds_read_b128 v[224:227], v175 offset:21504
	ds_read_b128 v[228:231], v175 offset:22528
	ds_read_b128 v[232:235], v175 offset:23552
	global_load_lds_dwordx4 v[156:157], off
	s_add_i32 m0, s67, 0x2000
	s_add_u32 s74, s92, 0x80000
	v_lshl_add_u64 v[160:161], s[92:93], 0, v[128:129]
	s_addc_u32 s75, s93, 0
	s_add_i32 s67, s89, s3
	global_load_lds_dwordx4 v[160:161], off
	v_lshl_add_u64 v[164:165], s[74:75], 0, v[132:133]
	s_mov_b32 m0, s67
	v_lshl_add_u64 v[214:215], s[94:95], 0, v[130:131]
	global_load_lds_dwordx4 v[164:165], off
	v_lshl_add_u64 v[164:165], s[74:75], 0, v[128:129]
	s_add_i32 m0, s67, 0x2000
	s_nop 0
	global_load_lds_dwordx4 v[164:165], off
	v_lshl_add_u64 v[164:165], s[94:95], 0, v[134:135]
	s_mov_b32 m0, s15
	s_nop 0
	global_load_lds_dwordx4 v[164:165], off
	s_mov_b32 m0, s34
	s_nop 0
	global_load_lds_dwordx4 v[214:215], off
	s_waitcnt vmcnt(8)
	s_waitcnt lgkmcnt(0)
	s_setprio 1
	s_barrier
; #define PG8_STAGE(bufoff, gbase, voff) do { _Pragma("unroll") for (int _i = 0; _i < 2; ++_i) \
;         __builtin_amdgcn_global_load_lds((const unsigned*)((const char*)(gbase) + (voff)[_i]), (PG8_LAS unsigned*)(lds + (bufoff) + ldsw + _i * 8192), 16, 0, 0); } while (0)
; #define PG8_LDA(dst, b, h) do { _Pragma("unroll") for (int m = 0; m < 4; ++m) _Pragma("unroll") for (int k = 0; k < 2; ++k) dst[m][k] = *(const PG8_LAS bf16x8*)(lds + PG8_SA(b, h) + aoff + m * 2048 + k * 1024); } while (0)
; #define PG8_LDB(dst, b, h) do { _Pragma("unroll") for (int n = 0; n < 2; ++n) _Pragma("unroll") for (int k = 0; k < 2; ++k) dst[n][k] = *(const PG8_LAS bf16x8*)(lds + PG8_SB(b, h) + boff + n * 2048 + k * 1024); } while (0)
; #define PG8_MMA(ai, bj, At, Bt) do { __builtin_amdgcn_s_setprio(1); _Pragma("unroll") for (int m = 0; m < 4; ++m) _Pragma("unroll") for (int n = 0; n < 2; ++n) _Pragma("unroll") for (int k = 0; k < 2; ++k) \
;         acc[ai][bj][m][n] = __builtin_amdgcn_mfma_f32_16x16x32_bf16(Bt[n][k], At[m][k], acc[ai][bj][m][n], 0, 0, 0); __builtin_amdgcn_s_setprio(0); } while (0)
; #define PG8_WAIT_V(n) asm volatile("s_waitcnt vmcnt(" #n ")" ::: "memory")
; #define PG8_WAIT_L(n) asm volatile("s_waitcnt lgkmcnt(" #n ")" ::: "memory")
; #define PG8_BAR __builtin_amdgcn_s_barrier()
; #define PG8_SCHED __builtin_amdgcn_sched_barrier(0)
; template <class Epi, class Sched, bool ALIGN_EPI = false, bool SP2 = false>
; __device__ __forceinline__ void gemm_phase(PG8_LAS unsigned char* lds, const Gemm g, const Sched& S, const Epi& E) {
;     ...
;             PG8_WAIT_V(8); PG8_WAIT_L(0); PG8_BAR; PG8_MMA(1, 0, At, B0); PG8_MMA(1, 1, At, B1); PG8_BAR; PG8_SCHED;
;             PG8_LDB(B0, 1, 0); PG8_LDB(B1, 1, 1); PG8_SCHED; PG8_LDA(At, 1, 0); PG8_STAGE(PG8_SA(0, 1), a2 + hstep, voffA);
;             PG8_WAIT_V(8); PG8_WAIT_L(0); PG8_BAR; PG8_MMA(0, 0, At, B0); PG8_MMA(0, 1, At, B1); PG8_BAR; PG8_SCHED;
	v_mfma_f32_16x16x32_bf16 v[60:63], v[146:149], v[198:201], v[60:63]
	v_mfma_f32_16x16x32_bf16 v[56:59], v[168:171], v[198:201], v[56:59]
	v_mfma_f32_16x16x32_bf16 v[44:47], v[146:149], v[206:209], v[44:47]
	v_mfma_f32_16x16x32_bf16 v[40:43], v[168:171], v[206:209], v[40:43]
	v_mfma_f32_16x16x32_bf16 v[28:31], v[146:149], v[218:221], v[28:31]
	v_mfma_f32_16x16x32_bf16 v[24:27], v[168:171], v[218:221], v[24:27]
	v_mfma_f32_16x16x32_bf16 v[12:15], v[146:149], v[228:231], v[12:15]
	v_mfma_f32_16x16x32_bf16 v[8:11], v[168:171], v[228:231], v[8:11]
	v_mfma_f32_16x16x32_bf16 v[60:63], v[150:153], v[202:205], v[60:63]
	v_mfma_f32_16x16x32_bf16 v[56:59], v[178:181], v[202:205], v[56:59]
	v_mfma_f32_16x16x32_bf16 v[44:47], v[150:153], v[210:213], v[44:47]
	v_mfma_f32_16x16x32_bf16 v[40:43], v[178:181], v[210:213], v[40:43]
	v_mfma_f32_16x16x32_bf16 v[28:31], v[150:153], v[224:227], v[28:31]
	v_mfma_f32_16x16x32_bf16 v[24:27], v[178:181], v[224:227], v[24:27]
	v_mfma_f32_16x16x32_bf16 v[12:15], v[150:153], v[232:235], v[12:15]
	v_mfma_f32_16x16x32_bf16 v[8:11], v[178:181], v[232:235], v[8:11]
	v_mfma_f32_16x16x32_bf16 v[52:55], v[182:185], v[198:201], v[52:55]
	v_mfma_f32_16x16x32_bf16 v[48:51], v[190:193], v[198:201], v[48:51]
	v_mfma_f32_16x16x32_bf16 v[36:39], v[182:185], v[206:209], v[36:39]
	v_mfma_f32_16x16x32_bf16 v[32:35], v[190:193], v[206:209], v[32:35]
	v_mfma_f32_16x16x32_bf16 v[20:23], v[182:185], v[218:221], v[20:23]
	v_mfma_f32_16x16x32_bf16 v[16:19], v[190:193], v[218:221], v[16:19]
	v_mfma_f32_16x16x32_bf16 v[4:7], v[182:185], v[228:231], v[4:7]
	v_mfma_f32_16x16x32_bf16 v[0:3], v[190:193], v[228:231], v[0:3]
	v_mfma_f32_16x16x32_bf16 v[52:55], v[186:189], v[202:205], v[52:55]
	v_mfma_f32_16x16x32_bf16 v[48:51], v[194:197], v[202:205], v[48:51]
	v_mfma_f32_16x16x32_bf16 v[36:39], v[186:189], v[210:213], v[36:39]
	v_mfma_f32_16x16x32_bf16 v[32:35], v[194:197], v[210:213], v[32:35]
	v_mfma_f32_16x16x32_bf16 v[20:23], v[186:189], v[224:227], v[20:23]
	v_mfma_f32_16x16x32_bf16 v[16:19], v[194:197], v[224:227], v[16:19]
	v_mfma_f32_16x16x32_bf16 v[4:7], v[186:189], v[232:235], v[4:7]
	v_mfma_f32_16x16x32_bf16 v[0:3], v[194:197], v[232:235], v[0:3]
	s_barrier
	s_setprio 0
	s_add_i32 s67, 0, 0x18000
	v_add_u32_e32 v154, s67, v159
	s_add_i32 s76, 0, 0x1c000
	ds_read_b128 v[146:149], v154
	ds_read_b128 v[150:153], v154 offset:1024
	ds_read_b128 v[168:171], v154 offset:2048
	ds_read_b128 v[178:181], v154 offset:3072
	v_add_u32_e32 v154, s76, v159
	ds_read_b128 v[182:185], v154
	ds_read_b128 v[186:189], v154 offset:1024
	ds_read_b128 v[190:193], v154 offset:2048
	ds_read_b128 v[194:197], v154 offset:3072
	s_add_u32 s74, s94, 0x80000
	s_addc_u32 s75, s95, 0
	s_mov_b32 m0, s35
	v_lshl_add_u64 v[236:237], s[74:75], 0, v[134:135]
	ds_read_b128 v[198:201], v175 offset:32768
	ds_read_b128 v[202:205], v175 offset:33792
	ds_read_b128 v[206:209], v175 offset:34816
	ds_read_b128 v[210:213], v175 offset:35840
	ds_read_b128 v[218:221], v175 offset:36864
	ds_read_b128 v[224:227], v175 offset:37888
	ds_read_b128 v[228:231], v175 offset:38912
	ds_read_b128 v[232:235], v175 offset:39936
	global_load_lds_dwordx4 v[236:237], off
	v_lshl_add_u64 v[236:237], s[74:75], 0, v[130:131]
	s_mov_b32 m0, s63
	s_nop 0
	global_load_lds_dwordx4 v[236:237], off
	s_waitcnt vmcnt(8)
	s_waitcnt lgkmcnt(0)
	s_setprio 1
	s_barrier
	v_mfma_f32_16x16x32_bf16 v[124:127], v[146:149], v[198:201], v[124:127]
	v_mfma_f32_16x16x32_bf16 v[120:123], v[168:171], v[198:201], v[120:123]
	v_mfma_f32_16x16x32_bf16 v[108:111], v[146:149], v[206:209], v[108:111]
	v_mfma_f32_16x16x32_bf16 v[104:107], v[168:171], v[206:209], v[104:107]
	v_mfma_f32_16x16x32_bf16 v[92:95], v[146:149], v[218:221], v[92:95]
	v_mfma_f32_16x16x32_bf16 v[88:91], v[168:171], v[218:221], v[88:91]
	v_mfma_f32_16x16x32_bf16 v[76:79], v[146:149], v[228:231], v[76:79]
	v_mfma_f32_16x16x32_bf16 v[72:75], v[168:171], v[228:231], v[72:75]
	v_mfma_f32_16x16x32_bf16 v[124:127], v[150:153], v[202:205], v[124:127]
	v_mfma_f32_16x16x32_bf16 v[120:123], v[178:181], v[202:205], v[120:123]
	v_mfma_f32_16x16x32_bf16 v[108:111], v[150:153], v[210:213], v[108:111]
	v_mfma_f32_16x16x32_bf16 v[104:107], v[178:181], v[210:213], v[104:107]
	v_mfma_f32_16x16x32_bf16 v[92:95], v[150:153], v[224:227], v[92:95]
	v_mfma_f32_16x16x32_bf16 v[88:91], v[178:181], v[224:227], v[88:91]
	v_mfma_f32_16x16x32_bf16 v[76:79], v[150:153], v[232:235], v[76:79]
	v_mfma_f32_16x16x32_bf16 v[72:75], v[178:181], v[232:235], v[72:75]
	v_mfma_f32_16x16x32_bf16 v[116:119], v[182:185], v[198:201], v[116:119]
	v_mfma_f32_16x16x32_bf16 v[112:115], v[190:193], v[198:201], v[112:115]
	v_mfma_f32_16x16x32_bf16 v[100:103], v[182:185], v[206:209], v[100:103]
	v_mfma_f32_16x16x32_bf16 v[96:99], v[190:193], v[206:209], v[96:99]
	v_mfma_f32_16x16x32_bf16 v[84:87], v[182:185], v[218:221], v[84:87]
	v_mfma_f32_16x16x32_bf16 v[80:83], v[190:193], v[218:221], v[80:83]
	v_mfma_f32_16x16x32_bf16 v[68:71], v[182:185], v[228:231], v[68:71]
	v_mfma_f32_16x16x32_bf16 v[64:67], v[190:193], v[228:231], v[64:67]
	v_mfma_f32_16x16x32_bf16 v[116:119], v[186:189], v[202:205], v[116:119]
	v_mfma_f32_16x16x32_bf16 v[112:115], v[194:197], v[202:205], v[112:115]
	v_mfma_f32_16x16x32_bf16 v[100:103], v[186:189], v[210:213], v[100:103]
	v_mfma_f32_16x16x32_bf16 v[96:99], v[194:197], v[210:213], v[96:99]
	v_mfma_f32_16x16x32_bf16 v[84:87], v[186:189], v[224:227], v[84:87]
	v_mfma_f32_16x16x32_bf16 v[80:83], v[194:197], v[224:227], v[80:83]
	v_mfma_f32_16x16x32_bf16 v[68:71], v[186:189], v[232:235], v[68:71]
	v_mfma_f32_16x16x32_bf16 v[64:67], v[194:197], v[232:235], v[64:67]
	s_barrier
; #define PG8_STAGE(bufoff, gbase, voff) do { _Pragma("unroll") for (int _i = 0; _i < 2; ++_i) \
;         __builtin_amdgcn_global_load_lds((const unsigned*)((const char*)(gbase) + (voff)[_i]), (PG8_LAS unsigned*)(lds + (bufoff) + ldsw + _i * 8192), 16, 0, 0); } while (0)
; #define PG8_LDA(dst, b, h) do { _Pragma("unroll") for (int m = 0; m < 4; ++m) _Pragma("unroll") for (int k = 0; k < 2; ++k) dst[m][k] = *(const PG8_LAS bf16x8*)(lds + PG8_SA(b, h) + aoff + m * 2048 + k * 1024); } while (0)
; #define PG8_MMA(ai, bj, At, Bt) do { __builtin_amdgcn_s_setprio(1); _Pragma("unroll") for (int m = 0; m < 4; ++m) _Pragma("unroll") for (int n = 0; n < 2; ++n) _Pragma("unroll") for (int k = 0; k < 2; ++k) \
;         acc[ai][bj][m][n] = __builtin_amdgcn_mfma_f32_16x16x32_bf16(Bt[n][k], At[m][k], acc[ai][bj][m][n], 0, 0, 0); __builtin_amdgcn_s_setprio(0); } while (0)
; #define PG8_WAIT_V(n) asm volatile("s_waitcnt vmcnt(" #n ")" ::: "memory")
; #define PG8_WAIT_L(n) asm volatile("s_waitcnt lgkmcnt(" #n ")" ::: "memory")
; #define PG8_BAR __builtin_amdgcn_s_barrier()
; #define PG8_SCHED __builtin_amdgcn_sched_barrier(0)
; template <class Epi, class Sched, bool ALIGN_EPI = false, bool SP2 = false>
; __device__ __forceinline__ void gemm_phase(PG8_LAS unsigned char* lds, const Gemm g, const Sched& S, const Epi& E) {
;     ...
;         for (int t = 0; t < nt; t += 2) {
;             const bool last = (t == nt - 2);
;             const char* a1 = cA + (size_t)(t + 1) * kstep;
;             const char* a2 = last ? nA : cA + (size_t)(t + 2) * kstep; const char* b2 = last ? nB : cB + (size_t)(t + 2) * kstep;
;     ...
;             PG8_WAIT_V(8); PG8_WAIT_L(0); PG8_BAR; PG8_MMA(0, 0, At, B0); PG8_MMA(0, 1, At, B1); PG8_BAR; PG8_SCHED;
;             PG8_LDA(At, 1, 1); PG8_STAGE(PG8_SB(1, 0), b3, voffB); PG8_STAGE(PG8_SB(1, 1), b3 + hstep, voffB); PG8_STAGE(PG8_SA(1, 0), a3, voffA);
;             PG8_WAIT_V(8); PG8_WAIT_L(0); PG8_BAR; PG8_MMA(1, 0, At, B0); PG8_MMA(1, 1, At, B1); PG8_BAR; PG8_SCHED;
	s_setprio 0
	s_add_i32 s67, s67, s3
	v_lshl_add_u64 v[156:157], v[156:157], 0, s[8:9]
	s_mov_b32 m0, s67
	ds_read_b128 v[198:201], v175 offset:49152
	ds_read_b128 v[202:205], v175 offset:50176
	ds_read_b128 v[206:209], v175 offset:51200
	ds_read_b128 v[210:213], v175 offset:52224
	ds_read_b128 v[218:221], v175 offset:53248
	ds_read_b128 v[224:227], v175 offset:54272
	ds_read_b128 v[228:231], v175 offset:55296
	ds_read_b128 v[232:235], v175 offset:56320
	global_load_lds_dwordx4 v[156:157], off
	s_add_i32 m0, s67, 0x2000
	s_add_u32 s74, s92, 0x80080
	v_lshl_add_u64 v[156:157], v[160:161], 0, s[8:9]
	s_addc_u32 s75, s93, 0
	s_add_i32 s67, s76, s3
	global_load_lds_dwordx4 v[156:157], off
	v_lshl_add_u64 v[156:157], s[74:75], 0, v[132:133]
	s_mov_b32 m0, s67
	s_nop 0
	global_load_lds_dwordx4 v[156:157], off
	v_lshl_add_u64 v[156:157], s[74:75], 0, v[128:129]
	s_add_i32 m0, s67, 0x2000
	s_nop 0
	global_load_lds_dwordx4 v[156:157], off
	v_lshl_add_u64 v[156:157], v[164:165], 0, s[8:9]
	s_mov_b32 m0, s69
	s_nop 0
	global_load_lds_dwordx4 v[156:157], off
	v_lshl_add_u64 v[156:157], v[214:215], 0, s[8:9]
	s_mov_b32 m0, s80
	s_nop 0
	global_load_lds_dwordx4 v[156:157], off
	s_waitcnt vmcnt(8)
	s_waitcnt lgkmcnt(0)
	s_setprio 1
	s_barrier
	v_mfma_f32_16x16x32_bf16 v[60:63], v[146:149], v[198:201], v[60:63]
	v_mfma_f32_16x16x32_bf16 v[56:59], v[168:171], v[198:201], v[56:59]
	v_mfma_f32_16x16x32_bf16 v[44:47], v[146:149], v[206:209], v[44:47]
	v_mfma_f32_16x16x32_bf16 v[40:43], v[168:171], v[206:209], v[40:43]
	v_mfma_f32_16x16x32_bf16 v[28:31], v[146:149], v[218:221], v[28:31]
	v_mfma_f32_16x16x32_bf16 v[24:27], v[168:171], v[218:221], v[24:27]
	v_mfma_f32_16x16x32_bf16 v[12:15], v[146:149], v[228:231], v[12:15]
	v_mfma_f32_16x16x32_bf16 v[8:11], v[168:171], v[228:231], v[8:11]
	v_mfma_f32_16x16x32_bf16 v[60:63], v[150:153], v[202:205], v[60:63]
	v_mfma_f32_16x16x32_bf16 v[56:59], v[178:181], v[202:205], v[56:59]
	v_mfma_f32_16x16x32_bf16 v[44:47], v[150:153], v[210:213], v[44:47]
	v_mfma_f32_16x16x32_bf16 v[40:43], v[178:181], v[210:213], v[40:43]
	v_mfma_f32_16x16x32_bf16 v[28:31], v[150:153], v[224:227], v[28:31]
	v_mfma_f32_16x16x32_bf16 v[24:27], v[178:181], v[224:227], v[24:27]
	v_mfma_f32_16x16x32_bf16 v[12:15], v[150:153], v[232:235], v[12:15]
	v_mfma_f32_16x16x32_bf16 v[8:11], v[178:181], v[232:235], v[8:11]
	v_mfma_f32_16x16x32_bf16 v[52:55], v[182:185], v[198:201], v[52:55]
	v_mfma_f32_16x16x32_bf16 v[48:51], v[190:193], v[198:201], v[48:51]
	v_mfma_f32_16x16x32_bf16 v[36:39], v[182:185], v[206:209], v[36:39]
	v_mfma_f32_16x16x32_bf16 v[32:35], v[190:193], v[206:209], v[32:35]
	v_mfma_f32_16x16x32_bf16 v[20:23], v[182:185], v[218:221], v[20:23]
	v_mfma_f32_16x16x32_bf16 v[16:19], v[190:193], v[218:221], v[16:19]
	v_mfma_f32_16x16x32_bf16 v[4:7], v[182:185], v[228:231], v[4:7]
	v_mfma_f32_16x16x32_bf16 v[0:3], v[190:193], v[228:231], v[0:3]
	v_mfma_f32_16x16x32_bf16 v[52:55], v[186:189], v[202:205], v[52:55]
	v_mfma_f32_16x16x32_bf16 v[48:51], v[194:197], v[202:205], v[48:51]
	v_mfma_f32_16x16x32_bf16 v[36:39], v[186:189], v[210:213], v[36:39]
	v_mfma_f32_16x16x32_bf16 v[32:35], v[194:197], v[210:213], v[32:35]
	v_mfma_f32_16x16x32_bf16 v[20:23], v[186:189], v[224:227], v[20:23]
	v_mfma_f32_16x16x32_bf16 v[16:19], v[194:197], v[224:227], v[16:19]
	v_mfma_f32_16x16x32_bf16 v[4:7], v[186:189], v[232:235], v[4:7]
	v_mfma_f32_16x16x32_bf16 v[0:3], v[194:197], v[232:235], v[0:3]
	s_barrier
	s_setprio 0
	s_add_i32 s66, s66, 2
	s_add_u32 s90, s90, 0x100
	s_addc_u32 s91, s91, 0
	s_add_u32 vcc_lo, vcc_lo, 0x100
	s_addc_u32 vcc_hi, vcc_hi, 0
	s_cmp_gt_u32 s66, 29
	s_cbranch_scc0 .LBB0_127
	s_and_b64 vcc, exec, s[10:11]
	s_cbranch_vccz .LBB0_130
	s_barrier

; #define PG8_STAGE(bufoff, gbase, voff) do { _Pragma("unroll") for (int _i = 0; _i < 2; ++_i) \
;         __builtin_amdgcn_global_load_lds((const unsigned*)((const char*)(gbase) + (voff)[_i]), (PG8_LAS unsigned*)(lds + (bufoff) + ldsw + _i * 8192), 16, 0, 0); } while (0)
; #define PG8_LDA(dst, b, h) do { _Pragma("unroll") for (int m = 0; m < 4; ++m) _Pragma("unroll") for (int k = 0; k < 2; ++k) dst[m][k] = *(const PG8_LAS bf16x8*)(lds + PG8_SA(b, h) + aoff + m * 2048 + k * 1024); } while (0)
; #define PG8_LDB(dst, b, h) do { _Pragma("unroll") for (int n = 0; n < 2; ++n) _Pragma("unroll") for (int k = 0; k < 2; ++k) dst[n][k] = *(const PG8_LAS bf16x8*)(lds + PG8_SB(b, h) + boff + n * 2048 + k * 1024); } while (0)
; #define PG8_WAIT_V(n) asm volatile("s_waitcnt vmcnt(" #n ")" ::: "memory")
; #define PG8_WAIT_L(n) asm volatile("s_waitcnt lgkmcnt(" #n ")" ::: "memory")
; #define PG8_BAR __builtin_amdgcn_s_barrier()
; #define PG8_SCHED __builtin_amdgcn_sched_barrier(0)
; template <class Epi, class Sched, bool ALIGN_EPI = false, bool SP2 = false>
; __device__ __forceinline__ void gemm_phase(PG8_LAS unsigned char* lds, const Gemm g, const Sched& S, const Epi& E) {
;     ...
;         const bool has_next = S.next(ui + 1, nxt);
;         const char* nA = has_next ? (const char*)g.A + (size_t)nxt.pm * tstep : cA; const char* nB = has_next ? (const char*)g.Bt + (size_t)nxt.pn * tstep : cB;
;         for (int t = 0; t < nt; t += 2) {
;             const bool last = (t == nt - 2);
;             const char* a1 = cA + (size_t)(t + 1) * kstep;
;             const char* a2 = last ? nA : cA + (size_t)(t + 2) * kstep; const char* b2 = last ? nB : cB + (size_t)(t + 2) * kstep;
;             const char* a3 = a2 + kstep; const char* b3 = b2 + kstep;
;             if (last && has_next) S.a_ready(nxt);
;             if constexpr (SP2) {
;             PG8_LDB(B0, 0, 0); PG8_LDB(B1, 0, 1); PG8_SCHED; PG8_LDA(At, 0, 0); PG8_STAGE(PG8_SA(1, 1), a1 + hstep, voffA);
;             PG8_WAIT_V(8); PG8_WAIT_L(0); PG8_BAR; PG8_MMA(0, 0, At, B0); PG8_MMA(0, 1, At, B1); PG8_BAR; PG8_SCHED;
;             PG8_LDA(At, 0, 1); PG8_STAGE(PG8_SB(0, 0), b2, voffB); PG8_STAGE(PG8_SB(0, 1), b2 + hstep, voffB); PG8_STAGE(PG8_SA(0, 0), a2, voffA);
;             PG8_WAIT_V(8); PG8_WAIT_L(0); PG8_BAR; PG8_MMA(1, 0, At, B0); PG8_MMA(1, 1, At, B1); PG8_BAR; PG8_SCHED;
.LBB0_248:
	ds_read_b128 v[128:131], v220
	ds_read_b128 v[132:135], v220 offset:1024
	ds_read_b128 v[136:139], v220 offset:2048
	ds_read_b128 v[140:143], v220 offset:3072
	ds_read_b128 v[144:147], v221
	ds_read_b128 v[148:151], v221 offset:1024
	ds_read_b128 v[152:155], v221 offset:2048
	ds_read_b128 v[156:159], v221 offset:3072
	s_add_u32 s10, s92, 0x100
	s_addc_u32 s11, s93, 0
	s_cmpk_eq_i32 s66, 0x54
	s_cselect_b32 s95, s89, s11
	s_cselect_b32 s94, s88, s10
	s_cselect_b32 s83, s91, vcc_lo
	s_cselect_b32 s82, s90, s22
	v_lshl_add_u64 v[204:205], s[92:93], 0, v[192:193]
	s_add_i32 m0, s15, 0xc000
	ds_read_b128 v[160:163], v223
	ds_read_b128 v[164:167], v223 offset:1024
	ds_read_b128 v[168:171], v223 offset:2048
	ds_read_b128 v[172:175], v223 offset:3072
	ds_read_b128 v[176:179], v223 offset:4096
	ds_read_b128 v[180:183], v223 offset:5120
	ds_read_b128 v[184:187], v223 offset:6144
	ds_read_b128 v[200:203], v223 offset:7168
	global_load_lds_dwordx4 v[204:205], off
	v_lshl_add_u64 v[204:205], s[92:93], 0, v[194:195]
	s_add_i32 m0, s15, 0xe000
	s_nop 0
	global_load_lds_dwordx4 v[204:205], off
	s_waitcnt vmcnt(8)
	s_waitcnt lgkmcnt(0)
	s_setprio 1
	s_barrier
	v_mfma_f32_16x16x32_bf16 v[124:127], v[128:131], v[160:163], v[124:127]
	v_mfma_f32_16x16x32_bf16 v[120:123], v[136:139], v[160:163], v[120:123]
	v_mfma_f32_16x16x32_bf16 v[108:111], v[128:131], v[168:171], v[108:111]
	v_mfma_f32_16x16x32_bf16 v[104:107], v[136:139], v[168:171], v[104:107]
	v_mfma_f32_16x16x32_bf16 v[92:95], v[128:131], v[176:179], v[92:95]
	v_mfma_f32_16x16x32_bf16 v[88:91], v[136:139], v[176:179], v[88:91]
	v_mfma_f32_16x16x32_bf16 v[76:79], v[128:131], v[184:187], v[76:79]
	v_mfma_f32_16x16x32_bf16 v[72:75], v[136:139], v[184:187], v[72:75]
	v_mfma_f32_16x16x32_bf16 v[124:127], v[132:135], v[164:167], v[124:127]
	v_mfma_f32_16x16x32_bf16 v[120:123], v[140:143], v[164:167], v[120:123]
	v_mfma_f32_16x16x32_bf16 v[108:111], v[132:135], v[172:175], v[108:111]
	v_mfma_f32_16x16x32_bf16 v[104:107], v[140:143], v[172:175], v[104:107]
	v_mfma_f32_16x16x32_bf16 v[92:95], v[132:135], v[180:183], v[92:95]
	v_mfma_f32_16x16x32_bf16 v[88:91], v[140:143], v[180:183], v[88:91]
	v_mfma_f32_16x16x32_bf16 v[76:79], v[132:135], v[200:203], v[76:79]
	v_mfma_f32_16x16x32_bf16 v[72:75], v[140:143], v[200:203], v[72:75]
	v_mfma_f32_16x16x32_bf16 v[116:119], v[144:147], v[160:163], v[116:119]
	v_mfma_f32_16x16x32_bf16 v[112:115], v[152:155], v[160:163], v[112:115]
	v_mfma_f32_16x16x32_bf16 v[100:103], v[144:147], v[168:171], v[100:103]
	v_mfma_f32_16x16x32_bf16 v[96:99], v[152:155], v[168:171], v[96:99]
	v_mfma_f32_16x16x32_bf16 v[84:87], v[144:147], v[176:179], v[84:87]
	v_mfma_f32_16x16x32_bf16 v[80:83], v[152:155], v[176:179], v[80:83]
	v_mfma_f32_16x16x32_bf16 v[68:71], v[144:147], v[184:187], v[68:71]
	v_mfma_f32_16x16x32_bf16 v[64:67], v[152:155], v[184:187], v[64:67]
	v_mfma_f32_16x16x32_bf16 v[116:119], v[148:151], v[164:167], v[116:119]
	v_mfma_f32_16x16x32_bf16 v[112:115], v[156:159], v[164:167], v[112:115]
	v_mfma_f32_16x16x32_bf16 v[100:103], v[148:151], v[172:175], v[100:103]
	v_mfma_f32_16x16x32_bf16 v[96:99], v[156:159], v[172:175], v[96:99]
	v_mfma_f32_16x16x32_bf16 v[84:87], v[148:151], v[180:183], v[84:87]
	v_mfma_f32_16x16x32_bf16 v[80:83], v[156:159], v[180:183], v[80:83]
	v_mfma_f32_16x16x32_bf16 v[68:71], v[148:151], v[200:203], v[68:71]
	v_mfma_f32_16x16x32_bf16 v[64:67], v[156:159], v[200:203], v[64:67]
	s_barrier
	s_setprio 0
	s_add_i32 s67, s73, s14
	v_lshl_add_u64 v[204:205], s[82:83], 0, v[188:189]
	s_mov_b32 m0, s67
	ds_read_b128 v[160:163], v223 offset:16384
	ds_read_b128 v[164:167], v223 offset:17408
	ds_read_b128 v[168:171], v223 offset:18432
	ds_read_b128 v[172:175], v223 offset:19456
	ds_read_b128 v[176:179], v223 offset:20480
	ds_read_b128 v[180:183], v223 offset:21504
	ds_read_b128 v[184:187], v223 offset:22528
	ds_read_b128 v[200:203], v223 offset:23552
	global_load_lds_dwordx4 v[204:205], off
	s_add_i32 m0, s67, 0x2000
	s_add_u32 s74, s82, 0x160000
	v_lshl_add_u64 v[206:207], s[82:83], 0, v[190:191]
	s_addc_u32 s75, s83, 0
	s_add_i32 s67, s80, s14
	global_load_lds_dwordx4 v[206:207], off
	v_lshl_add_u64 v[208:209], s[74:75], 0, v[188:189]
	s_mov_b32 m0, s67
	v_lshl_add_u64 v[210:211], s[94:95], 0, v[190:191]
	global_load_lds_dwordx4 v[208:209], off
	v_lshl_add_u64 v[208:209], s[74:75], 0, v[190:191]
	s_add_i32 m0, s67, 0x2000
	s_nop 0
	global_load_lds_dwordx4 v[208:209], off
	v_lshl_add_u64 v[208:209], s[94:95], 0, v[188:189]
	s_mov_b32 m0, s15
	s_nop 0
	global_load_lds_dwordx4 v[208:209], off
	s_mov_b32 m0, s34
	s_nop 0
	global_load_lds_dwordx4 v[210:211], off
	s_waitcnt vmcnt(8)
	s_waitcnt lgkmcnt(0)
	s_setprio 1
	s_barrier
; #define PG8_STAGE(bufoff, gbase, voff) do { _Pragma("unroll") for (int _i = 0; _i < 2; ++_i) \
;         __builtin_amdgcn_global_load_lds((const unsigned*)((const char*)(gbase) + (voff)[_i]), (PG8_LAS unsigned*)(lds + (bufoff) + ldsw + _i * 8192), 16, 0, 0); } while (0)
; #define PG8_LDA(dst, b, h) do { _Pragma("unroll") for (int m = 0; m < 4; ++m) _Pragma("unroll") for (int k = 0; k < 2; ++k) dst[m][k] = *(const PG8_LAS bf16x8*)(lds + PG8_SA(b, h) + aoff + m * 2048 + k * 1024); } while (0)
; #define PG8_LDB(dst, b, h) do { _Pragma("unroll") for (int n = 0; n < 2; ++n) _Pragma("unroll") for (int k = 0; k < 2; ++k) dst[n][k] = *(const PG8_LAS bf16x8*)(lds + PG8_SB(b, h) + boff + n * 2048 + k * 1024); } while (0)
; #define PG8_MMA(ai, bj, At, Bt) do { __builtin_amdgcn_s_setprio(1); _Pragma("unroll") for (int m = 0; m < 4; ++m) _Pragma("unroll") for (int n = 0; n < 2; ++n) _Pragma("unroll") for (int k = 0; k < 2; ++k) \
;         acc[ai][bj][m][n] = __builtin_amdgcn_mfma_f32_16x16x32_bf16(Bt[n][k], At[m][k], acc[ai][bj][m][n], 0, 0, 0); __builtin_amdgcn_s_setprio(0); } while (0)
; #define PG8_WAIT_V(n) asm volatile("s_waitcnt vmcnt(" #n ")" ::: "memory")
; #define PG8_WAIT_L(n) asm volatile("s_waitcnt lgkmcnt(" #n ")" ::: "memory")
; #define PG8_BAR __builtin_amdgcn_s_barrier()
; #define PG8_SCHED __builtin_amdgcn_sched_barrier(0)
; template <class Epi, class Sched, bool ALIGN_EPI = false, bool SP2 = false>
; __device__ __forceinline__ void gemm_phase(PG8_LAS unsigned char* lds, const Gemm g, const Sched& S, const Epi& E) {
;     ...
;             PG8_WAIT_V(8); PG8_WAIT_L(0); PG8_BAR; PG8_MMA(1, 0, At, B0); PG8_MMA(1, 1, At, B1); PG8_BAR; PG8_SCHED;
;             PG8_LDB(B0, 1, 0); PG8_LDB(B1, 1, 1); PG8_SCHED; PG8_LDA(At, 1, 0); PG8_STAGE(PG8_SA(0, 1), a2 + hstep, voffA);
;             PG8_WAIT_V(8); PG8_WAIT_L(0); PG8_BAR; PG8_MMA(0, 0, At, B0); PG8_MMA(0, 1, At, B1); PG8_BAR; PG8_SCHED;
	v_mfma_f32_16x16x32_bf16 v[60:63], v[128:131], v[160:163], v[60:63]
	v_mfma_f32_16x16x32_bf16 v[56:59], v[136:139], v[160:163], v[56:59]
	v_mfma_f32_16x16x32_bf16 v[44:47], v[128:131], v[168:171], v[44:47]
	v_mfma_f32_16x16x32_bf16 v[40:43], v[136:139], v[168:171], v[40:43]
	v_mfma_f32_16x16x32_bf16 v[28:31], v[128:131], v[176:179], v[28:31]
	v_mfma_f32_16x16x32_bf16 v[24:27], v[136:139], v[176:179], v[24:27]
	v_mfma_f32_16x16x32_bf16 v[12:15], v[128:131], v[184:187], v[12:15]
	v_mfma_f32_16x16x32_bf16 v[8:11], v[136:139], v[184:187], v[8:11]
	v_mfma_f32_16x16x32_bf16 v[60:63], v[132:135], v[164:167], v[60:63]
	v_mfma_f32_16x16x32_bf16 v[56:59], v[140:143], v[164:167], v[56:59]
	v_mfma_f32_16x16x32_bf16 v[44:47], v[132:135], v[172:175], v[44:47]
	v_mfma_f32_16x16x32_bf16 v[40:43], v[140:143], v[172:175], v[40:43]
	v_mfma_f32_16x16x32_bf16 v[28:31], v[132:135], v[180:183], v[28:31]
	v_mfma_f32_16x16x32_bf16 v[24:27], v[140:143], v[180:183], v[24:27]
	v_mfma_f32_16x16x32_bf16 v[12:15], v[132:135], v[200:203], v[12:15]
	v_mfma_f32_16x16x32_bf16 v[8:11], v[140:143], v[200:203], v[8:11]
	v_mfma_f32_16x16x32_bf16 v[52:55], v[144:147], v[160:163], v[52:55]
	v_mfma_f32_16x16x32_bf16 v[48:51], v[152:155], v[160:163], v[48:51]
	v_mfma_f32_16x16x32_bf16 v[36:39], v[144:147], v[168:171], v[36:39]
	v_mfma_f32_16x16x32_bf16 v[32:35], v[152:155], v[168:171], v[32:35]
	v_mfma_f32_16x16x32_bf16 v[20:23], v[144:147], v[176:179], v[20:23]
	v_mfma_f32_16x16x32_bf16 v[16:19], v[152:155], v[176:179], v[16:19]
	v_mfma_f32_16x16x32_bf16 v[4:7], v[144:147], v[184:187], v[4:7]
	v_mfma_f32_16x16x32_bf16 v[0:3], v[152:155], v[184:187], v[0:3]
	v_mfma_f32_16x16x32_bf16 v[52:55], v[148:151], v[164:167], v[52:55]
	v_mfma_f32_16x16x32_bf16 v[48:51], v[156:159], v[164:167], v[48:51]
	v_mfma_f32_16x16x32_bf16 v[36:39], v[148:151], v[172:175], v[36:39]
	v_mfma_f32_16x16x32_bf16 v[32:35], v[156:159], v[172:175], v[32:35]
	v_mfma_f32_16x16x32_bf16 v[20:23], v[148:151], v[180:183], v[20:23]
	v_mfma_f32_16x16x32_bf16 v[16:19], v[156:159], v[180:183], v[16:19]
	v_mfma_f32_16x16x32_bf16 v[4:7], v[148:151], v[200:203], v[4:7]
	v_mfma_f32_16x16x32_bf16 v[0:3], v[156:159], v[200:203], v[0:3]
	s_barrier
	s_setprio 0
	s_add_i32 s67, 0, 0x18000
	s_add_i32 s76, 0, 0x1c000
	v_add_u32_e32 v140, s67, v218
	v_add_u32_e32 v156, s76, v218
	ds_read_b128 v[128:131], v140
	ds_read_b128 v[132:135], v140 offset:1024
	ds_read_b128 v[136:139], v140 offset:2048
	ds_read_b128 v[140:143], v140 offset:3072
	ds_read_b128 v[144:147], v156
	ds_read_b128 v[148:151], v156 offset:1024
	ds_read_b128 v[152:155], v156 offset:2048
	ds_read_b128 v[156:159], v156 offset:3072
	s_add_u32 s74, s94, 0x160000
	s_addc_u32 s75, s95, 0
	s_mov_b32 m0, s35
	v_lshl_add_u64 v[212:213], s[74:75], 0, v[188:189]
	ds_read_b128 v[160:163], v223 offset:32768
	ds_read_b128 v[164:167], v223 offset:33792
	ds_read_b128 v[168:171], v223 offset:34816
	ds_read_b128 v[172:175], v223 offset:35840
	ds_read_b128 v[176:179], v223 offset:36864
	ds_read_b128 v[180:183], v223 offset:37888
	ds_read_b128 v[184:187], v223 offset:38912
	ds_read_b128 v[200:203], v223 offset:39936
	global_load_lds_dwordx4 v[212:213], off
	v_lshl_add_u64 v[212:213], s[74:75], 0, v[190:191]
	s_mov_b32 m0, s68
	s_nop 0
	global_load_lds_dwordx4 v[212:213], off
	s_waitcnt vmcnt(8)
	s_waitcnt lgkmcnt(0)
	s_setprio 1
	s_barrier
	v_mfma_f32_16x16x32_bf16 v[124:127], v[128:131], v[160:163], v[124:127]
	v_mfma_f32_16x16x32_bf16 v[120:123], v[136:139], v[160:163], v[120:123]
	v_mfma_f32_16x16x32_bf16 v[108:111], v[128:131], v[168:171], v[108:111]
	v_mfma_f32_16x16x32_bf16 v[104:107], v[136:139], v[168:171], v[104:107]
	v_mfma_f32_16x16x32_bf16 v[92:95], v[128:131], v[176:179], v[92:95]
	v_mfma_f32_16x16x32_bf16 v[88:91], v[136:139], v[176:179], v[88:91]
	v_mfma_f32_16x16x32_bf16 v[76:79], v[128:131], v[184:187], v[76:79]
	v_mfma_f32_16x16x32_bf16 v[72:75], v[136:139], v[184:187], v[72:75]
	v_mfma_f32_16x16x32_bf16 v[124:127], v[132:135], v[164:167], v[124:127]
	v_mfma_f32_16x16x32_bf16 v[120:123], v[140:143], v[164:167], v[120:123]
	v_mfma_f32_16x16x32_bf16 v[108:111], v[132:135], v[172:175], v[108:111]
	v_mfma_f32_16x16x32_bf16 v[104:107], v[140:143], v[172:175], v[104:107]
	v_mfma_f32_16x16x32_bf16 v[92:95], v[132:135], v[180:183], v[92:95]
	v_mfma_f32_16x16x32_bf16 v[88:91], v[140:143], v[180:183], v[88:91]
	v_mfma_f32_16x16x32_bf16 v[76:79], v[132:135], v[200:203], v[76:79]
	v_mfma_f32_16x16x32_bf16 v[72:75], v[140:143], v[200:203], v[72:75]
	v_mfma_f32_16x16x32_bf16 v[116:119], v[144:147], v[160:163], v[116:119]
	v_mfma_f32_16x16x32_bf16 v[112:115], v[152:155], v[160:163], v[112:115]
	v_mfma_f32_16x16x32_bf16 v[100:103], v[144:147], v[168:171], v[100:103]
	v_mfma_f32_16x16x32_bf16 v[96:99], v[152:155], v[168:171], v[96:99]
	v_mfma_f32_16x16x32_bf16 v[84:87], v[144:147], v[176:179], v[84:87]
	v_mfma_f32_16x16x32_bf16 v[80:83], v[152:155], v[176:179], v[80:83]
	v_mfma_f32_16x16x32_bf16 v[68:71], v[144:147], v[184:187], v[68:71]
	v_mfma_f32_16x16x32_bf16 v[64:67], v[152:155], v[184:187], v[64:67]
	v_mfma_f32_16x16x32_bf16 v[116:119], v[148:151], v[164:167], v[116:119]
	v_mfma_f32_16x16x32_bf16 v[112:115], v[156:159], v[164:167], v[112:115]
	v_mfma_f32_16x16x32_bf16 v[100:103], v[148:151], v[172:175], v[100:103]
	v_mfma_f32_16x16x32_bf16 v[96:99], v[156:159], v[172:175], v[96:99]
	v_mfma_f32_16x16x32_bf16 v[84:87], v[148:151], v[180:183], v[84:87]
	v_mfma_f32_16x16x32_bf16 v[80:83], v[156:159], v[180:183], v[80:83]
	v_mfma_f32_16x16x32_bf16 v[68:71], v[148:151], v[200:203], v[68:71]
	v_mfma_f32_16x16x32_bf16 v[64:67], v[156:159], v[200:203], v[64:67]
	s_barrier
; #define PG8_STAGE(bufoff, gbase, voff) do { _Pragma("unroll") for (int _i = 0; _i < 2; ++_i) \
;         __builtin_amdgcn_global_load_lds((const unsigned*)((const char*)(gbase) + (voff)[_i]), (PG8_LAS unsigned*)(lds + (bufoff) + ldsw + _i * 8192), 16, 0, 0); } while (0)
; #define PG8_LDA(dst, b, h) do { _Pragma("unroll") for (int m = 0; m < 4; ++m) _Pragma("unroll") for (int k = 0; k < 2; ++k) dst[m][k] = *(const PG8_LAS bf16x8*)(lds + PG8_SA(b, h) + aoff + m * 2048 + k * 1024); } while (0)
; #define PG8_MMA(ai, bj, At, Bt) do { __builtin_amdgcn_s_setprio(1); _Pragma("unroll") for (int m = 0; m < 4; ++m) _Pragma("unroll") for (int n = 0; n < 2; ++n) _Pragma("unroll") for (int k = 0; k < 2; ++k) \
;         acc[ai][bj][m][n] = __builtin_amdgcn_mfma_f32_16x16x32_bf16(Bt[n][k], At[m][k], acc[ai][bj][m][n], 0, 0, 0); __builtin_amdgcn_s_setprio(0); } while (0)
; #define PG8_WAIT_V(n) asm volatile("s_waitcnt vmcnt(" #n ")" ::: "memory")
; #define PG8_WAIT_L(n) asm volatile("s_waitcnt lgkmcnt(" #n ")" ::: "memory")
; #define PG8_BAR __builtin_amdgcn_s_barrier()
; #define PG8_SCHED __builtin_amdgcn_sched_barrier(0)
; template <class Epi, class Sched, bool ALIGN_EPI = false, bool SP2 = false>
; __device__ __forceinline__ void gemm_phase(PG8_LAS unsigned char* lds, const Gemm g, const Sched& S, const Epi& E) {
;     ...
;         for (int t = 0; t < nt; t += 2) {
;             const bool last = (t == nt - 2);
;             const char* a1 = cA + (size_t)(t + 1) * kstep;
;             const char* a2 = last ? nA : cA + (size_t)(t + 2) * kstep; const char* b2 = last ? nB : cB + (size_t)(t + 2) * kstep;
;     ...
;             PG8_WAIT_V(8); PG8_WAIT_L(0); PG8_BAR; PG8_MMA(0, 0, At, B0); PG8_MMA(0, 1, At, B1); PG8_BAR; PG8_SCHED;
;             PG8_LDA(At, 1, 1); PG8_STAGE(PG8_SB(1, 0), b3, voffB); PG8_STAGE(PG8_SB(1, 1), b3 + hstep, voffB); PG8_STAGE(PG8_SA(1, 0), a3, voffA);
;             PG8_WAIT_V(8); PG8_WAIT_L(0); PG8_BAR; PG8_MMA(1, 0, At, B0); PG8_MMA(1, 1, At, B1); PG8_BAR; PG8_SCHED;
	s_setprio 0
	s_add_i32 s67, s67, s14
	v_lshl_add_u64 v[204:205], v[204:205], 0, s[46:47]
	s_mov_b32 m0, s67
	ds_read_b128 v[160:163], v223 offset:49152
	ds_read_b128 v[164:167], v223 offset:50176
	ds_read_b128 v[168:171], v223 offset:51200
	ds_read_b128 v[172:175], v223 offset:52224
	ds_read_b128 v[176:179], v223 offset:53248
	ds_read_b128 v[180:183], v223 offset:54272
	ds_read_b128 v[184:187], v223 offset:55296
	ds_read_b128 v[200:203], v223 offset:56320
	global_load_lds_dwordx4 v[204:205], off
	s_add_i32 m0, s67, 0x2000
	s_add_u32 s74, s82, 0x160080
	v_lshl_add_u64 v[204:205], v[206:207], 0, s[46:47]
	s_addc_u32 s75, s83, 0
	s_add_i32 s67, s76, s14
	global_load_lds_dwordx4 v[204:205], off
	v_lshl_add_u64 v[204:205], s[74:75], 0, v[188:189]
	s_mov_b32 m0, s67
	s_nop 0
	global_load_lds_dwordx4 v[204:205], off
	v_lshl_add_u64 v[204:205], s[74:75], 0, v[190:191]
	s_add_i32 m0, s67, 0x2000
	s_nop 0
	global_load_lds_dwordx4 v[204:205], off
	v_lshl_add_u64 v[204:205], v[208:209], 0, s[46:47]
	s_mov_b32 m0, s70
	s_nop 0
	global_load_lds_dwordx4 v[204:205], off
	v_lshl_add_u64 v[204:205], v[210:211], 0, s[46:47]
	s_mov_b32 m0, s71
	s_nop 0
	global_load_lds_dwordx4 v[204:205], off
	s_waitcnt vmcnt(8)
	s_waitcnt lgkmcnt(0)
	s_setprio 1
	s_barrier
	v_mfma_f32_16x16x32_bf16 v[60:63], v[128:131], v[160:163], v[60:63]
	v_mfma_f32_16x16x32_bf16 v[56:59], v[136:139], v[160:163], v[56:59]
	v_mfma_f32_16x16x32_bf16 v[44:47], v[128:131], v[168:171], v[44:47]
	v_mfma_f32_16x16x32_bf16 v[40:43], v[136:139], v[168:171], v[40:43]
	v_mfma_f32_16x16x32_bf16 v[28:31], v[128:131], v[176:179], v[28:31]
	v_mfma_f32_16x16x32_bf16 v[24:27], v[136:139], v[176:179], v[24:27]
	v_mfma_f32_16x16x32_bf16 v[12:15], v[128:131], v[184:187], v[12:15]
	v_mfma_f32_16x16x32_bf16 v[8:11], v[136:139], v[184:187], v[8:11]
	v_mfma_f32_16x16x32_bf16 v[60:63], v[132:135], v[164:167], v[60:63]
	v_mfma_f32_16x16x32_bf16 v[56:59], v[140:143], v[164:167], v[56:59]
	v_mfma_f32_16x16x32_bf16 v[44:47], v[132:135], v[172:175], v[44:47]
	v_mfma_f32_16x16x32_bf16 v[40:43], v[140:143], v[172:175], v[40:43]
	v_mfma_f32_16x16x32_bf16 v[28:31], v[132:135], v[180:183], v[28:31]
	v_mfma_f32_16x16x32_bf16 v[24:27], v[140:143], v[180:183], v[24:27]
	v_mfma_f32_16x16x32_bf16 v[12:15], v[132:135], v[200:203], v[12:15]
	v_mfma_f32_16x16x32_bf16 v[8:11], v[140:143], v[200:203], v[8:11]
	v_mfma_f32_16x16x32_bf16 v[52:55], v[144:147], v[160:163], v[52:55]
	v_mfma_f32_16x16x32_bf16 v[48:51], v[152:155], v[160:163], v[48:51]
	v_mfma_f32_16x16x32_bf16 v[36:39], v[144:147], v[168:171], v[36:39]
	v_mfma_f32_16x16x32_bf16 v[32:35], v[152:155], v[168:171], v[32:35]
	v_mfma_f32_16x16x32_bf16 v[20:23], v[144:147], v[176:179], v[20:23]
	v_mfma_f32_16x16x32_bf16 v[16:19], v[152:155], v[176:179], v[16:19]
	v_mfma_f32_16x16x32_bf16 v[4:7], v[144:147], v[184:187], v[4:7]
	v_mfma_f32_16x16x32_bf16 v[0:3], v[152:155], v[184:187], v[0:3]
	v_mfma_f32_16x16x32_bf16 v[52:55], v[148:151], v[164:167], v[52:55]
	v_mfma_f32_16x16x32_bf16 v[48:51], v[156:159], v[164:167], v[48:51]
	v_mfma_f32_16x16x32_bf16 v[36:39], v[148:151], v[172:175], v[36:39]
	v_mfma_f32_16x16x32_bf16 v[32:35], v[156:159], v[172:175], v[32:35]
	v_mfma_f32_16x16x32_bf16 v[20:23], v[148:151], v[180:183], v[20:23]
	v_mfma_f32_16x16x32_bf16 v[16:19], v[156:159], v[180:183], v[16:19]
	v_mfma_f32_16x16x32_bf16 v[4:7], v[148:151], v[200:203], v[4:7]
	v_mfma_f32_16x16x32_bf16 v[0:3], v[156:159], v[200:203], v[0:3]
	s_barrier
	s_setprio 0
	s_add_i32 s66, s66, 2
	s_add_u32 s22, s22, 0x100
	s_addc_u32 vcc_lo, vcc_lo, 0
	s_cmpk_gt_u32 s66, 0x55
	s_mov_b64 s[92:93], s[10:11]
	s_cbranch_scc0 .LBB0_248
	s_and_b64 vcc, exec, s[86:87]
	s_cbranch_vccz .LBB0_251
	s_barrier

; #define PG8_STAGE(bufoff, gbase, voff) do { _Pragma("unroll") for (int _i = 0; _i < 2; ++_i) \
;         __builtin_amdgcn_global_load_lds((const unsigned*)((const char*)(gbase) + (voff)[_i]), (PG8_LAS unsigned*)(lds + (bufoff) + ldsw + _i * 8192), 16, 0, 0); } while (0)
; #define PG8_LDA(dst, b, h) do { _Pragma("unroll") for (int m = 0; m < 4; ++m) _Pragma("unroll") for (int k = 0; k < 2; ++k) dst[m][k] = *(const PG8_LAS bf16x8*)(lds + PG8_SA(b, h) + aoff + m * 2048 + k * 1024); } while (0)
; #define PG8_LDB(dst, b, h) do { _Pragma("unroll") for (int n = 0; n < 2; ++n) _Pragma("unroll") for (int k = 0; k < 2; ++k) dst[n][k] = *(const PG8_LAS bf16x8*)(lds + PG8_SB(b, h) + boff + n * 2048 + k * 1024); } while (0)
; #define PG8_WAIT_V(n) asm volatile("s_waitcnt vmcnt(" #n ")" ::: "memory")
; #define PG8_WAIT_L(n) asm volatile("s_waitcnt lgkmcnt(" #n ")" ::: "memory")
; #define PG8_BAR __builtin_amdgcn_s_barrier()
; #define PG8_SCHED __builtin_amdgcn_sched_barrier(0)
; template <class Epi, class Sched, bool ALIGN_EPI = false, bool SP2 = false>
; __device__ __forceinline__ void gemm_phase(PG8_LAS unsigned char* lds, const Gemm g, const Sched& S, const Epi& E) {
;     ...
;         const bool has_next = S.next(ui + 1, nxt);
;         const char* nA = has_next ? (const char*)g.A + (size_t)nxt.pm * tstep : cA; const char* nB = has_next ? (const char*)g.Bt + (size_t)nxt.pn * tstep : cB;
;         for (int t = 0; t < nt; t += 2) {
;             const bool last = (t == nt - 2);
;             const char* a1 = cA + (size_t)(t + 1) * kstep;
;             const char* a2 = last ? nA : cA + (size_t)(t + 2) * kstep; const char* b2 = last ? nB : cB + (size_t)(t + 2) * kstep;
;             const char* a3 = a2 + kstep; const char* b3 = b2 + kstep;
;             if (last && has_next) S.a_ready(nxt);
;             if constexpr (SP2) {
;             PG8_LDB(B0, 0, 0); PG8_LDB(B1, 0, 1); PG8_SCHED; PG8_LDA(At, 0, 0); PG8_STAGE(PG8_SA(1, 1), a1 + hstep, voffA);
;             PG8_WAIT_V(8); PG8_WAIT_L(0); PG8_BAR; PG8_MMA(0, 0, At, B0); PG8_MMA(0, 1, At, B1); PG8_BAR; PG8_SCHED;
;             PG8_LDA(At, 0, 1); PG8_STAGE(PG8_SB(0, 0), b2, voffB); PG8_STAGE(PG8_SB(0, 1), b2 + hstep, voffB); PG8_STAGE(PG8_SA(0, 0), a2, voffA);
;             PG8_WAIT_V(8); PG8_WAIT_L(0); PG8_BAR; PG8_MMA(1, 0, At, B0); PG8_MMA(1, 1, At, B1); PG8_BAR; PG8_SCHED;
.LBB0_403:
	ds_read_b128 v[128:131], v179
	ds_read_b128 v[132:135], v179 offset:1024
	ds_read_b128 v[154:157], v179 offset:2048
	ds_read_b128 v[158:161], v179 offset:3072
	ds_read_b128 v[162:165], v180
	ds_read_b128 v[166:169], v180 offset:1024
	ds_read_b128 v[170:173], v180 offset:2048
	ds_read_b128 v[186:189], v180 offset:3072
	s_add_u32 s67, s10, 0xfff80080
	s_addc_u32 s74, s11, -1
	s_cmp_eq_u32 s66, 28
	s_cselect_b32 vcc_hi, s12, s74
	s_cselect_b32 vcc_lo, s13, s67
	s_cselect_b32 s97, s47, s95
	s_cselect_b32 s96, s89, s91
	v_lshl_add_u64 v[174:175], s[10:11], 0, v[146:147]
	s_add_i32 m0, s14, 0xc000
	ds_read_b128 v[190:193], v181
	ds_read_b128 v[194:197], v181 offset:1024
	ds_read_b128 v[198:201], v181 offset:2048
	ds_read_b128 v[202:205], v181 offset:3072
	ds_read_b128 v[206:209], v181 offset:4096
	ds_read_b128 v[210:213], v181 offset:5120
	ds_read_b128 v[218:221], v181 offset:6144
	ds_read_b128 v[224:227], v181 offset:7168
	global_load_lds_dwordx4 v[174:175], off
	v_lshl_add_u64 v[174:175], s[10:11], 0, v[148:149]
	s_add_i32 m0, s14, 0xe000
	s_nop 0
	global_load_lds_dwordx4 v[174:175], off
	s_waitcnt vmcnt(8)
	s_waitcnt lgkmcnt(0)
	s_setprio 1
	s_barrier
	v_mfma_f32_16x16x32_bf16 v[72:75], v[128:131], v[190:193], v[72:75]
	v_mfma_f32_16x16x32_bf16 v[80:83], v[154:157], v[190:193], v[80:83]
	v_mfma_f32_16x16x32_bf16 v[104:107], v[128:131], v[198:201], v[104:107]
	v_mfma_f32_16x16x32_bf16 v[108:111], v[154:157], v[198:201], v[108:111]
	v_mfma_f32_16x16x32_bf16 v[124:127], v[128:131], v[206:209], v[124:127]
	v_mfma_f32_16x16x32_bf16 v[120:123], v[154:157], v[206:209], v[120:123]
	v_mfma_f32_16x16x32_bf16 v[100:103], v[128:131], v[218:221], v[100:103]
	v_mfma_f32_16x16x32_bf16 v[96:99], v[154:157], v[218:221], v[96:99]
	v_mfma_f32_16x16x32_bf16 v[72:75], v[132:135], v[194:197], v[72:75]
	v_mfma_f32_16x16x32_bf16 v[80:83], v[158:161], v[194:197], v[80:83]
	v_mfma_f32_16x16x32_bf16 v[104:107], v[132:135], v[202:205], v[104:107]
	v_mfma_f32_16x16x32_bf16 v[108:111], v[158:161], v[202:205], v[108:111]
	v_mfma_f32_16x16x32_bf16 v[124:127], v[132:135], v[210:213], v[124:127]
	v_mfma_f32_16x16x32_bf16 v[120:123], v[158:161], v[210:213], v[120:123]
	v_mfma_f32_16x16x32_bf16 v[100:103], v[132:135], v[224:227], v[100:103]
	v_mfma_f32_16x16x32_bf16 v[96:99], v[158:161], v[224:227], v[96:99]
	v_mfma_f32_16x16x32_bf16 v[64:67], v[162:165], v[190:193], v[64:67]
	v_mfma_f32_16x16x32_bf16 v[68:71], v[170:173], v[190:193], v[68:71]
	v_mfma_f32_16x16x32_bf16 v[88:91], v[162:165], v[198:201], v[88:91]
	v_mfma_f32_16x16x32_bf16 v[92:95], v[170:173], v[198:201], v[92:95]
	v_mfma_f32_16x16x32_bf16 v[116:119], v[162:165], v[206:209], v[116:119]
	v_mfma_f32_16x16x32_bf16 v[112:115], v[170:173], v[206:209], v[112:115]
	v_mfma_f32_16x16x32_bf16 v[84:87], v[162:165], v[218:221], v[84:87]
	v_mfma_f32_16x16x32_bf16 v[76:79], v[170:173], v[218:221], v[76:79]
	v_mfma_f32_16x16x32_bf16 v[64:67], v[166:169], v[194:197], v[64:67]
	v_mfma_f32_16x16x32_bf16 v[68:71], v[186:189], v[194:197], v[68:71]
	v_mfma_f32_16x16x32_bf16 v[88:91], v[166:169], v[202:205], v[88:91]
	v_mfma_f32_16x16x32_bf16 v[92:95], v[186:189], v[202:205], v[92:95]
	v_mfma_f32_16x16x32_bf16 v[116:119], v[166:169], v[210:213], v[116:119]
	v_mfma_f32_16x16x32_bf16 v[112:115], v[186:189], v[210:213], v[112:115]
	v_mfma_f32_16x16x32_bf16 v[84:87], v[166:169], v[224:227], v[84:87]
	v_mfma_f32_16x16x32_bf16 v[76:79], v[186:189], v[224:227], v[76:79]
	s_barrier
	s_setprio 0
	s_add_i32 s67, s80, s3
	v_lshl_add_u64 v[174:175], s[96:97], 0, v[138:139]
	s_mov_b32 m0, s67
	ds_read_b128 v[190:193], v181 offset:16384
	ds_read_b128 v[194:197], v181 offset:17408
	ds_read_b128 v[198:201], v181 offset:18432
	ds_read_b128 v[202:205], v181 offset:19456
	ds_read_b128 v[206:209], v181 offset:20480
	ds_read_b128 v[210:213], v181 offset:21504
	ds_read_b128 v[218:221], v181 offset:22528
	ds_read_b128 v[224:227], v181 offset:23552
	global_load_lds_dwordx4 v[174:175], off
	s_add_i32 m0, s67, 0x2000
	s_add_u32 s74, s96, 0x80000
	v_lshl_add_u64 v[214:215], s[96:97], 0, v[142:143]
	s_addc_u32 s75, s97, 0
	s_add_i32 s67, s81, s3
	global_load_lds_dwordx4 v[214:215], off
	v_lshl_add_u64 v[228:229], s[74:75], 0, v[138:139]
	s_mov_b32 m0, s67
	v_lshl_add_u64 v[230:231], vcc, 0, v[140:141]
	global_load_lds_dwordx4 v[228:229], off
	v_lshl_add_u64 v[228:229], s[74:75], 0, v[142:143]
	s_add_i32 m0, s67, 0x2000
	s_nop 0
	global_load_lds_dwordx4 v[228:229], off
	v_lshl_add_u64 v[228:229], vcc, 0, v[136:137]
	s_mov_b32 m0, s14
	s_nop 0
	global_load_lds_dwordx4 v[228:229], off
	s_mov_b32 m0, s15
	s_nop 0
	global_load_lds_dwordx4 v[230:231], off
	s_waitcnt vmcnt(8)
	s_waitcnt lgkmcnt(0)
	s_setprio 1
	s_barrier
; #define PG8_STAGE(bufoff, gbase, voff) do { _Pragma("unroll") for (int _i = 0; _i < 2; ++_i) \
;         __builtin_amdgcn_global_load_lds((const unsigned*)((const char*)(gbase) + (voff)[_i]), (PG8_LAS unsigned*)(lds + (bufoff) + ldsw + _i * 8192), 16, 0, 0); } while (0)
; #define PG8_LDA(dst, b, h) do { _Pragma("unroll") for (int m = 0; m < 4; ++m) _Pragma("unroll") for (int k = 0; k < 2; ++k) dst[m][k] = *(const PG8_LAS bf16x8*)(lds + PG8_SA(b, h) + aoff + m * 2048 + k * 1024); } while (0)
; #define PG8_LDB(dst, b, h) do { _Pragma("unroll") for (int n = 0; n < 2; ++n) _Pragma("unroll") for (int k = 0; k < 2; ++k) dst[n][k] = *(const PG8_LAS bf16x8*)(lds + PG8_SB(b, h) + boff + n * 2048 + k * 1024); } while (0)
; #define PG8_MMA(ai, bj, At, Bt) do { __builtin_amdgcn_s_setprio(1); _Pragma("unroll") for (int m = 0; m < 4; ++m) _Pragma("unroll") for (int n = 0; n < 2; ++n) _Pragma("unroll") for (int k = 0; k < 2; ++k) \
;         acc[ai][bj][m][n] = __builtin_amdgcn_mfma_f32_16x16x32_bf16(Bt[n][k], At[m][k], acc[ai][bj][m][n], 0, 0, 0); __builtin_amdgcn_s_setprio(0); } while (0)
; #define PG8_WAIT_V(n) asm volatile("s_waitcnt vmcnt(" #n ")" ::: "memory")
; #define PG8_WAIT_L(n) asm volatile("s_waitcnt lgkmcnt(" #n ")" ::: "memory")
; #define PG8_BAR __builtin_amdgcn_s_barrier()
; #define PG8_SCHED __builtin_amdgcn_sched_barrier(0)
; template <class Epi, class Sched, bool ALIGN_EPI = false, bool SP2 = false>
; __device__ __forceinline__ void gemm_phase(PG8_LAS unsigned char* lds, const Gemm g, const Sched& S, const Epi& E) {
;     ...
;             PG8_WAIT_V(8); PG8_WAIT_L(0); PG8_BAR; PG8_MMA(1, 0, At, B0); PG8_MMA(1, 1, At, B1); PG8_BAR; PG8_SCHED;
;             PG8_LDB(B0, 1, 0); PG8_LDB(B1, 1, 1); PG8_SCHED; PG8_LDA(At, 1, 0); PG8_STAGE(PG8_SA(0, 1), a2 + hstep, voffA);
;             PG8_WAIT_V(8); PG8_WAIT_L(0); PG8_BAR; PG8_MMA(0, 0, At, B0); PG8_MMA(0, 1, At, B1); PG8_BAR; PG8_SCHED;
	v_mfma_f32_16x16x32_bf16 v[60:63], v[128:131], v[190:193], v[60:63]
	v_mfma_f32_16x16x32_bf16 v[56:59], v[154:157], v[190:193], v[56:59]
	v_mfma_f32_16x16x32_bf16 v[44:47], v[128:131], v[198:201], v[44:47]
	v_mfma_f32_16x16x32_bf16 v[40:43], v[154:157], v[198:201], v[40:43]
	v_mfma_f32_16x16x32_bf16 v[28:31], v[128:131], v[206:209], v[28:31]
	v_mfma_f32_16x16x32_bf16 v[24:27], v[154:157], v[206:209], v[24:27]
	v_mfma_f32_16x16x32_bf16 v[12:15], v[128:131], v[218:221], v[12:15]
	v_mfma_f32_16x16x32_bf16 v[8:11], v[154:157], v[218:221], v[8:11]
	v_mfma_f32_16x16x32_bf16 v[60:63], v[132:135], v[194:197], v[60:63]
	v_mfma_f32_16x16x32_bf16 v[56:59], v[158:161], v[194:197], v[56:59]
	v_mfma_f32_16x16x32_bf16 v[44:47], v[132:135], v[202:205], v[44:47]
	v_mfma_f32_16x16x32_bf16 v[40:43], v[158:161], v[202:205], v[40:43]
	v_mfma_f32_16x16x32_bf16 v[28:31], v[132:135], v[210:213], v[28:31]
	v_mfma_f32_16x16x32_bf16 v[24:27], v[158:161], v[210:213], v[24:27]
	v_mfma_f32_16x16x32_bf16 v[12:15], v[132:135], v[224:227], v[12:15]
	v_mfma_f32_16x16x32_bf16 v[8:11], v[158:161], v[224:227], v[8:11]
	v_mfma_f32_16x16x32_bf16 v[52:55], v[162:165], v[190:193], v[52:55]
	v_mfma_f32_16x16x32_bf16 v[48:51], v[170:173], v[190:193], v[48:51]
	v_mfma_f32_16x16x32_bf16 v[36:39], v[162:165], v[198:201], v[36:39]
	v_mfma_f32_16x16x32_bf16 v[32:35], v[170:173], v[198:201], v[32:35]
	v_mfma_f32_16x16x32_bf16 v[20:23], v[162:165], v[206:209], v[20:23]
	v_mfma_f32_16x16x32_bf16 v[16:19], v[170:173], v[206:209], v[16:19]
	v_mfma_f32_16x16x32_bf16 v[4:7], v[162:165], v[218:221], v[4:7]
	v_mfma_f32_16x16x32_bf16 v[0:3], v[170:173], v[218:221], v[0:3]
	v_mfma_f32_16x16x32_bf16 v[52:55], v[166:169], v[194:197], v[52:55]
	v_mfma_f32_16x16x32_bf16 v[48:51], v[186:189], v[194:197], v[48:51]
	v_mfma_f32_16x16x32_bf16 v[36:39], v[166:169], v[202:205], v[36:39]
	v_mfma_f32_16x16x32_bf16 v[32:35], v[186:189], v[202:205], v[32:35]
	v_mfma_f32_16x16x32_bf16 v[20:23], v[166:169], v[210:213], v[20:23]
	v_mfma_f32_16x16x32_bf16 v[16:19], v[186:189], v[210:213], v[16:19]
	v_mfma_f32_16x16x32_bf16 v[4:7], v[166:169], v[224:227], v[4:7]
	v_mfma_f32_16x16x32_bf16 v[0:3], v[186:189], v[224:227], v[0:3]
	s_barrier
	s_setprio 0
	s_add_i32 s67, 0, 0x18000
	s_add_i32 s76, 0, 0x1c000
	v_add_u32_e32 v158, s67, v177
	v_add_u32_e32 v186, s76, v177
	ds_read_b128 v[128:131], v158
	ds_read_b128 v[132:135], v158 offset:1024
	ds_read_b128 v[154:157], v158 offset:2048
	ds_read_b128 v[158:161], v158 offset:3072
	ds_read_b128 v[162:165], v186
	ds_read_b128 v[166:169], v186 offset:1024
	ds_read_b128 v[170:173], v186 offset:2048
	ds_read_b128 v[186:189], v186 offset:3072
	s_add_u32 s74, vcc_lo, 0x80000
	s_addc_u32 s75, vcc_hi, 0
	s_mov_b32 m0, s23
	v_lshl_add_u64 v[232:233], s[74:75], 0, v[136:137]
	ds_read_b128 v[190:193], v181 offset:32768
	ds_read_b128 v[194:197], v181 offset:33792
	ds_read_b128 v[198:201], v181 offset:34816
	ds_read_b128 v[202:205], v181 offset:35840
	ds_read_b128 v[206:209], v181 offset:36864
	ds_read_b128 v[210:213], v181 offset:37888
	ds_read_b128 v[218:221], v181 offset:38912
	ds_read_b128 v[224:227], v181 offset:39936
	global_load_lds_dwordx4 v[232:233], off
	v_lshl_add_u64 v[232:233], s[74:75], 0, v[140:141]
	s_mov_b32 m0, s34
	s_nop 0
	global_load_lds_dwordx4 v[232:233], off
	s_waitcnt vmcnt(8)
	s_waitcnt lgkmcnt(0)
	s_setprio 1
	s_barrier
	v_mfma_f32_16x16x32_bf16 v[72:75], v[128:131], v[190:193], v[72:75]
	v_mfma_f32_16x16x32_bf16 v[80:83], v[154:157], v[190:193], v[80:83]
	v_mfma_f32_16x16x32_bf16 v[104:107], v[128:131], v[198:201], v[104:107]
	v_mfma_f32_16x16x32_bf16 v[108:111], v[154:157], v[198:201], v[108:111]
	v_mfma_f32_16x16x32_bf16 v[124:127], v[128:131], v[206:209], v[124:127]
	v_mfma_f32_16x16x32_bf16 v[120:123], v[154:157], v[206:209], v[120:123]
	v_mfma_f32_16x16x32_bf16 v[100:103], v[128:131], v[218:221], v[100:103]
	v_mfma_f32_16x16x32_bf16 v[96:99], v[154:157], v[218:221], v[96:99]
	v_mfma_f32_16x16x32_bf16 v[72:75], v[132:135], v[194:197], v[72:75]
	v_mfma_f32_16x16x32_bf16 v[80:83], v[158:161], v[194:197], v[80:83]
	v_mfma_f32_16x16x32_bf16 v[104:107], v[132:135], v[202:205], v[104:107]
	v_mfma_f32_16x16x32_bf16 v[108:111], v[158:161], v[202:205], v[108:111]
	v_mfma_f32_16x16x32_bf16 v[124:127], v[132:135], v[210:213], v[124:127]
	v_mfma_f32_16x16x32_bf16 v[120:123], v[158:161], v[210:213], v[120:123]
	v_mfma_f32_16x16x32_bf16 v[100:103], v[132:135], v[224:227], v[100:103]
	v_mfma_f32_16x16x32_bf16 v[96:99], v[158:161], v[224:227], v[96:99]
	v_mfma_f32_16x16x32_bf16 v[64:67], v[162:165], v[190:193], v[64:67]
	v_mfma_f32_16x16x32_bf16 v[68:71], v[170:173], v[190:193], v[68:71]
	v_mfma_f32_16x16x32_bf16 v[88:91], v[162:165], v[198:201], v[88:91]
	v_mfma_f32_16x16x32_bf16 v[92:95], v[170:173], v[198:201], v[92:95]
	v_mfma_f32_16x16x32_bf16 v[116:119], v[162:165], v[206:209], v[116:119]
	v_mfma_f32_16x16x32_bf16 v[112:115], v[170:173], v[206:209], v[112:115]
	v_mfma_f32_16x16x32_bf16 v[84:87], v[162:165], v[218:221], v[84:87]
	v_mfma_f32_16x16x32_bf16 v[76:79], v[170:173], v[218:221], v[76:79]
	v_mfma_f32_16x16x32_bf16 v[64:67], v[166:169], v[194:197], v[64:67]
	v_mfma_f32_16x16x32_bf16 v[68:71], v[186:189], v[194:197], v[68:71]
	v_mfma_f32_16x16x32_bf16 v[88:91], v[166:169], v[202:205], v[88:91]
	v_mfma_f32_16x16x32_bf16 v[92:95], v[186:189], v[202:205], v[92:95]
	v_mfma_f32_16x16x32_bf16 v[116:119], v[166:169], v[210:213], v[116:119]
	v_mfma_f32_16x16x32_bf16 v[112:115], v[186:189], v[210:213], v[112:115]
	v_mfma_f32_16x16x32_bf16 v[84:87], v[166:169], v[224:227], v[84:87]
	v_mfma_f32_16x16x32_bf16 v[76:79], v[186:189], v[224:227], v[76:79]
	s_barrier
; #define PG8_STAGE(bufoff, gbase, voff) do { _Pragma("unroll") for (int _i = 0; _i < 2; ++_i) \
;         __builtin_amdgcn_global_load_lds((const unsigned*)((const char*)(gbase) + (voff)[_i]), (PG8_LAS unsigned*)(lds + (bufoff) + ldsw + _i * 8192), 16, 0, 0); } while (0)
; #define PG8_LDA(dst, b, h) do { _Pragma("unroll") for (int m = 0; m < 4; ++m) _Pragma("unroll") for (int k = 0; k < 2; ++k) dst[m][k] = *(const PG8_LAS bf16x8*)(lds + PG8_SA(b, h) + aoff + m * 2048 + k * 1024); } while (0)
; #define PG8_MMA(ai, bj, At, Bt) do { __builtin_amdgcn_s_setprio(1); _Pragma("unroll") for (int m = 0; m < 4; ++m) _Pragma("unroll") for (int n = 0; n < 2; ++n) _Pragma("unroll") for (int k = 0; k < 2; ++k) \
;         acc[ai][bj][m][n] = __builtin_amdgcn_mfma_f32_16x16x32_bf16(Bt[n][k], At[m][k], acc[ai][bj][m][n], 0, 0, 0); __builtin_amdgcn_s_setprio(0); } while (0)
; #define PG8_WAIT_V(n) asm volatile("s_waitcnt vmcnt(" #n ")" ::: "memory")
; #define PG8_WAIT_L(n) asm volatile("s_waitcnt lgkmcnt(" #n ")" ::: "memory")
; #define PG8_BAR __builtin_amdgcn_s_barrier()
; #define PG8_SCHED __builtin_amdgcn_sched_barrier(0)
; template <class Epi, class Sched, bool ALIGN_EPI = false, bool SP2 = false>
; __device__ __forceinline__ void gemm_phase(PG8_LAS unsigned char* lds, const Gemm g, const Sched& S, const Epi& E) {
;     ...
;         for (int t = 0; t < nt; t += 2) {
;             const bool last = (t == nt - 2);
;             const char* a1 = cA + (size_t)(t + 1) * kstep;
;             const char* a2 = last ? nA : cA + (size_t)(t + 2) * kstep; const char* b2 = last ? nB : cB + (size_t)(t + 2) * kstep;
;     ...
;             PG8_WAIT_V(8); PG8_WAIT_L(0); PG8_BAR; PG8_MMA(0, 0, At, B0); PG8_MMA(0, 1, At, B1); PG8_BAR; PG8_SCHED;
;             PG8_LDA(At, 1, 1); PG8_STAGE(PG8_SB(1, 0), b3, voffB); PG8_STAGE(PG8_SB(1, 1), b3 + hstep, voffB); PG8_STAGE(PG8_SA(1, 0), a3, voffA);
;             PG8_WAIT_V(8); PG8_WAIT_L(0); PG8_BAR; PG8_MMA(1, 0, At, B0); PG8_MMA(1, 1, At, B1); PG8_BAR; PG8_SCHED;
	s_setprio 0
	s_add_i32 s67, s67, s3
	v_lshl_add_u64 v[174:175], v[174:175], 0, s[44:45]
	s_mov_b32 m0, s67
	ds_read_b128 v[190:193], v181 offset:49152
	ds_read_b128 v[194:197], v181 offset:50176
	ds_read_b128 v[198:201], v181 offset:51200
	ds_read_b128 v[202:205], v181 offset:52224
	ds_read_b128 v[206:209], v181 offset:53248
	ds_read_b128 v[210:213], v181 offset:54272
	ds_read_b128 v[218:221], v181 offset:55296
	ds_read_b128 v[224:227], v181 offset:56320
	global_load_lds_dwordx4 v[174:175], off
	s_add_i32 m0, s67, 0x2000
	s_add_u32 s74, s96, 0x80080
	v_lshl_add_u64 v[174:175], v[214:215], 0, s[44:45]
	s_addc_u32 s75, s97, 0
	s_add_i32 s67, s76, s3
	global_load_lds_dwordx4 v[174:175], off
	v_lshl_add_u64 v[174:175], s[74:75], 0, v[138:139]
	s_mov_b32 m0, s67
	s_nop 0
	global_load_lds_dwordx4 v[174:175], off
	v_lshl_add_u64 v[174:175], s[74:75], 0, v[142:143]
	s_add_i32 m0, s67, 0x2000
	s_nop 0
	global_load_lds_dwordx4 v[174:175], off
	v_lshl_add_u64 v[174:175], v[228:229], 0, s[44:45]
	s_mov_b32 m0, s68
	s_nop 0
	global_load_lds_dwordx4 v[174:175], off
	v_lshl_add_u64 v[174:175], v[230:231], 0, s[44:45]
	s_mov_b32 m0, s69
	s_nop 0
	global_load_lds_dwordx4 v[174:175], off
	s_waitcnt vmcnt(8)
	s_waitcnt lgkmcnt(0)
	s_setprio 1
	s_barrier
	v_mfma_f32_16x16x32_bf16 v[60:63], v[128:131], v[190:193], v[60:63]
	v_mfma_f32_16x16x32_bf16 v[56:59], v[154:157], v[190:193], v[56:59]
	v_mfma_f32_16x16x32_bf16 v[44:47], v[128:131], v[198:201], v[44:47]
	v_mfma_f32_16x16x32_bf16 v[40:43], v[154:157], v[198:201], v[40:43]
	v_mfma_f32_16x16x32_bf16 v[28:31], v[128:131], v[206:209], v[28:31]
	v_mfma_f32_16x16x32_bf16 v[24:27], v[154:157], v[206:209], v[24:27]
	v_mfma_f32_16x16x32_bf16 v[12:15], v[128:131], v[218:221], v[12:15]
	v_mfma_f32_16x16x32_bf16 v[8:11], v[154:157], v[218:221], v[8:11]
	v_mfma_f32_16x16x32_bf16 v[60:63], v[132:135], v[194:197], v[60:63]
	v_mfma_f32_16x16x32_bf16 v[56:59], v[158:161], v[194:197], v[56:59]
	v_mfma_f32_16x16x32_bf16 v[44:47], v[132:135], v[202:205], v[44:47]
	v_mfma_f32_16x16x32_bf16 v[40:43], v[158:161], v[202:205], v[40:43]
	v_mfma_f32_16x16x32_bf16 v[28:31], v[132:135], v[210:213], v[28:31]
	v_mfma_f32_16x16x32_bf16 v[24:27], v[158:161], v[210:213], v[24:27]
	v_mfma_f32_16x16x32_bf16 v[12:15], v[132:135], v[224:227], v[12:15]
	v_mfma_f32_16x16x32_bf16 v[8:11], v[158:161], v[224:227], v[8:11]
	v_mfma_f32_16x16x32_bf16 v[52:55], v[162:165], v[190:193], v[52:55]
	v_mfma_f32_16x16x32_bf16 v[48:51], v[170:173], v[190:193], v[48:51]
	v_mfma_f32_16x16x32_bf16 v[36:39], v[162:165], v[198:201], v[36:39]
	v_mfma_f32_16x16x32_bf16 v[32:35], v[170:173], v[198:201], v[32:35]
	v_mfma_f32_16x16x32_bf16 v[20:23], v[162:165], v[206:209], v[20:23]
	v_mfma_f32_16x16x32_bf16 v[16:19], v[170:173], v[206:209], v[16:19]
	v_mfma_f32_16x16x32_bf16 v[4:7], v[162:165], v[218:221], v[4:7]
	v_mfma_f32_16x16x32_bf16 v[0:3], v[170:173], v[218:221], v[0:3]
	v_mfma_f32_16x16x32_bf16 v[52:55], v[166:169], v[194:197], v[52:55]
	v_mfma_f32_16x16x32_bf16 v[48:51], v[186:189], v[194:197], v[48:51]
	v_mfma_f32_16x16x32_bf16 v[36:39], v[166:169], v[202:205], v[36:39]
	v_mfma_f32_16x16x32_bf16 v[32:35], v[186:189], v[202:205], v[32:35]
	v_mfma_f32_16x16x32_bf16 v[20:23], v[166:169], v[210:213], v[20:23]
	v_mfma_f32_16x16x32_bf16 v[16:19], v[186:189], v[210:213], v[16:19]
	v_mfma_f32_16x16x32_bf16 v[4:7], v[166:169], v[224:227], v[4:7]
	v_mfma_f32_16x16x32_bf16 v[0:3], v[186:189], v[224:227], v[0:3]
	s_barrier
	s_setprio 0
	s_add_i32 s66, s66, 2
	s_add_u32 s10, s10, 0x100
	s_addc_u32 s11, s11, 0
	s_add_u32 s91, s91, 0x100
	s_addc_u32 s95, s95, 0
	s_cmp_gt_u32 s66, 29
	s_cbranch_scc0 .LBB0_403
	s_and_b64 vcc, exec, s[86:87]
	s_cbranch_vccz .LBB0_406
	s_barrier

; #define PG8_STAGE(bufoff, gbase, voff) do { _Pragma("unroll") for (int _i = 0; _i < 2; ++_i) \
;         __builtin_amdgcn_global_load_lds((const unsigned*)((const char*)(gbase) + (voff)[_i]), (PG8_LAS unsigned*)(lds + (bufoff) + ldsw + _i * 8192), 16, 0, 0); } while (0)
; #define PG8_LDA(dst, b, h) do { _Pragma("unroll") for (int m = 0; m < 4; ++m) _Pragma("unroll") for (int k = 0; k < 2; ++k) dst[m][k] = *(const PG8_LAS bf16x8*)(lds + PG8_SA(b, h) + aoff + m * 2048 + k * 1024); } while (0)
; #define PG8_LDB(dst, b, h) do { _Pragma("unroll") for (int n = 0; n < 2; ++n) _Pragma("unroll") for (int k = 0; k < 2; ++k) dst[n][k] = *(const PG8_LAS bf16x8*)(lds + PG8_SB(b, h) + boff + n * 2048 + k * 1024); } while (0)
; #define PG8_WAIT_V(n) asm volatile("s_waitcnt vmcnt(" #n ")" ::: "memory")
; #define PG8_WAIT_L(n) asm volatile("s_waitcnt lgkmcnt(" #n ")" ::: "memory")
; #define PG8_BAR __builtin_amdgcn_s_barrier()
; #define PG8_SCHED __builtin_amdgcn_sched_barrier(0)
; template <class Epi, class Sched, bool ALIGN_EPI = false, bool SP2 = false>
; __device__ __forceinline__ void gemm_phase(PG8_LAS unsigned char* lds, const Gemm g, const Sched& S, const Epi& E) {
;     ...
;         const bool has_next = S.next(ui + 1, nxt);
;         const char* nA = has_next ? (const char*)g.A + (size_t)nxt.pm * tstep : cA; const char* nB = has_next ? (const char*)g.Bt + (size_t)nxt.pn * tstep : cB;
;         for (int t = 0; t < nt; t += 2) {
;             const bool last = (t == nt - 2);
;             const char* a1 = cA + (size_t)(t + 1) * kstep;
;             const char* a2 = last ? nA : cA + (size_t)(t + 2) * kstep; const char* b2 = last ? nB : cB + (size_t)(t + 2) * kstep;
;             const char* a3 = a2 + kstep; const char* b3 = b2 + kstep;
;             if (last && has_next) S.a_ready(nxt);
;             if constexpr (SP2) {
;             PG8_LDB(B0, 0, 0); PG8_LDB(B1, 0, 1); PG8_SCHED; PG8_LDA(At, 0, 0); PG8_STAGE(PG8_SA(1, 1), a1 + hstep, voffA);
;             PG8_WAIT_V(8); PG8_WAIT_L(0); PG8_BAR; PG8_MMA(0, 0, At, B0); PG8_MMA(0, 1, At, B1); PG8_BAR; PG8_SCHED;
;             PG8_LDA(At, 0, 1); PG8_STAGE(PG8_SB(0, 0), b2, voffB); PG8_STAGE(PG8_SB(0, 1), b2 + hstep, voffB); PG8_STAGE(PG8_SA(0, 0), a2, voffA);
;             PG8_WAIT_V(8); PG8_WAIT_L(0); PG8_BAR; PG8_MMA(1, 0, At, B0); PG8_MMA(1, 1, At, B1); PG8_BAR; PG8_SCHED;
.LBB0_493:
	ds_read_b128 v[144:147], v166
	ds_read_b128 v[148:151], v166 offset:1024
	ds_read_b128 v[152:155], v166 offset:2048
	ds_read_b128 v[156:159], v166 offset:3072
	ds_read_b128 v[172:175], v167
	ds_read_b128 v[176:179], v167 offset:1024
	ds_read_b128 v[180:183], v167 offset:2048
	ds_read_b128 v[184:187], v167 offset:3072
	s_add_u32 s67, s92, 0xfff80080
	s_addc_u32 s74, s93, -1
	s_cmp_eq_u32 s66, 28
	s_cselect_b32 s95, s12, s74
	s_cselect_b32 s94, s13, s67
	s_cselect_b32 s83, s47, s91
	s_cselect_b32 s82, s81, s85
	v_lshl_add_u64 v[160:161], s[92:93], 0, v[136:137]
	s_add_i32 m0, s14, 0xc000
	ds_read_b128 v[188:191], v168
	ds_read_b128 v[192:195], v168 offset:1024
	ds_read_b128 v[196:199], v168 offset:2048
	ds_read_b128 v[200:203], v168 offset:3072
	ds_read_b128 v[204:207], v168 offset:4096
	ds_read_b128 v[208:211], v168 offset:5120
	ds_read_b128 v[212:215], v168 offset:6144
	ds_read_b128 v[218:221], v168 offset:7168
	global_load_lds_dwordx4 v[160:161], off
	v_lshl_add_u64 v[160:161], s[92:93], 0, v[138:139]
	s_add_i32 m0, s14, 0xe000
	s_nop 0
	global_load_lds_dwordx4 v[160:161], off
	s_waitcnt vmcnt(8)
	s_waitcnt lgkmcnt(0)
	s_setprio 1
	s_barrier
	v_mfma_f32_16x16x32_bf16 v[124:127], v[144:147], v[188:191], v[124:127]
	v_mfma_f32_16x16x32_bf16 v[120:123], v[152:155], v[188:191], v[120:123]
	v_mfma_f32_16x16x32_bf16 v[108:111], v[144:147], v[196:199], v[108:111]
	v_mfma_f32_16x16x32_bf16 v[104:107], v[152:155], v[196:199], v[104:107]
	v_mfma_f32_16x16x32_bf16 v[100:103], v[144:147], v[204:207], v[100:103]
	v_mfma_f32_16x16x32_bf16 v[92:95], v[152:155], v[204:207], v[92:95]
	v_mfma_f32_16x16x32_bf16 v[84:87], v[144:147], v[212:215], v[84:87]
	v_mfma_f32_16x16x32_bf16 v[76:79], v[152:155], v[212:215], v[76:79]
	v_mfma_f32_16x16x32_bf16 v[124:127], v[148:151], v[192:195], v[124:127]
	v_mfma_f32_16x16x32_bf16 v[120:123], v[156:159], v[192:195], v[120:123]
	v_mfma_f32_16x16x32_bf16 v[108:111], v[148:151], v[200:203], v[108:111]
	v_mfma_f32_16x16x32_bf16 v[104:107], v[156:159], v[200:203], v[104:107]
	v_mfma_f32_16x16x32_bf16 v[100:103], v[148:151], v[208:211], v[100:103]
	v_mfma_f32_16x16x32_bf16 v[92:95], v[156:159], v[208:211], v[92:95]
	v_mfma_f32_16x16x32_bf16 v[84:87], v[148:151], v[218:221], v[84:87]
	v_mfma_f32_16x16x32_bf16 v[76:79], v[156:159], v[218:221], v[76:79]
	v_mfma_f32_16x16x32_bf16 v[116:119], v[172:175], v[188:191], v[116:119]
	v_mfma_f32_16x16x32_bf16 v[112:115], v[180:183], v[188:191], v[112:115]
	v_mfma_f32_16x16x32_bf16 v[96:99], v[172:175], v[196:199], v[96:99]
	v_mfma_f32_16x16x32_bf16 v[88:91], v[180:183], v[196:199], v[88:91]
	v_mfma_f32_16x16x32_bf16 v[80:83], v[172:175], v[204:207], v[80:83]
	v_mfma_f32_16x16x32_bf16 v[72:75], v[180:183], v[204:207], v[72:75]
	v_mfma_f32_16x16x32_bf16 v[68:71], v[172:175], v[212:215], v[68:71]
	v_mfma_f32_16x16x32_bf16 v[64:67], v[180:183], v[212:215], v[64:67]
	v_mfma_f32_16x16x32_bf16 v[116:119], v[176:179], v[192:195], v[116:119]
	v_mfma_f32_16x16x32_bf16 v[112:115], v[184:187], v[192:195], v[112:115]
	v_mfma_f32_16x16x32_bf16 v[96:99], v[176:179], v[200:203], v[96:99]
	v_mfma_f32_16x16x32_bf16 v[88:91], v[184:187], v[200:203], v[88:91]
	v_mfma_f32_16x16x32_bf16 v[80:83], v[176:179], v[208:211], v[80:83]
	v_mfma_f32_16x16x32_bf16 v[72:75], v[184:187], v[208:211], v[72:75]
	v_mfma_f32_16x16x32_bf16 v[68:71], v[176:179], v[218:221], v[68:71]
	v_mfma_f32_16x16x32_bf16 v[64:67], v[184:187], v[218:221], v[64:67]
	s_barrier
	s_setprio 0
	s_add_i32 s67, s70, s3
	v_lshl_add_u64 v[160:161], s[82:83], 0, v[132:133]
	s_mov_b32 m0, s67
	ds_read_b128 v[188:191], v168 offset:16384
	ds_read_b128 v[192:195], v168 offset:17408
	ds_read_b128 v[196:199], v168 offset:18432
	ds_read_b128 v[200:203], v168 offset:19456
	ds_read_b128 v[204:207], v168 offset:20480
	ds_read_b128 v[208:211], v168 offset:21504
	ds_read_b128 v[212:215], v168 offset:22528
	ds_read_b128 v[218:221], v168 offset:23552
	global_load_lds_dwordx4 v[160:161], off
	s_add_i32 m0, s67, 0x2000
	s_add_u32 s74, s82, 0x80000
	v_lshl_add_u64 v[224:225], s[82:83], 0, v[128:129]
	s_addc_u32 s75, s83, 0
	s_add_i32 s67, s71, s3
	global_load_lds_dwordx4 v[224:225], off
	v_lshl_add_u64 v[226:227], s[74:75], 0, v[132:133]
	s_mov_b32 m0, s67
	v_lshl_add_u64 v[228:229], s[94:95], 0, v[130:131]
	global_load_lds_dwordx4 v[226:227], off
	v_lshl_add_u64 v[226:227], s[74:75], 0, v[128:129]
	s_add_i32 m0, s67, 0x2000
	s_nop 0
	global_load_lds_dwordx4 v[226:227], off
	v_lshl_add_u64 v[226:227], s[94:95], 0, v[134:135]
	s_mov_b32 m0, s14
	s_nop 0
	global_load_lds_dwordx4 v[226:227], off
	s_mov_b32 m0, s15
	s_nop 0
	global_load_lds_dwordx4 v[228:229], off
	s_waitcnt vmcnt(8)
	s_waitcnt lgkmcnt(0)
	s_setprio 1
	s_barrier
; #define PG8_STAGE(bufoff, gbase, voff) do { _Pragma("unroll") for (int _i = 0; _i < 2; ++_i) \
;         __builtin_amdgcn_global_load_lds((const unsigned*)((const char*)(gbase) + (voff)[_i]), (PG8_LAS unsigned*)(lds + (bufoff) + ldsw + _i * 8192), 16, 0, 0); } while (0)
; #define PG8_LDA(dst, b, h) do { _Pragma("unroll") for (int m = 0; m < 4; ++m) _Pragma("unroll") for (int k = 0; k < 2; ++k) dst[m][k] = *(const PG8_LAS bf16x8*)(lds + PG8_SA(b, h) + aoff + m * 2048 + k * 1024); } while (0)
; #define PG8_LDB(dst, b, h) do { _Pragma("unroll") for (int n = 0; n < 2; ++n) _Pragma("unroll") for (int k = 0; k < 2; ++k) dst[n][k] = *(const PG8_LAS bf16x8*)(lds + PG8_SB(b, h) + boff + n * 2048 + k * 1024); } while (0)
; #define PG8_MMA(ai, bj, At, Bt) do { __builtin_amdgcn_s_setprio(1); _Pragma("unroll") for (int m = 0; m < 4; ++m) _Pragma("unroll") for (int n = 0; n < 2; ++n) _Pragma("unroll") for (int k = 0; k < 2; ++k) \
;         acc[ai][bj][m][n] = __builtin_amdgcn_mfma_f32_16x16x32_bf16(Bt[n][k], At[m][k], acc[ai][bj][m][n], 0, 0, 0); __builtin_amdgcn_s_setprio(0); } while (0)
; #define PG8_WAIT_V(n) asm volatile("s_waitcnt vmcnt(" #n ")" ::: "memory")
; #define PG8_WAIT_L(n) asm volatile("s_waitcnt lgkmcnt(" #n ")" ::: "memory")
; #define PG8_BAR __builtin_amdgcn_s_barrier()
; #define PG8_SCHED __builtin_amdgcn_sched_barrier(0)
; template <class Epi, class Sched, bool ALIGN_EPI = false, bool SP2 = false>
; __device__ __forceinline__ void gemm_phase(PG8_LAS unsigned char* lds, const Gemm g, const Sched& S, const Epi& E) {
;     ...
;             PG8_WAIT_V(8); PG8_WAIT_L(0); PG8_BAR; PG8_MMA(1, 0, At, B0); PG8_MMA(1, 1, At, B1); PG8_BAR; PG8_SCHED;
;             PG8_LDB(B0, 1, 0); PG8_LDB(B1, 1, 1); PG8_SCHED; PG8_LDA(At, 1, 0); PG8_STAGE(PG8_SA(0, 1), a2 + hstep, voffA);
;             PG8_WAIT_V(8); PG8_WAIT_L(0); PG8_BAR; PG8_MMA(0, 0, At, B0); PG8_MMA(0, 1, At, B1); PG8_BAR; PG8_SCHED;
	v_mfma_f32_16x16x32_bf16 v[60:63], v[144:147], v[188:191], v[60:63]
	v_mfma_f32_16x16x32_bf16 v[56:59], v[152:155], v[188:191], v[56:59]
	v_mfma_f32_16x16x32_bf16 v[52:55], v[144:147], v[196:199], v[52:55]
	v_mfma_f32_16x16x32_bf16 v[44:47], v[152:155], v[196:199], v[44:47]
	v_mfma_f32_16x16x32_bf16 v[36:39], v[144:147], v[204:207], v[36:39]
	v_mfma_f32_16x16x32_bf16 v[28:31], v[152:155], v[204:207], v[28:31]
	v_mfma_f32_16x16x32_bf16 v[20:23], v[144:147], v[212:215], v[20:23]
	v_mfma_f32_16x16x32_bf16 v[12:15], v[152:155], v[212:215], v[12:15]
	v_mfma_f32_16x16x32_bf16 v[60:63], v[148:151], v[192:195], v[60:63]
	v_mfma_f32_16x16x32_bf16 v[56:59], v[156:159], v[192:195], v[56:59]
	v_mfma_f32_16x16x32_bf16 v[52:55], v[148:151], v[200:203], v[52:55]
	v_mfma_f32_16x16x32_bf16 v[44:47], v[156:159], v[200:203], v[44:47]
	v_mfma_f32_16x16x32_bf16 v[36:39], v[148:151], v[208:211], v[36:39]
	v_mfma_f32_16x16x32_bf16 v[28:31], v[156:159], v[208:211], v[28:31]
	v_mfma_f32_16x16x32_bf16 v[20:23], v[148:151], v[218:221], v[20:23]
	v_mfma_f32_16x16x32_bf16 v[12:15], v[156:159], v[218:221], v[12:15]
	v_mfma_f32_16x16x32_bf16 v[48:51], v[172:175], v[188:191], v[48:51]
	v_mfma_f32_16x16x32_bf16 v[40:43], v[180:183], v[188:191], v[40:43]
	v_mfma_f32_16x16x32_bf16 v[32:35], v[172:175], v[196:199], v[32:35]
	v_mfma_f32_16x16x32_bf16 v[24:27], v[180:183], v[196:199], v[24:27]
	v_mfma_f32_16x16x32_bf16 v[16:19], v[172:175], v[204:207], v[16:19]
	v_mfma_f32_16x16x32_bf16 v[8:11], v[180:183], v[204:207], v[8:11]
	v_mfma_f32_16x16x32_bf16 v[4:7], v[172:175], v[212:215], v[4:7]
	v_mfma_f32_16x16x32_bf16 v[0:3], v[180:183], v[212:215], v[0:3]
	v_mfma_f32_16x16x32_bf16 v[48:51], v[176:179], v[192:195], v[48:51]
	v_mfma_f32_16x16x32_bf16 v[40:43], v[184:187], v[192:195], v[40:43]
	v_mfma_f32_16x16x32_bf16 v[32:35], v[176:179], v[200:203], v[32:35]
	v_mfma_f32_16x16x32_bf16 v[24:27], v[184:187], v[200:203], v[24:27]
	v_mfma_f32_16x16x32_bf16 v[16:19], v[176:179], v[208:211], v[16:19]
	v_mfma_f32_16x16x32_bf16 v[8:11], v[184:187], v[208:211], v[8:11]
	v_mfma_f32_16x16x32_bf16 v[4:7], v[176:179], v[218:221], v[4:7]
	v_mfma_f32_16x16x32_bf16 v[0:3], v[184:187], v[218:221], v[0:3]
	s_barrier
	s_setprio 0
	s_add_i32 s67, 0, 0x18000
	s_add_i32 s76, 0, 0x1c000
	v_add_u32_e32 v156, s67, v163
	v_add_u32_e32 v171, s76, v163
	ds_read_b128 v[144:147], v156
	ds_read_b128 v[148:151], v156 offset:1024
	ds_read_b128 v[152:155], v156 offset:2048
	ds_read_b128 v[156:159], v156 offset:3072
	ds_read_b128 v[172:175], v171
	ds_read_b128 v[176:179], v171 offset:1024
	ds_read_b128 v[180:183], v171 offset:2048
	ds_read_b128 v[184:187], v171 offset:3072
	s_add_u32 s74, s94, 0x80000
	s_addc_u32 s75, s95, 0
	s_mov_b32 m0, s23
	v_lshl_add_u64 v[230:231], s[74:75], 0, v[134:135]
	ds_read_b128 v[188:191], v168 offset:32768
	ds_read_b128 v[192:195], v168 offset:33792
	ds_read_b128 v[196:199], v168 offset:34816
	ds_read_b128 v[200:203], v168 offset:35840
	ds_read_b128 v[204:207], v168 offset:36864
	ds_read_b128 v[208:211], v168 offset:37888
	ds_read_b128 v[212:215], v168 offset:38912
	ds_read_b128 v[218:221], v168 offset:39936
	global_load_lds_dwordx4 v[230:231], off
	v_lshl_add_u64 v[230:231], s[74:75], 0, v[130:131]
	s_mov_b32 m0, s34
	s_nop 0
	global_load_lds_dwordx4 v[230:231], off
	s_waitcnt vmcnt(8)
	s_waitcnt lgkmcnt(0)
	s_setprio 1
	s_barrier
	v_mfma_f32_16x16x32_bf16 v[124:127], v[144:147], v[188:191], v[124:127]
	v_mfma_f32_16x16x32_bf16 v[120:123], v[152:155], v[188:191], v[120:123]
	v_mfma_f32_16x16x32_bf16 v[108:111], v[144:147], v[196:199], v[108:111]
	v_mfma_f32_16x16x32_bf16 v[104:107], v[152:155], v[196:199], v[104:107]
	v_mfma_f32_16x16x32_bf16 v[100:103], v[144:147], v[204:207], v[100:103]
	v_mfma_f32_16x16x32_bf16 v[92:95], v[152:155], v[204:207], v[92:95]
	v_mfma_f32_16x16x32_bf16 v[84:87], v[144:147], v[212:215], v[84:87]
	v_mfma_f32_16x16x32_bf16 v[76:79], v[152:155], v[212:215], v[76:79]
	v_mfma_f32_16x16x32_bf16 v[124:127], v[148:151], v[192:195], v[124:127]
	v_mfma_f32_16x16x32_bf16 v[120:123], v[156:159], v[192:195], v[120:123]
	v_mfma_f32_16x16x32_bf16 v[108:111], v[148:151], v[200:203], v[108:111]
	v_mfma_f32_16x16x32_bf16 v[104:107], v[156:159], v[200:203], v[104:107]
	v_mfma_f32_16x16x32_bf16 v[100:103], v[148:151], v[208:211], v[100:103]
	v_mfma_f32_16x16x32_bf16 v[92:95], v[156:159], v[208:211], v[92:95]
	v_mfma_f32_16x16x32_bf16 v[84:87], v[148:151], v[218:221], v[84:87]
	v_mfma_f32_16x16x32_bf16 v[76:79], v[156:159], v[218:221], v[76:79]
	v_mfma_f32_16x16x32_bf16 v[116:119], v[172:175], v[188:191], v[116:119]
	v_mfma_f32_16x16x32_bf16 v[112:115], v[180:183], v[188:191], v[112:115]
	v_mfma_f32_16x16x32_bf16 v[96:99], v[172:175], v[196:199], v[96:99]
	v_mfma_f32_16x16x32_bf16 v[88:91], v[180:183], v[196:199], v[88:91]
	v_mfma_f32_16x16x32_bf16 v[80:83], v[172:175], v[204:207], v[80:83]
	v_mfma_f32_16x16x32_bf16 v[72:75], v[180:183], v[204:207], v[72:75]
	v_mfma_f32_16x16x32_bf16 v[68:71], v[172:175], v[212:215], v[68:71]
	v_mfma_f32_16x16x32_bf16 v[64:67], v[180:183], v[212:215], v[64:67]
	v_mfma_f32_16x16x32_bf16 v[116:119], v[176:179], v[192:195], v[116:119]
	v_mfma_f32_16x16x32_bf16 v[112:115], v[184:187], v[192:195], v[112:115]
	v_mfma_f32_16x16x32_bf16 v[96:99], v[176:179], v[200:203], v[96:99]
	v_mfma_f32_16x16x32_bf16 v[88:91], v[184:187], v[200:203], v[88:91]
	v_mfma_f32_16x16x32_bf16 v[80:83], v[176:179], v[208:211], v[80:83]
	v_mfma_f32_16x16x32_bf16 v[72:75], v[184:187], v[208:211], v[72:75]
	v_mfma_f32_16x16x32_bf16 v[68:71], v[176:179], v[218:221], v[68:71]
	v_mfma_f32_16x16x32_bf16 v[64:67], v[184:187], v[218:221], v[64:67]
	s_barrier
; #define PG8_STAGE(bufoff, gbase, voff) do { _Pragma("unroll") for (int _i = 0; _i < 2; ++_i) \
;         __builtin_amdgcn_global_load_lds((const unsigned*)((const char*)(gbase) + (voff)[_i]), (PG8_LAS unsigned*)(lds + (bufoff) + ldsw + _i * 8192), 16, 0, 0); } while (0)
; #define PG8_LDA(dst, b, h) do { _Pragma("unroll") for (int m = 0; m < 4; ++m) _Pragma("unroll") for (int k = 0; k < 2; ++k) dst[m][k] = *(const PG8_LAS bf16x8*)(lds + PG8_SA(b, h) + aoff + m * 2048 + k * 1024); } while (0)
; #define PG8_MMA(ai, bj, At, Bt) do { __builtin_amdgcn_s_setprio(1); _Pragma("unroll") for (int m = 0; m < 4; ++m) _Pragma("unroll") for (int n = 0; n < 2; ++n) _Pragma("unroll") for (int k = 0; k < 2; ++k) \
;         acc[ai][bj][m][n] = __builtin_amdgcn_mfma_f32_16x16x32_bf16(Bt[n][k], At[m][k], acc[ai][bj][m][n], 0, 0, 0); __builtin_amdgcn_s_setprio(0); } while (0)
; #define PG8_WAIT_V(n) asm volatile("s_waitcnt vmcnt(" #n ")" ::: "memory")
; #define PG8_WAIT_L(n) asm volatile("s_waitcnt lgkmcnt(" #n ")" ::: "memory")
; #define PG8_BAR __builtin_amdgcn_s_barrier()
; #define PG8_SCHED __builtin_amdgcn_sched_barrier(0)
; template <class Epi, class Sched, bool ALIGN_EPI = false, bool SP2 = false>
; __device__ __forceinline__ void gemm_phase(PG8_LAS unsigned char* lds, const Gemm g, const Sched& S, const Epi& E) {
;     ...
;             PG8_LDA(At, 1, 1); PG8_STAGE(PG8_SB(1, 0), b3, voffB); PG8_STAGE(PG8_SB(1, 1), b3 + hstep, voffB); PG8_STAGE(PG8_SA(1, 0), a3, voffA);
;             PG8_WAIT_V(8); PG8_WAIT_L(0); PG8_BAR; PG8_MMA(1, 0, At, B0); PG8_MMA(1, 1, At, B1); PG8_BAR; PG8_SCHED;
;     ...
;         }
;         if constexpr (ALIGN_EPI) { if (wr == 0) PG8_BAR; }
	s_setprio 0
	s_add_i32 s67, s67, s3
	v_lshl_add_u64 v[160:161], v[160:161], 0, s[10:11]
	s_mov_b32 m0, s67
	ds_read_b128 v[188:191], v168 offset:49152
	ds_read_b128 v[192:195], v168 offset:50176
	ds_read_b128 v[196:199], v168 offset:51200
	ds_read_b128 v[200:203], v168 offset:52224
	ds_read_b128 v[204:207], v168 offset:53248
	ds_read_b128 v[208:211], v168 offset:54272
	ds_read_b128 v[212:215], v168 offset:55296
	ds_read_b128 v[218:221], v168 offset:56320
	global_load_lds_dwordx4 v[160:161], off
	s_add_i32 m0, s67, 0x2000
	s_add_u32 s74, s82, 0x80080
	v_lshl_add_u64 v[160:161], v[224:225], 0, s[10:11]
	s_addc_u32 s75, s83, 0
	s_add_i32 s67, s76, s3
	global_load_lds_dwordx4 v[160:161], off
	v_lshl_add_u64 v[160:161], s[74:75], 0, v[132:133]
	s_mov_b32 m0, s67
	s_nop 0
	global_load_lds_dwordx4 v[160:161], off
	v_lshl_add_u64 v[160:161], s[74:75], 0, v[128:129]
	s_add_i32 m0, s67, 0x2000
	s_nop 0
	global_load_lds_dwordx4 v[160:161], off
	v_lshl_add_u64 v[160:161], v[226:227], 0, s[10:11]
	s_mov_b32 m0, s68
	s_nop 0
	global_load_lds_dwordx4 v[160:161], off
	v_lshl_add_u64 v[160:161], v[228:229], 0, s[10:11]
	s_mov_b32 m0, s69
	s_nop 0
	global_load_lds_dwordx4 v[160:161], off
	s_waitcnt vmcnt(8)
	s_waitcnt lgkmcnt(0)
	s_setprio 1
	s_barrier
	v_mfma_f32_16x16x32_bf16 v[60:63], v[144:147], v[188:191], v[60:63]
	v_mfma_f32_16x16x32_bf16 v[56:59], v[152:155], v[188:191], v[56:59]
	v_mfma_f32_16x16x32_bf16 v[52:55], v[144:147], v[196:199], v[52:55]
	v_mfma_f32_16x16x32_bf16 v[44:47], v[152:155], v[196:199], v[44:47]
	v_mfma_f32_16x16x32_bf16 v[36:39], v[144:147], v[204:207], v[36:39]
	v_mfma_f32_16x16x32_bf16 v[28:31], v[152:155], v[204:207], v[28:31]
	v_mfma_f32_16x16x32_bf16 v[20:23], v[144:147], v[212:215], v[20:23]
	v_mfma_f32_16x16x32_bf16 v[12:15], v[152:155], v[212:215], v[12:15]
	v_mfma_f32_16x16x32_bf16 v[60:63], v[148:151], v[192:195], v[60:63]
	v_mfma_f32_16x16x32_bf16 v[56:59], v[156:159], v[192:195], v[56:59]
	v_mfma_f32_16x16x32_bf16 v[52:55], v[148:151], v[200:203], v[52:55]
	v_mfma_f32_16x16x32_bf16 v[44:47], v[156:159], v[200:203], v[44:47]
	v_mfma_f32_16x16x32_bf16 v[36:39], v[148:151], v[208:211], v[36:39]
	v_mfma_f32_16x16x32_bf16 v[28:31], v[156:159], v[208:211], v[28:31]
	v_mfma_f32_16x16x32_bf16 v[20:23], v[148:151], v[218:221], v[20:23]
	v_mfma_f32_16x16x32_bf16 v[12:15], v[156:159], v[218:221], v[12:15]
	v_mfma_f32_16x16x32_bf16 v[48:51], v[172:175], v[188:191], v[48:51]
	v_mfma_f32_16x16x32_bf16 v[40:43], v[180:183], v[188:191], v[40:43]
	v_mfma_f32_16x16x32_bf16 v[32:35], v[172:175], v[196:199], v[32:35]
	v_mfma_f32_16x16x32_bf16 v[24:27], v[180:183], v[196:199], v[24:27]
	v_mfma_f32_16x16x32_bf16 v[16:19], v[172:175], v[204:207], v[16:19]
	v_mfma_f32_16x16x32_bf16 v[8:11], v[180:183], v[204:207], v[8:11]
	v_mfma_f32_16x16x32_bf16 v[4:7], v[172:175], v[212:215], v[4:7]
	v_mfma_f32_16x16x32_bf16 v[0:3], v[180:183], v[212:215], v[0:3]
	v_mfma_f32_16x16x32_bf16 v[48:51], v[176:179], v[192:195], v[48:51]
	v_mfma_f32_16x16x32_bf16 v[40:43], v[184:187], v[192:195], v[40:43]
	v_mfma_f32_16x16x32_bf16 v[32:35], v[176:179], v[200:203], v[32:35]
	v_mfma_f32_16x16x32_bf16 v[24:27], v[184:187], v[200:203], v[24:27]
	v_mfma_f32_16x16x32_bf16 v[16:19], v[176:179], v[208:211], v[16:19]
	v_mfma_f32_16x16x32_bf16 v[8:11], v[184:187], v[208:211], v[8:11]
	v_mfma_f32_16x16x32_bf16 v[4:7], v[176:179], v[218:221], v[4:7]
	v_mfma_f32_16x16x32_bf16 v[0:3], v[184:187], v[218:221], v[0:3]
	s_barrier
	s_setprio 0
	s_add_i32 s66, s66, 2
	s_add_u32 s92, s92, 0x100
	s_addc_u32 s93, s93, 0
	s_add_u32 s85, s85, 0x100
	s_addc_u32 s91, s91, 0
	s_cmp_gt_u32 s66, 29
	s_cbranch_scc0 .LBB0_493
	s_and_b64 vcc, exec, s[44:45]
	s_cbranch_vccz .LBB0_496
	s_barrier

; #define PG8_STAGE(bufoff, gbase, voff) do { _Pragma("unroll") for (int _i = 0; _i < 2; ++_i) \
;         __builtin_amdgcn_global_load_lds((const unsigned*)((const char*)(gbase) + (voff)[_i]), (PG8_LAS unsigned*)(lds + (bufoff) + ldsw + _i * 8192), 16, 0, 0); } while (0)
; #define PG8_LDA(dst, b, h) do { _Pragma("unroll") for (int m = 0; m < 4; ++m) _Pragma("unroll") for (int k = 0; k < 2; ++k) dst[m][k] = *(const PG8_LAS bf16x8*)(lds + PG8_SA(b, h) + aoff + m * 2048 + k * 1024); } while (0)
; #define PG8_LDB(dst, b, h) do { _Pragma("unroll") for (int n = 0; n < 2; ++n) _Pragma("unroll") for (int k = 0; k < 2; ++k) dst[n][k] = *(const PG8_LAS bf16x8*)(lds + PG8_SB(b, h) + boff + n * 2048 + k * 1024); } while (0)
; #define PG8_MMA(ai, bj, At, Bt) do { __builtin_amdgcn_s_setprio(1); _Pragma("unroll") for (int m = 0; m < 4; ++m) _Pragma("unroll") for (int n = 0; n < 2; ++n) _Pragma("unroll") for (int k = 0; k < 2; ++k) \
;         acc[ai][bj][m][n] = __builtin_amdgcn_mfma_f32_16x16x32_bf16(Bt[n][k], At[m][k], acc[ai][bj][m][n], 0, 0, 0); __builtin_amdgcn_s_setprio(0); } while (0)
; #define PG8_WAIT_V(n) asm volatile("s_waitcnt vmcnt(" #n ")" ::: "memory")
; #define PG8_WAIT_L(n) asm volatile("s_waitcnt lgkmcnt(" #n ")" ::: "memory")
; #define PG8_BAR __builtin_amdgcn_s_barrier()
; #define PG8_SCHED __builtin_amdgcn_sched_barrier(0)
; template <class Epi, class Sched, bool ALIGN_EPI = false, bool SP2 = false>
; __device__ __forceinline__ void gemm_phase(PG8_LAS unsigned char* lds, const Gemm g, const Sched& S, const Epi& E) {
;     ...
;             const bool last = (t == nt - 2);
;             const char* a1 = cA + (size_t)(t + 1) * kstep;
;             const char* a2 = last ? nA : cA + (size_t)(t + 2) * kstep; const char* b2 = last ? nB : cB + (size_t)(t + 2) * kstep;
;     ...
;             PG8_LDB(B0, 0, 0); PG8_LDB(B1, 0, 1); PG8_SCHED; PG8_LDA(At, 0, 0); PG8_STAGE(PG8_SA(1, 1), a1 + hstep, voffA);
;             PG8_WAIT_V(8); PG8_WAIT_L(0); PG8_BAR; PG8_MMA(0, 0, At, B0); PG8_MMA(0, 1, At, B1); PG8_BAR; PG8_SCHED;
;             PG8_LDA(At, 0, 1); PG8_STAGE(PG8_SB(0, 0), b2, voffB); PG8_STAGE(PG8_SB(0, 1), b2 + hstep, voffB); PG8_STAGE(PG8_SA(0, 0), a2, voffA);
;             PG8_WAIT_V(8); PG8_WAIT_L(0); PG8_BAR; PG8_MMA(1, 0, At, B0); PG8_MMA(1, 1, At, B1); PG8_BAR; PG8_SCHED;
.LBB0_781:
	ds_read_b128 v[144:147], v153
	ds_read_b128 v[156:159], v153 offset:1024
	ds_read_b128 v[160:163], v153 offset:2048
	ds_read_b128 v[164:167], v153 offset:3072
	ds_read_b128 v[168:171], v154
	ds_read_b128 v[172:175], v154 offset:1024
	ds_read_b128 v[176:179], v154 offset:2048
	ds_read_b128 v[180:183], v154 offset:3072
	s_add_u32 s48, s46, 0xfffc0080
	s_addc_u32 s49, s47, -1
	s_cmp_eq_u32 s66, 12
	s_cselect_b32 s51, s12, s49
	s_cselect_b32 s50, s13, s48
	s_cselect_b32 s49, s21, s72
	s_cselect_b32 s48, s29, s71
	v_lshl_add_u64 v[148:149], s[46:47], 0, v[136:137]
	s_add_i32 m0, s14, 0xc000
	ds_read_b128 v[184:187], v155
	ds_read_b128 v[188:191], v155 offset:1024
	ds_read_b128 v[192:195], v155 offset:2048
	ds_read_b128 v[196:199], v155 offset:3072
	ds_read_b128 v[200:203], v155 offset:4096
	ds_read_b128 v[204:207], v155 offset:5120
	ds_read_b128 v[208:211], v155 offset:6144
	ds_read_b128 v[212:215], v155 offset:7168
	global_load_lds_dwordx4 v[148:149], off
	v_lshl_add_u64 v[148:149], s[46:47], 0, v[138:139]
	s_add_i32 m0, s14, 0xe000
	s_nop 0
	global_load_lds_dwordx4 v[148:149], off
	s_waitcnt vmcnt(8)
	s_waitcnt lgkmcnt(0)
	s_setprio 1
	s_barrier
	v_mfma_f32_16x16x32_bf16 v[124:127], v[144:147], v[184:187], v[124:127]
	v_mfma_f32_16x16x32_bf16 v[120:123], v[160:163], v[184:187], v[120:123]
	v_mfma_f32_16x16x32_bf16 v[108:111], v[144:147], v[192:195], v[108:111]
	v_mfma_f32_16x16x32_bf16 v[104:107], v[160:163], v[192:195], v[104:107]
	v_mfma_f32_16x16x32_bf16 v[96:99], v[144:147], v[200:203], v[96:99]
	v_mfma_f32_16x16x32_bf16 v[88:91], v[160:163], v[200:203], v[88:91]
	v_mfma_f32_16x16x32_bf16 v[80:83], v[144:147], v[208:211], v[80:83]
	v_mfma_f32_16x16x32_bf16 v[72:75], v[160:163], v[208:211], v[72:75]
	v_mfma_f32_16x16x32_bf16 v[124:127], v[156:159], v[188:191], v[124:127]
	v_mfma_f32_16x16x32_bf16 v[120:123], v[164:167], v[188:191], v[120:123]
	v_mfma_f32_16x16x32_bf16 v[108:111], v[156:159], v[196:199], v[108:111]
	v_mfma_f32_16x16x32_bf16 v[104:107], v[164:167], v[196:199], v[104:107]
	v_mfma_f32_16x16x32_bf16 v[96:99], v[156:159], v[204:207], v[96:99]
	v_mfma_f32_16x16x32_bf16 v[88:91], v[164:167], v[204:207], v[88:91]
	v_mfma_f32_16x16x32_bf16 v[80:83], v[156:159], v[212:215], v[80:83]
	v_mfma_f32_16x16x32_bf16 v[72:75], v[164:167], v[212:215], v[72:75]
	v_mfma_f32_16x16x32_bf16 v[116:119], v[168:171], v[184:187], v[116:119]
	v_mfma_f32_16x16x32_bf16 v[112:115], v[176:179], v[184:187], v[112:115]
	v_mfma_f32_16x16x32_bf16 v[100:103], v[168:171], v[192:195], v[100:103]
	v_mfma_f32_16x16x32_bf16 v[92:95], v[176:179], v[192:195], v[92:95]
	v_mfma_f32_16x16x32_bf16 v[84:87], v[168:171], v[200:203], v[84:87]
	v_mfma_f32_16x16x32_bf16 v[76:79], v[176:179], v[200:203], v[76:79]
	v_mfma_f32_16x16x32_bf16 v[68:71], v[168:171], v[208:211], v[68:71]
	v_mfma_f32_16x16x32_bf16 v[64:67], v[176:179], v[208:211], v[64:67]
	v_mfma_f32_16x16x32_bf16 v[116:119], v[172:175], v[188:191], v[116:119]
	v_mfma_f32_16x16x32_bf16 v[112:115], v[180:183], v[188:191], v[112:115]
	v_mfma_f32_16x16x32_bf16 v[100:103], v[172:175], v[196:199], v[100:103]
	v_mfma_f32_16x16x32_bf16 v[92:95], v[180:183], v[196:199], v[92:95]
	v_mfma_f32_16x16x32_bf16 v[84:87], v[172:175], v[204:207], v[84:87]
	v_mfma_f32_16x16x32_bf16 v[76:79], v[180:183], v[204:207], v[76:79]
	v_mfma_f32_16x16x32_bf16 v[68:71], v[172:175], v[212:215], v[68:71]
	v_mfma_f32_16x16x32_bf16 v[64:67], v[180:183], v[212:215], v[64:67]
	s_barrier
	s_setprio 0
	s_add_i32 s67, s68, s3
	v_lshl_add_u64 v[148:149], s[48:49], 0, v[132:133]
	s_mov_b32 m0, s67
	ds_read_b128 v[184:187], v155 offset:16384
	ds_read_b128 v[188:191], v155 offset:17408
	ds_read_b128 v[192:195], v155 offset:18432
	ds_read_b128 v[196:199], v155 offset:19456
	ds_read_b128 v[200:203], v155 offset:20480
	ds_read_b128 v[204:207], v155 offset:21504
	ds_read_b128 v[208:211], v155 offset:22528
	ds_read_b128 v[212:215], v155 offset:23552
	global_load_lds_dwordx4 v[148:149], off
	s_add_i32 m0, s67, 0x2000
	s_add_u32 s74, s48, 0x40000
	v_lshl_add_u64 v[216:217], s[48:49], 0, v[128:129]
	s_addc_u32 s75, s49, 0
	s_add_i32 s67, s69, s3
	global_load_lds_dwordx4 v[216:217], off
	v_lshl_add_u64 v[218:219], s[74:75], 0, v[132:133]
	s_mov_b32 m0, s67
	v_lshl_add_u64 v[220:221], s[50:51], 0, v[130:131]
	global_load_lds_dwordx4 v[218:219], off
	v_lshl_add_u64 v[218:219], s[74:75], 0, v[128:129]
	s_add_i32 m0, s67, 0x2000
	s_nop 0
	global_load_lds_dwordx4 v[218:219], off
	v_lshl_add_u64 v[218:219], s[50:51], 0, v[134:135]
	s_mov_b32 m0, s14
	s_nop 0
	global_load_lds_dwordx4 v[218:219], off
	s_mov_b32 m0, s15
	s_nop 0
	global_load_lds_dwordx4 v[220:221], off
	s_waitcnt vmcnt(8)
	s_waitcnt lgkmcnt(0)
	s_setprio 1
	s_barrier
; #define PG8_STAGE(bufoff, gbase, voff) do { _Pragma("unroll") for (int _i = 0; _i < 2; ++_i) \
;         __builtin_amdgcn_global_load_lds((const unsigned*)((const char*)(gbase) + (voff)[_i]), (PG8_LAS unsigned*)(lds + (bufoff) + ldsw + _i * 8192), 16, 0, 0); } while (0)
; #define PG8_LDA(dst, b, h) do { _Pragma("unroll") for (int m = 0; m < 4; ++m) _Pragma("unroll") for (int k = 0; k < 2; ++k) dst[m][k] = *(const PG8_LAS bf16x8*)(lds + PG8_SA(b, h) + aoff + m * 2048 + k * 1024); } while (0)
; #define PG8_LDB(dst, b, h) do { _Pragma("unroll") for (int n = 0; n < 2; ++n) _Pragma("unroll") for (int k = 0; k < 2; ++k) dst[n][k] = *(const PG8_LAS bf16x8*)(lds + PG8_SB(b, h) + boff + n * 2048 + k * 1024); } while (0)
; #define PG8_MMA(ai, bj, At, Bt) do { __builtin_amdgcn_s_setprio(1); _Pragma("unroll") for (int m = 0; m < 4; ++m) _Pragma("unroll") for (int n = 0; n < 2; ++n) _Pragma("unroll") for (int k = 0; k < 2; ++k) \
;         acc[ai][bj][m][n] = __builtin_amdgcn_mfma_f32_16x16x32_bf16(Bt[n][k], At[m][k], acc[ai][bj][m][n], 0, 0, 0); __builtin_amdgcn_s_setprio(0); } while (0)
; #define PG8_WAIT_V(n) asm volatile("s_waitcnt vmcnt(" #n ")" ::: "memory")
; #define PG8_WAIT_L(n) asm volatile("s_waitcnt lgkmcnt(" #n ")" ::: "memory")
; #define PG8_BAR __builtin_amdgcn_s_barrier()
; #define PG8_SCHED __builtin_amdgcn_sched_barrier(0)
; template <class Epi, class Sched, bool ALIGN_EPI = false, bool SP2 = false>
; __device__ __forceinline__ void gemm_phase(PG8_LAS unsigned char* lds, const Gemm g, const Sched& S, const Epi& E) {
;     ...
;             PG8_WAIT_V(8); PG8_WAIT_L(0); PG8_BAR; PG8_MMA(1, 0, At, B0); PG8_MMA(1, 1, At, B1); PG8_BAR; PG8_SCHED;
;             PG8_LDB(B0, 1, 0); PG8_LDB(B1, 1, 1); PG8_SCHED; PG8_LDA(At, 1, 0); PG8_STAGE(PG8_SA(0, 1), a2 + hstep, voffA);
;             PG8_WAIT_V(8); PG8_WAIT_L(0); PG8_BAR; PG8_MMA(0, 0, At, B0); PG8_MMA(0, 1, At, B1); PG8_BAR; PG8_SCHED;
	v_mfma_f32_16x16x32_bf16 v[60:63], v[144:147], v[184:187], v[60:63]
	v_mfma_f32_16x16x32_bf16 v[56:59], v[160:163], v[184:187], v[56:59]
	v_mfma_f32_16x16x32_bf16 v[48:51], v[144:147], v[192:195], v[48:51]
	v_mfma_f32_16x16x32_bf16 v[40:43], v[160:163], v[192:195], v[40:43]
	v_mfma_f32_16x16x32_bf16 v[32:35], v[144:147], v[200:203], v[32:35]
	v_mfma_f32_16x16x32_bf16 v[24:27], v[160:163], v[200:203], v[24:27]
	v_mfma_f32_16x16x32_bf16 v[16:19], v[144:147], v[208:211], v[16:19]
	v_mfma_f32_16x16x32_bf16 v[8:11], v[160:163], v[208:211], v[8:11]
	v_mfma_f32_16x16x32_bf16 v[60:63], v[156:159], v[188:191], v[60:63]
	v_mfma_f32_16x16x32_bf16 v[56:59], v[164:167], v[188:191], v[56:59]
	v_mfma_f32_16x16x32_bf16 v[48:51], v[156:159], v[196:199], v[48:51]
	v_mfma_f32_16x16x32_bf16 v[40:43], v[164:167], v[196:199], v[40:43]
	v_mfma_f32_16x16x32_bf16 v[32:35], v[156:159], v[204:207], v[32:35]
	v_mfma_f32_16x16x32_bf16 v[24:27], v[164:167], v[204:207], v[24:27]
	v_mfma_f32_16x16x32_bf16 v[16:19], v[156:159], v[212:215], v[16:19]
	v_mfma_f32_16x16x32_bf16 v[8:11], v[164:167], v[212:215], v[8:11]
	v_mfma_f32_16x16x32_bf16 v[52:55], v[168:171], v[184:187], v[52:55]
	v_mfma_f32_16x16x32_bf16 v[44:47], v[176:179], v[184:187], v[44:47]
	v_mfma_f32_16x16x32_bf16 v[36:39], v[168:171], v[192:195], v[36:39]
	v_mfma_f32_16x16x32_bf16 v[28:31], v[176:179], v[192:195], v[28:31]
	v_mfma_f32_16x16x32_bf16 v[20:23], v[168:171], v[200:203], v[20:23]
	v_mfma_f32_16x16x32_bf16 v[12:15], v[176:179], v[200:203], v[12:15]
	v_mfma_f32_16x16x32_bf16 v[4:7], v[168:171], v[208:211], v[4:7]
	v_mfma_f32_16x16x32_bf16 v[0:3], v[176:179], v[208:211], v[0:3]
	v_mfma_f32_16x16x32_bf16 v[52:55], v[172:175], v[188:191], v[52:55]
	v_mfma_f32_16x16x32_bf16 v[44:47], v[180:183], v[188:191], v[44:47]
	v_mfma_f32_16x16x32_bf16 v[36:39], v[172:175], v[196:199], v[36:39]
	v_mfma_f32_16x16x32_bf16 v[28:31], v[180:183], v[196:199], v[28:31]
	v_mfma_f32_16x16x32_bf16 v[20:23], v[172:175], v[204:207], v[20:23]
	v_mfma_f32_16x16x32_bf16 v[12:15], v[180:183], v[204:207], v[12:15]
	v_mfma_f32_16x16x32_bf16 v[4:7], v[172:175], v[212:215], v[4:7]
	v_mfma_f32_16x16x32_bf16 v[0:3], v[180:183], v[212:215], v[0:3]
	s_barrier
	s_setprio 0
	s_add_i32 s67, 0, 0x18000
	s_add_i32 s74, 0, 0x1c000
	v_add_u32_e32 v164, s67, v151
	v_add_u32_e32 v180, s74, v151
	ds_read_b128 v[144:147], v164
	ds_read_b128 v[156:159], v164 offset:1024
	ds_read_b128 v[160:163], v164 offset:2048
	ds_read_b128 v[164:167], v164 offset:3072
	ds_read_b128 v[168:171], v180
	ds_read_b128 v[172:175], v180 offset:1024
	ds_read_b128 v[176:179], v180 offset:2048
	ds_read_b128 v[180:183], v180 offset:3072
	s_add_u32 s50, s50, 0x40000
	s_addc_u32 s51, s51, 0
	s_mov_b32 m0, s22
	v_lshl_add_u64 v[226:227], s[50:51], 0, v[134:135]
	ds_read_b128 v[184:187], v155 offset:32768
	ds_read_b128 v[188:191], v155 offset:33792
	ds_read_b128 v[192:195], v155 offset:34816
	ds_read_b128 v[196:199], v155 offset:35840
	ds_read_b128 v[200:203], v155 offset:36864
	ds_read_b128 v[204:207], v155 offset:37888
	ds_read_b128 v[208:211], v155 offset:38912
	ds_read_b128 v[212:215], v155 offset:39936
	global_load_lds_dwordx4 v[226:227], off
	v_lshl_add_u64 v[226:227], s[50:51], 0, v[130:131]
	s_mov_b32 m0, s23
	s_nop 0
	global_load_lds_dwordx4 v[226:227], off
	s_waitcnt vmcnt(8)
	s_waitcnt lgkmcnt(0)
	s_setprio 1
	s_barrier
	v_mfma_f32_16x16x32_bf16 v[124:127], v[144:147], v[184:187], v[124:127]
	v_mfma_f32_16x16x32_bf16 v[120:123], v[160:163], v[184:187], v[120:123]
	v_mfma_f32_16x16x32_bf16 v[108:111], v[144:147], v[192:195], v[108:111]
	v_mfma_f32_16x16x32_bf16 v[104:107], v[160:163], v[192:195], v[104:107]
	v_mfma_f32_16x16x32_bf16 v[96:99], v[144:147], v[200:203], v[96:99]
	v_mfma_f32_16x16x32_bf16 v[88:91], v[160:163], v[200:203], v[88:91]
	v_mfma_f32_16x16x32_bf16 v[80:83], v[144:147], v[208:211], v[80:83]
	v_mfma_f32_16x16x32_bf16 v[72:75], v[160:163], v[208:211], v[72:75]
	v_mfma_f32_16x16x32_bf16 v[124:127], v[156:159], v[188:191], v[124:127]
	v_mfma_f32_16x16x32_bf16 v[120:123], v[164:167], v[188:191], v[120:123]
	v_mfma_f32_16x16x32_bf16 v[108:111], v[156:159], v[196:199], v[108:111]
	v_mfma_f32_16x16x32_bf16 v[104:107], v[164:167], v[196:199], v[104:107]
	v_mfma_f32_16x16x32_bf16 v[96:99], v[156:159], v[204:207], v[96:99]
	v_mfma_f32_16x16x32_bf16 v[88:91], v[164:167], v[204:207], v[88:91]
	v_mfma_f32_16x16x32_bf16 v[80:83], v[156:159], v[212:215], v[80:83]
	v_mfma_f32_16x16x32_bf16 v[72:75], v[164:167], v[212:215], v[72:75]
	v_mfma_f32_16x16x32_bf16 v[116:119], v[168:171], v[184:187], v[116:119]
	v_mfma_f32_16x16x32_bf16 v[112:115], v[176:179], v[184:187], v[112:115]
	v_mfma_f32_16x16x32_bf16 v[100:103], v[168:171], v[192:195], v[100:103]
	v_mfma_f32_16x16x32_bf16 v[92:95], v[176:179], v[192:195], v[92:95]
	v_mfma_f32_16x16x32_bf16 v[84:87], v[168:171], v[200:203], v[84:87]
	v_mfma_f32_16x16x32_bf16 v[76:79], v[176:179], v[200:203], v[76:79]
	v_mfma_f32_16x16x32_bf16 v[68:71], v[168:171], v[208:211], v[68:71]
	v_mfma_f32_16x16x32_bf16 v[64:67], v[176:179], v[208:211], v[64:67]
	v_mfma_f32_16x16x32_bf16 v[116:119], v[172:175], v[188:191], v[116:119]
	v_mfma_f32_16x16x32_bf16 v[112:115], v[180:183], v[188:191], v[112:115]
	v_mfma_f32_16x16x32_bf16 v[100:103], v[172:175], v[196:199], v[100:103]
	v_mfma_f32_16x16x32_bf16 v[92:95], v[180:183], v[196:199], v[92:95]
	v_mfma_f32_16x16x32_bf16 v[84:87], v[172:175], v[204:207], v[84:87]
	v_mfma_f32_16x16x32_bf16 v[76:79], v[180:183], v[204:207], v[76:79]
	v_mfma_f32_16x16x32_bf16 v[68:71], v[172:175], v[212:215], v[68:71]
	v_mfma_f32_16x16x32_bf16 v[64:67], v[180:183], v[212:215], v[64:67]
	s_barrier
; #define PG8_STAGE(bufoff, gbase, voff) do { _Pragma("unroll") for (int _i = 0; _i < 2; ++_i) \
;         __builtin_amdgcn_global_load_lds((const unsigned*)((const char*)(gbase) + (voff)[_i]), (PG8_LAS unsigned*)(lds + (bufoff) + ldsw + _i * 8192), 16, 0, 0); } while (0)
; #define PG8_LDA(dst, b, h) do { _Pragma("unroll") for (int m = 0; m < 4; ++m) _Pragma("unroll") for (int k = 0; k < 2; ++k) dst[m][k] = *(const PG8_LAS bf16x8*)(lds + PG8_SA(b, h) + aoff + m * 2048 + k * 1024); } while (0)
; #define PG8_MMA(ai, bj, At, Bt) do { __builtin_amdgcn_s_setprio(1); _Pragma("unroll") for (int m = 0; m < 4; ++m) _Pragma("unroll") for (int n = 0; n < 2; ++n) _Pragma("unroll") for (int k = 0; k < 2; ++k) \
;         acc[ai][bj][m][n] = __builtin_amdgcn_mfma_f32_16x16x32_bf16(Bt[n][k], At[m][k], acc[ai][bj][m][n], 0, 0, 0); __builtin_amdgcn_s_setprio(0); } while (0)
; #define PG8_WAIT_V(n) asm volatile("s_waitcnt vmcnt(" #n ")" ::: "memory")
; #define PG8_WAIT_L(n) asm volatile("s_waitcnt lgkmcnt(" #n ")" ::: "memory")
; #define PG8_BAR __builtin_amdgcn_s_barrier()
; #define PG8_SCHED __builtin_amdgcn_sched_barrier(0)
; template <class Epi, class Sched, bool ALIGN_EPI = false, bool SP2 = false>
; __device__ __forceinline__ void gemm_phase(PG8_LAS unsigned char* lds, const Gemm g, const Sched& S, const Epi& E) {
;     ...
;             PG8_LDA(At, 1, 1); PG8_STAGE(PG8_SB(1, 0), b3, voffB); PG8_STAGE(PG8_SB(1, 1), b3 + hstep, voffB); PG8_STAGE(PG8_SA(1, 0), a3, voffA);
;             PG8_WAIT_V(8); PG8_WAIT_L(0); PG8_BAR; PG8_MMA(1, 0, At, B0); PG8_MMA(1, 1, At, B1); PG8_BAR; PG8_SCHED;
;     ...
;         }
;         if constexpr (ALIGN_EPI) { if (wr == 0) PG8_BAR; }
	s_setprio 0
	s_add_i32 s50, s67, s3
	v_lshl_add_u64 v[148:149], v[148:149], 0, s[16:17]
	s_mov_b32 m0, s50
	ds_read_b128 v[184:187], v155 offset:49152
	ds_read_b128 v[188:191], v155 offset:50176
	ds_read_b128 v[192:195], v155 offset:51200
	ds_read_b128 v[196:199], v155 offset:52224
	ds_read_b128 v[200:203], v155 offset:53248
	ds_read_b128 v[204:207], v155 offset:54272
	ds_read_b128 v[208:211], v155 offset:55296
	ds_read_b128 v[212:215], v155 offset:56320
	global_load_lds_dwordx4 v[148:149], off
	s_add_i32 m0, s50, 0x2000
	s_add_u32 s48, s48, 0x40080
	v_lshl_add_u64 v[148:149], v[216:217], 0, s[16:17]
	s_addc_u32 s49, s49, 0
	s_add_i32 s50, s74, s3
	global_load_lds_dwordx4 v[148:149], off
	v_lshl_add_u64 v[148:149], s[48:49], 0, v[132:133]
	s_mov_b32 m0, s50
	s_nop 0
	global_load_lds_dwordx4 v[148:149], off
	v_lshl_add_u64 v[148:149], s[48:49], 0, v[128:129]
	s_add_i32 m0, s50, 0x2000
	s_nop 0
	global_load_lds_dwordx4 v[148:149], off
	v_lshl_add_u64 v[148:149], v[218:219], 0, s[16:17]
	s_mov_b32 m0, s35
	s_nop 0
	global_load_lds_dwordx4 v[148:149], off
	v_lshl_add_u64 v[148:149], v[220:221], 0, s[16:17]
	s_mov_b32 m0, s45
	s_nop 0
	global_load_lds_dwordx4 v[148:149], off
	s_waitcnt vmcnt(8)
	s_waitcnt lgkmcnt(0)
	s_setprio 1
	s_barrier
	v_mfma_f32_16x16x32_bf16 v[60:63], v[144:147], v[184:187], v[60:63]
	v_mfma_f32_16x16x32_bf16 v[56:59], v[160:163], v[184:187], v[56:59]
	v_mfma_f32_16x16x32_bf16 v[48:51], v[144:147], v[192:195], v[48:51]
	v_mfma_f32_16x16x32_bf16 v[40:43], v[160:163], v[192:195], v[40:43]
	v_mfma_f32_16x16x32_bf16 v[32:35], v[144:147], v[200:203], v[32:35]
	v_mfma_f32_16x16x32_bf16 v[24:27], v[160:163], v[200:203], v[24:27]
	v_mfma_f32_16x16x32_bf16 v[16:19], v[144:147], v[208:211], v[16:19]
	v_mfma_f32_16x16x32_bf16 v[8:11], v[160:163], v[208:211], v[8:11]
	v_mfma_f32_16x16x32_bf16 v[60:63], v[156:159], v[188:191], v[60:63]
	v_mfma_f32_16x16x32_bf16 v[56:59], v[164:167], v[188:191], v[56:59]
	v_mfma_f32_16x16x32_bf16 v[48:51], v[156:159], v[196:199], v[48:51]
	v_mfma_f32_16x16x32_bf16 v[40:43], v[164:167], v[196:199], v[40:43]
	v_mfma_f32_16x16x32_bf16 v[32:35], v[156:159], v[204:207], v[32:35]
	v_mfma_f32_16x16x32_bf16 v[24:27], v[164:167], v[204:207], v[24:27]
	v_mfma_f32_16x16x32_bf16 v[16:19], v[156:159], v[212:215], v[16:19]
	v_mfma_f32_16x16x32_bf16 v[8:11], v[164:167], v[212:215], v[8:11]
	v_mfma_f32_16x16x32_bf16 v[52:55], v[168:171], v[184:187], v[52:55]
	v_mfma_f32_16x16x32_bf16 v[44:47], v[176:179], v[184:187], v[44:47]
	v_mfma_f32_16x16x32_bf16 v[36:39], v[168:171], v[192:195], v[36:39]
	v_mfma_f32_16x16x32_bf16 v[28:31], v[176:179], v[192:195], v[28:31]
	v_mfma_f32_16x16x32_bf16 v[20:23], v[168:171], v[200:203], v[20:23]
	v_mfma_f32_16x16x32_bf16 v[12:15], v[176:179], v[200:203], v[12:15]
	v_mfma_f32_16x16x32_bf16 v[4:7], v[168:171], v[208:211], v[4:7]
	v_mfma_f32_16x16x32_bf16 v[0:3], v[176:179], v[208:211], v[0:3]
	v_mfma_f32_16x16x32_bf16 v[52:55], v[172:175], v[188:191], v[52:55]
	v_mfma_f32_16x16x32_bf16 v[44:47], v[180:183], v[188:191], v[44:47]
	v_mfma_f32_16x16x32_bf16 v[36:39], v[172:175], v[196:199], v[36:39]
	v_mfma_f32_16x16x32_bf16 v[28:31], v[180:183], v[196:199], v[28:31]
	v_mfma_f32_16x16x32_bf16 v[20:23], v[172:175], v[204:207], v[20:23]
	v_mfma_f32_16x16x32_bf16 v[12:15], v[180:183], v[204:207], v[12:15]
	v_mfma_f32_16x16x32_bf16 v[4:7], v[172:175], v[212:215], v[4:7]
	v_mfma_f32_16x16x32_bf16 v[0:3], v[180:183], v[212:215], v[0:3]
	s_barrier
	s_setprio 0
	s_add_i32 s66, s66, 2
	s_add_u32 s46, s46, 0x100
	s_addc_u32 s47, s47, 0
	s_add_u32 s71, s71, 0x100
	s_addc_u32 s72, s72, 0
	s_cmp_gt_u32 s66, 13
	s_cbranch_scc0 .LBB0_781
	s_and_b64 vcc, exec, s[18:19]
	s_cbranch_vccz .LBB0_784
	s_barrier

; #define PG8_STAGE(bufoff, gbase, voff) do { _Pragma("unroll") for (int _i = 0; _i < 2; ++_i) \
;         __builtin_amdgcn_global_load_lds((const unsigned*)((const char*)(gbase) + (voff)[_i]), (PG8_LAS unsigned*)(lds + (bufoff) + ldsw + _i * 8192), 16, 0, 0); } while (0)
; #define PG8_LDA(dst, b, h) do { _Pragma("unroll") for (int m = 0; m < 4; ++m) _Pragma("unroll") for (int k = 0; k < 2; ++k) dst[m][k] = *(const PG8_LAS bf16x8*)(lds + PG8_SA(b, h) + aoff + m * 2048 + k * 1024); } while (0)
; #define PG8_LDB(dst, b, h) do { _Pragma("unroll") for (int n = 0; n < 2; ++n) _Pragma("unroll") for (int k = 0; k < 2; ++k) dst[n][k] = *(const PG8_LAS bf16x8*)(lds + PG8_SB(b, h) + boff + n * 2048 + k * 1024); } while (0)
; #define PG8_MMA(ai, bj, At, Bt) do { __builtin_amdgcn_s_setprio(1); _Pragma("unroll") for (int m = 0; m < 4; ++m) _Pragma("unroll") for (int n = 0; n < 2; ++n) _Pragma("unroll") for (int k = 0; k < 2; ++k) \
;         acc[ai][bj][m][n] = __builtin_amdgcn_mfma_f32_16x16x32_bf16(Bt[n][k], At[m][k], acc[ai][bj][m][n], 0, 0, 0); __builtin_amdgcn_s_setprio(0); } while (0)
; #define PG8_WAIT_V(n) asm volatile("s_waitcnt vmcnt(" #n ")" ::: "memory")
; #define PG8_WAIT_L(n) asm volatile("s_waitcnt lgkmcnt(" #n ")" ::: "memory")
; #define PG8_BAR __builtin_amdgcn_s_barrier()
; #define PG8_SCHED __builtin_amdgcn_sched_barrier(0)
; template <class Epi, class Sched, bool ALIGN_EPI = false, bool SP2 = false>
; __device__ __forceinline__ void gemm_phase(PG8_LAS unsigned char* lds, const Gemm g, const Sched& S, const Epi& E) {
;     ...
;             const bool last = (t == nt - 2);
;             const char* a1 = cA + (size_t)(t + 1) * kstep;
;             const char* a2 = last ? nA : cA + (size_t)(t + 2) * kstep; const char* b2 = last ? nB : cB + (size_t)(t + 2) * kstep;
;     ...
;             PG8_LDB(B0, 0, 0); PG8_LDB(B1, 0, 1); PG8_SCHED; PG8_LDA(At, 0, 0); PG8_STAGE(PG8_SA(1, 1), a1 + hstep, voffA);
;             PG8_WAIT_V(8); PG8_WAIT_L(0); PG8_BAR; PG8_MMA(0, 0, At, B0); PG8_MMA(0, 1, At, B1); PG8_BAR; PG8_SCHED;
;             PG8_LDA(At, 0, 1); PG8_STAGE(PG8_SB(0, 0), b2, voffB); PG8_STAGE(PG8_SB(0, 1), b2 + hstep, voffB); PG8_STAGE(PG8_SA(0, 0), a2, voffA);
;             PG8_WAIT_V(8); PG8_WAIT_L(0); PG8_BAR; PG8_MMA(1, 0, At, B0); PG8_MMA(1, 1, At, B1); PG8_BAR; PG8_SCHED;
.LBB0_801:
	ds_read_b128 v[128:131], v179
	ds_read_b128 v[132:135], v179 offset:1024
	ds_read_b128 v[136:139], v179 offset:2048
	ds_read_b128 v[140:143], v179 offset:3072
	ds_read_b128 v[144:147], v180
	ds_read_b128 v[148:151], v180 offset:1024
	ds_read_b128 v[168:171], v180 offset:2048
	ds_read_b128 v[172:175], v180 offset:3072
	s_add_u32 s48, s46, 0xfffc0080
	s_addc_u32 s49, s47, -1
	s_cmp_eq_u32 s66, 12
	s_cselect_b32 s51, s12, s49
	s_cselect_b32 s50, s13, s48
	s_cselect_b32 s49, s21, s72
	s_cselect_b32 s48, s29, s71
	v_lshl_add_u64 v[214:215], s[46:47], 0, v[160:161]
	s_add_i32 m0, s14, 0xc000
	ds_read_b128 v[182:185], v181
	ds_read_b128 v[186:189], v181 offset:1024
	ds_read_b128 v[190:193], v181 offset:2048
	ds_read_b128 v[194:197], v181 offset:3072
	ds_read_b128 v[198:201], v181 offset:4096
	ds_read_b128 v[202:205], v181 offset:5120
	ds_read_b128 v[206:209], v181 offset:6144
	ds_read_b128 v[210:213], v181 offset:7168
	global_load_lds_dwordx4 v[214:215], off
	v_lshl_add_u64 v[214:215], s[46:47], 0, v[162:163]
	s_add_i32 m0, s14, 0xe000
	s_nop 0
	global_load_lds_dwordx4 v[214:215], off
	s_waitcnt vmcnt(8)
	s_waitcnt lgkmcnt(0)
	s_setprio 1
	s_barrier
	v_mfma_f32_16x16x32_bf16 v[124:127], v[128:131], v[182:185], v[124:127]
	v_mfma_f32_16x16x32_bf16 v[120:123], v[136:139], v[182:185], v[120:123]
	v_mfma_f32_16x16x32_bf16 v[108:111], v[128:131], v[190:193], v[108:111]
	v_mfma_f32_16x16x32_bf16 v[104:107], v[136:139], v[190:193], v[104:107]
	v_mfma_f32_16x16x32_bf16 v[92:95], v[128:131], v[198:201], v[92:95]
	v_mfma_f32_16x16x32_bf16 v[88:91], v[136:139], v[198:201], v[88:91]
	v_mfma_f32_16x16x32_bf16 v[76:79], v[128:131], v[206:209], v[76:79]
	v_mfma_f32_16x16x32_bf16 v[72:75], v[136:139], v[206:209], v[72:75]
	v_mfma_f32_16x16x32_bf16 v[124:127], v[132:135], v[186:189], v[124:127]
	v_mfma_f32_16x16x32_bf16 v[120:123], v[140:143], v[186:189], v[120:123]
	v_mfma_f32_16x16x32_bf16 v[108:111], v[132:135], v[194:197], v[108:111]
	v_mfma_f32_16x16x32_bf16 v[104:107], v[140:143], v[194:197], v[104:107]
	v_mfma_f32_16x16x32_bf16 v[92:95], v[132:135], v[202:205], v[92:95]
	v_mfma_f32_16x16x32_bf16 v[88:91], v[140:143], v[202:205], v[88:91]
	v_mfma_f32_16x16x32_bf16 v[76:79], v[132:135], v[210:213], v[76:79]
	v_mfma_f32_16x16x32_bf16 v[72:75], v[140:143], v[210:213], v[72:75]
	v_mfma_f32_16x16x32_bf16 v[116:119], v[144:147], v[182:185], v[116:119]
	v_mfma_f32_16x16x32_bf16 v[112:115], v[168:171], v[182:185], v[112:115]
	v_mfma_f32_16x16x32_bf16 v[100:103], v[144:147], v[190:193], v[100:103]
	v_mfma_f32_16x16x32_bf16 v[96:99], v[168:171], v[190:193], v[96:99]
	v_mfma_f32_16x16x32_bf16 v[84:87], v[144:147], v[198:201], v[84:87]
	v_mfma_f32_16x16x32_bf16 v[80:83], v[168:171], v[198:201], v[80:83]
	v_mfma_f32_16x16x32_bf16 v[68:71], v[144:147], v[206:209], v[68:71]
	v_mfma_f32_16x16x32_bf16 v[64:67], v[168:171], v[206:209], v[64:67]
	v_mfma_f32_16x16x32_bf16 v[116:119], v[148:151], v[186:189], v[116:119]
	v_mfma_f32_16x16x32_bf16 v[112:115], v[172:175], v[186:189], v[112:115]
	v_mfma_f32_16x16x32_bf16 v[100:103], v[148:151], v[194:197], v[100:103]
	v_mfma_f32_16x16x32_bf16 v[96:99], v[172:175], v[194:197], v[96:99]
	v_mfma_f32_16x16x32_bf16 v[84:87], v[148:151], v[202:205], v[84:87]
	v_mfma_f32_16x16x32_bf16 v[80:83], v[172:175], v[202:205], v[80:83]
	v_mfma_f32_16x16x32_bf16 v[68:71], v[148:151], v[210:213], v[68:71]
	v_mfma_f32_16x16x32_bf16 v[64:67], v[172:175], v[210:213], v[64:67]
	s_barrier
	s_setprio 0
	s_add_i32 s67, s68, s3
	v_lshl_add_u64 v[214:215], s[48:49], 0, v[156:157]
	s_mov_b32 m0, s67
	ds_read_b128 v[182:185], v181 offset:16384
	ds_read_b128 v[186:189], v181 offset:17408
	ds_read_b128 v[190:193], v181 offset:18432
	ds_read_b128 v[194:197], v181 offset:19456
	ds_read_b128 v[198:201], v181 offset:20480
	ds_read_b128 v[202:205], v181 offset:21504
	ds_read_b128 v[206:209], v181 offset:22528
	ds_read_b128 v[210:213], v181 offset:23552
	global_load_lds_dwordx4 v[214:215], off
	s_add_i32 m0, s67, 0x2000
	s_add_u32 s74, s48, 0x40000
	v_lshl_add_u64 v[216:217], s[48:49], 0, v[152:153]
	s_addc_u32 s75, s49, 0
	s_add_i32 s67, s69, s3
	global_load_lds_dwordx4 v[216:217], off
	v_lshl_add_u64 v[218:219], s[74:75], 0, v[156:157]
	s_mov_b32 m0, s67
	v_lshl_add_u64 v[220:221], s[50:51], 0, v[154:155]
	global_load_lds_dwordx4 v[218:219], off
	v_lshl_add_u64 v[218:219], s[74:75], 0, v[152:153]
	s_add_i32 m0, s67, 0x2000
	s_nop 0
	global_load_lds_dwordx4 v[218:219], off
	v_lshl_add_u64 v[218:219], s[50:51], 0, v[158:159]
	s_mov_b32 m0, s14
	s_nop 0
	global_load_lds_dwordx4 v[218:219], off
	s_mov_b32 m0, s15
	s_nop 0
	global_load_lds_dwordx4 v[220:221], off
	s_waitcnt vmcnt(8)
	s_waitcnt lgkmcnt(0)
	s_setprio 1
	s_barrier
; #define PG8_STAGE(bufoff, gbase, voff) do { _Pragma("unroll") for (int _i = 0; _i < 2; ++_i) \
;         __builtin_amdgcn_global_load_lds((const unsigned*)((const char*)(gbase) + (voff)[_i]), (PG8_LAS unsigned*)(lds + (bufoff) + ldsw + _i * 8192), 16, 0, 0); } while (0)
; #define PG8_LDA(dst, b, h) do { _Pragma("unroll") for (int m = 0; m < 4; ++m) _Pragma("unroll") for (int k = 0; k < 2; ++k) dst[m][k] = *(const PG8_LAS bf16x8*)(lds + PG8_SA(b, h) + aoff + m * 2048 + k * 1024); } while (0)
; #define PG8_LDB(dst, b, h) do { _Pragma("unroll") for (int n = 0; n < 2; ++n) _Pragma("unroll") for (int k = 0; k < 2; ++k) dst[n][k] = *(const PG8_LAS bf16x8*)(lds + PG8_SB(b, h) + boff + n * 2048 + k * 1024); } while (0)
; #define PG8_MMA(ai, bj, At, Bt) do { __builtin_amdgcn_s_setprio(1); _Pragma("unroll") for (int m = 0; m < 4; ++m) _Pragma("unroll") for (int n = 0; n < 2; ++n) _Pragma("unroll") for (int k = 0; k < 2; ++k) \
;         acc[ai][bj][m][n] = __builtin_amdgcn_mfma_f32_16x16x32_bf16(Bt[n][k], At[m][k], acc[ai][bj][m][n], 0, 0, 0); __builtin_amdgcn_s_setprio(0); } while (0)
; #define PG8_WAIT_V(n) asm volatile("s_waitcnt vmcnt(" #n ")" ::: "memory")
; #define PG8_WAIT_L(n) asm volatile("s_waitcnt lgkmcnt(" #n ")" ::: "memory")
; #define PG8_BAR __builtin_amdgcn_s_barrier()
; #define PG8_SCHED __builtin_amdgcn_sched_barrier(0)
; template <class Epi, class Sched, bool ALIGN_EPI = false, bool SP2 = false>
; __device__ __forceinline__ void gemm_phase(PG8_LAS unsigned char* lds, const Gemm g, const Sched& S, const Epi& E) {
;     ...
;             PG8_WAIT_V(8); PG8_WAIT_L(0); PG8_BAR; PG8_MMA(1, 0, At, B0); PG8_MMA(1, 1, At, B1); PG8_BAR; PG8_SCHED;
;             PG8_LDB(B0, 1, 0); PG8_LDB(B1, 1, 1); PG8_SCHED; PG8_LDA(At, 1, 0); PG8_STAGE(PG8_SA(0, 1), a2 + hstep, voffA);
;             PG8_WAIT_V(8); PG8_WAIT_L(0); PG8_BAR; PG8_MMA(0, 0, At, B0); PG8_MMA(0, 1, At, B1); PG8_BAR; PG8_SCHED;
	v_mfma_f32_16x16x32_bf16 v[60:63], v[128:131], v[182:185], v[60:63]
	v_mfma_f32_16x16x32_bf16 v[56:59], v[136:139], v[182:185], v[56:59]
	v_mfma_f32_16x16x32_bf16 v[44:47], v[128:131], v[190:193], v[44:47]
	v_mfma_f32_16x16x32_bf16 v[40:43], v[136:139], v[190:193], v[40:43]
	v_mfma_f32_16x16x32_bf16 v[28:31], v[128:131], v[198:201], v[28:31]
	v_mfma_f32_16x16x32_bf16 v[24:27], v[136:139], v[198:201], v[24:27]
	v_mfma_f32_16x16x32_bf16 v[12:15], v[128:131], v[206:209], v[12:15]
	v_mfma_f32_16x16x32_bf16 v[8:11], v[136:139], v[206:209], v[8:11]
	v_mfma_f32_16x16x32_bf16 v[60:63], v[132:135], v[186:189], v[60:63]
	v_mfma_f32_16x16x32_bf16 v[56:59], v[140:143], v[186:189], v[56:59]
	v_mfma_f32_16x16x32_bf16 v[44:47], v[132:135], v[194:197], v[44:47]
	v_mfma_f32_16x16x32_bf16 v[40:43], v[140:143], v[194:197], v[40:43]
	v_mfma_f32_16x16x32_bf16 v[28:31], v[132:135], v[202:205], v[28:31]
	v_mfma_f32_16x16x32_bf16 v[24:27], v[140:143], v[202:205], v[24:27]
	v_mfma_f32_16x16x32_bf16 v[12:15], v[132:135], v[210:213], v[12:15]
	v_mfma_f32_16x16x32_bf16 v[8:11], v[140:143], v[210:213], v[8:11]
	v_mfma_f32_16x16x32_bf16 v[52:55], v[144:147], v[182:185], v[52:55]
	v_mfma_f32_16x16x32_bf16 v[48:51], v[168:171], v[182:185], v[48:51]
	v_mfma_f32_16x16x32_bf16 v[36:39], v[144:147], v[190:193], v[36:39]
	v_mfma_f32_16x16x32_bf16 v[32:35], v[168:171], v[190:193], v[32:35]
	v_mfma_f32_16x16x32_bf16 v[20:23], v[144:147], v[198:201], v[20:23]
	v_mfma_f32_16x16x32_bf16 v[16:19], v[168:171], v[198:201], v[16:19]
	v_mfma_f32_16x16x32_bf16 v[4:7], v[144:147], v[206:209], v[4:7]
	v_mfma_f32_16x16x32_bf16 v[0:3], v[168:171], v[206:209], v[0:3]
	v_mfma_f32_16x16x32_bf16 v[52:55], v[148:151], v[186:189], v[52:55]
	v_mfma_f32_16x16x32_bf16 v[48:51], v[172:175], v[186:189], v[48:51]
	v_mfma_f32_16x16x32_bf16 v[36:39], v[148:151], v[194:197], v[36:39]
	v_mfma_f32_16x16x32_bf16 v[32:35], v[172:175], v[194:197], v[32:35]
	v_mfma_f32_16x16x32_bf16 v[20:23], v[148:151], v[202:205], v[20:23]
	v_mfma_f32_16x16x32_bf16 v[16:19], v[172:175], v[202:205], v[16:19]
	v_mfma_f32_16x16x32_bf16 v[4:7], v[148:151], v[210:213], v[4:7]
	v_mfma_f32_16x16x32_bf16 v[0:3], v[172:175], v[210:213], v[0:3]
	s_barrier
	s_setprio 0
	s_add_i32 s67, 0, 0x18000
	s_add_i32 s74, 0, 0x1c000
	v_add_u32_e32 v140, s67, v177
	v_add_u32_e32 v172, s74, v177
	ds_read_b128 v[128:131], v140
	ds_read_b128 v[132:135], v140 offset:1024
	ds_read_b128 v[136:139], v140 offset:2048
	ds_read_b128 v[140:143], v140 offset:3072
	ds_read_b128 v[144:147], v172
	ds_read_b128 v[148:151], v172 offset:1024
	ds_read_b128 v[168:171], v172 offset:2048
	ds_read_b128 v[172:175], v172 offset:3072
	s_add_u32 s50, s50, 0x40000
	s_addc_u32 s51, s51, 0
	s_mov_b32 m0, s22
	v_lshl_add_u64 v[226:227], s[50:51], 0, v[158:159]
	ds_read_b128 v[182:185], v181 offset:32768
	ds_read_b128 v[186:189], v181 offset:33792
	ds_read_b128 v[190:193], v181 offset:34816
	ds_read_b128 v[194:197], v181 offset:35840
	ds_read_b128 v[198:201], v181 offset:36864
	ds_read_b128 v[202:205], v181 offset:37888
	ds_read_b128 v[206:209], v181 offset:38912
	ds_read_b128 v[210:213], v181 offset:39936
	global_load_lds_dwordx4 v[226:227], off
	v_lshl_add_u64 v[226:227], s[50:51], 0, v[154:155]
	s_mov_b32 m0, s23
	s_nop 0
	global_load_lds_dwordx4 v[226:227], off
	s_waitcnt vmcnt(8)
	s_waitcnt lgkmcnt(0)
	s_setprio 1
	s_barrier
	v_mfma_f32_16x16x32_bf16 v[124:127], v[128:131], v[182:185], v[124:127]
	v_mfma_f32_16x16x32_bf16 v[120:123], v[136:139], v[182:185], v[120:123]
	v_mfma_f32_16x16x32_bf16 v[108:111], v[128:131], v[190:193], v[108:111]
	v_mfma_f32_16x16x32_bf16 v[104:107], v[136:139], v[190:193], v[104:107]
	v_mfma_f32_16x16x32_bf16 v[92:95], v[128:131], v[198:201], v[92:95]
	v_mfma_f32_16x16x32_bf16 v[88:91], v[136:139], v[198:201], v[88:91]
	v_mfma_f32_16x16x32_bf16 v[76:79], v[128:131], v[206:209], v[76:79]
	v_mfma_f32_16x16x32_bf16 v[72:75], v[136:139], v[206:209], v[72:75]
	v_mfma_f32_16x16x32_bf16 v[124:127], v[132:135], v[186:189], v[124:127]
	v_mfma_f32_16x16x32_bf16 v[120:123], v[140:143], v[186:189], v[120:123]
	v_mfma_f32_16x16x32_bf16 v[108:111], v[132:135], v[194:197], v[108:111]
	v_mfma_f32_16x16x32_bf16 v[104:107], v[140:143], v[194:197], v[104:107]
	v_mfma_f32_16x16x32_bf16 v[92:95], v[132:135], v[202:205], v[92:95]
	v_mfma_f32_16x16x32_bf16 v[88:91], v[140:143], v[202:205], v[88:91]
	v_mfma_f32_16x16x32_bf16 v[76:79], v[132:135], v[210:213], v[76:79]
	v_mfma_f32_16x16x32_bf16 v[72:75], v[140:143], v[210:213], v[72:75]
	v_mfma_f32_16x16x32_bf16 v[116:119], v[144:147], v[182:185], v[116:119]
	v_mfma_f32_16x16x32_bf16 v[112:115], v[168:171], v[182:185], v[112:115]
	v_mfma_f32_16x16x32_bf16 v[100:103], v[144:147], v[190:193], v[100:103]
	v_mfma_f32_16x16x32_bf16 v[96:99], v[168:171], v[190:193], v[96:99]
	v_mfma_f32_16x16x32_bf16 v[84:87], v[144:147], v[198:201], v[84:87]
	v_mfma_f32_16x16x32_bf16 v[80:83], v[168:171], v[198:201], v[80:83]
	v_mfma_f32_16x16x32_bf16 v[68:71], v[144:147], v[206:209], v[68:71]
	v_mfma_f32_16x16x32_bf16 v[64:67], v[168:171], v[206:209], v[64:67]
	v_mfma_f32_16x16x32_bf16 v[116:119], v[148:151], v[186:189], v[116:119]
	v_mfma_f32_16x16x32_bf16 v[112:115], v[172:175], v[186:189], v[112:115]
	v_mfma_f32_16x16x32_bf16 v[100:103], v[148:151], v[194:197], v[100:103]
	v_mfma_f32_16x16x32_bf16 v[96:99], v[172:175], v[194:197], v[96:99]
	v_mfma_f32_16x16x32_bf16 v[84:87], v[148:151], v[202:205], v[84:87]
	v_mfma_f32_16x16x32_bf16 v[80:83], v[172:175], v[202:205], v[80:83]
	v_mfma_f32_16x16x32_bf16 v[68:71], v[148:151], v[210:213], v[68:71]
	v_mfma_f32_16x16x32_bf16 v[64:67], v[172:175], v[210:213], v[64:67]
	s_barrier
; #define PG8_STAGE(bufoff, gbase, voff) do { _Pragma("unroll") for (int _i = 0; _i < 2; ++_i) \
;         __builtin_amdgcn_global_load_lds((const unsigned*)((const char*)(gbase) + (voff)[_i]), (PG8_LAS unsigned*)(lds + (bufoff) + ldsw + _i * 8192), 16, 0, 0); } while (0)
; #define PG8_LDA(dst, b, h) do { _Pragma("unroll") for (int m = 0; m < 4; ++m) _Pragma("unroll") for (int k = 0; k < 2; ++k) dst[m][k] = *(const PG8_LAS bf16x8*)(lds + PG8_SA(b, h) + aoff + m * 2048 + k * 1024); } while (0)
; #define PG8_MMA(ai, bj, At, Bt) do { __builtin_amdgcn_s_setprio(1); _Pragma("unroll") for (int m = 0; m < 4; ++m) _Pragma("unroll") for (int n = 0; n < 2; ++n) _Pragma("unroll") for (int k = 0; k < 2; ++k) \
;         acc[ai][bj][m][n] = __builtin_amdgcn_mfma_f32_16x16x32_bf16(Bt[n][k], At[m][k], acc[ai][bj][m][n], 0, 0, 0); __builtin_amdgcn_s_setprio(0); } while (0)
; #define PG8_WAIT_V(n) asm volatile("s_waitcnt vmcnt(" #n ")" ::: "memory")
; #define PG8_WAIT_L(n) asm volatile("s_waitcnt lgkmcnt(" #n ")" ::: "memory")
; #define PG8_BAR __builtin_amdgcn_s_barrier()
; #define PG8_SCHED __builtin_amdgcn_sched_barrier(0)
; template <class Epi, class Sched, bool ALIGN_EPI = false, bool SP2 = false>
; __device__ __forceinline__ void gemm_phase(PG8_LAS unsigned char* lds, const Gemm g, const Sched& S, const Epi& E) {
;     ...
;             PG8_LDA(At, 1, 1); PG8_STAGE(PG8_SB(1, 0), b3, voffB); PG8_STAGE(PG8_SB(1, 1), b3 + hstep, voffB); PG8_STAGE(PG8_SA(1, 0), a3, voffA);
;             PG8_WAIT_V(8); PG8_WAIT_L(0); PG8_BAR; PG8_MMA(1, 0, At, B0); PG8_MMA(1, 1, At, B1); PG8_BAR; PG8_SCHED;
;     ...
;         }
;         if constexpr (ALIGN_EPI) { if (wr == 0) PG8_BAR; }
	s_setprio 0
	s_add_i32 s50, s67, s3
	v_lshl_add_u64 v[214:215], v[214:215], 0, s[16:17]
	s_mov_b32 m0, s50
	ds_read_b128 v[182:185], v181 offset:49152
	ds_read_b128 v[186:189], v181 offset:50176
	ds_read_b128 v[190:193], v181 offset:51200
	ds_read_b128 v[194:197], v181 offset:52224
	ds_read_b128 v[198:201], v181 offset:53248
	ds_read_b128 v[202:205], v181 offset:54272
	ds_read_b128 v[206:209], v181 offset:55296
	ds_read_b128 v[210:213], v181 offset:56320
	global_load_lds_dwordx4 v[214:215], off
	s_add_i32 m0, s50, 0x2000
	s_add_u32 s48, s48, 0x40080
	v_lshl_add_u64 v[214:215], v[216:217], 0, s[16:17]
	s_addc_u32 s49, s49, 0
	s_add_i32 s50, s74, s3
	global_load_lds_dwordx4 v[214:215], off
	v_lshl_add_u64 v[214:215], s[48:49], 0, v[156:157]
	s_mov_b32 m0, s50
	s_nop 0
	global_load_lds_dwordx4 v[214:215], off
	v_lshl_add_u64 v[214:215], s[48:49], 0, v[152:153]
	s_add_i32 m0, s50, 0x2000
	s_nop 0
	global_load_lds_dwordx4 v[214:215], off
	v_lshl_add_u64 v[214:215], v[218:219], 0, s[16:17]
	s_mov_b32 m0, s35
	s_nop 0
	global_load_lds_dwordx4 v[214:215], off
	v_lshl_add_u64 v[214:215], v[220:221], 0, s[16:17]
	s_mov_b32 m0, s45
	s_nop 0
	global_load_lds_dwordx4 v[214:215], off
	s_waitcnt vmcnt(8)
	s_waitcnt lgkmcnt(0)
	s_setprio 1
	s_barrier
	v_mfma_f32_16x16x32_bf16 v[60:63], v[128:131], v[182:185], v[60:63]
	v_mfma_f32_16x16x32_bf16 v[56:59], v[136:139], v[182:185], v[56:59]
	v_mfma_f32_16x16x32_bf16 v[44:47], v[128:131], v[190:193], v[44:47]
	v_mfma_f32_16x16x32_bf16 v[40:43], v[136:139], v[190:193], v[40:43]
	v_mfma_f32_16x16x32_bf16 v[28:31], v[128:131], v[198:201], v[28:31]
	v_mfma_f32_16x16x32_bf16 v[24:27], v[136:139], v[198:201], v[24:27]
	v_mfma_f32_16x16x32_bf16 v[12:15], v[128:131], v[206:209], v[12:15]
	v_mfma_f32_16x16x32_bf16 v[8:11], v[136:139], v[206:209], v[8:11]
	v_mfma_f32_16x16x32_bf16 v[60:63], v[132:135], v[186:189], v[60:63]
	v_mfma_f32_16x16x32_bf16 v[56:59], v[140:143], v[186:189], v[56:59]
	v_mfma_f32_16x16x32_bf16 v[44:47], v[132:135], v[194:197], v[44:47]
	v_mfma_f32_16x16x32_bf16 v[40:43], v[140:143], v[194:197], v[40:43]
	v_mfma_f32_16x16x32_bf16 v[28:31], v[132:135], v[202:205], v[28:31]
	v_mfma_f32_16x16x32_bf16 v[24:27], v[140:143], v[202:205], v[24:27]
	v_mfma_f32_16x16x32_bf16 v[12:15], v[132:135], v[210:213], v[12:15]
	v_mfma_f32_16x16x32_bf16 v[8:11], v[140:143], v[210:213], v[8:11]
	v_mfma_f32_16x16x32_bf16 v[52:55], v[144:147], v[182:185], v[52:55]
	v_mfma_f32_16x16x32_bf16 v[48:51], v[168:171], v[182:185], v[48:51]
	v_mfma_f32_16x16x32_bf16 v[36:39], v[144:147], v[190:193], v[36:39]
	v_mfma_f32_16x16x32_bf16 v[32:35], v[168:171], v[190:193], v[32:35]
	v_mfma_f32_16x16x32_bf16 v[20:23], v[144:147], v[198:201], v[20:23]
	v_mfma_f32_16x16x32_bf16 v[16:19], v[168:171], v[198:201], v[16:19]
	v_mfma_f32_16x16x32_bf16 v[4:7], v[144:147], v[206:209], v[4:7]
	v_mfma_f32_16x16x32_bf16 v[0:3], v[168:171], v[206:209], v[0:3]
	v_mfma_f32_16x16x32_bf16 v[52:55], v[148:151], v[186:189], v[52:55]
	v_mfma_f32_16x16x32_bf16 v[48:51], v[172:175], v[186:189], v[48:51]
	v_mfma_f32_16x16x32_bf16 v[36:39], v[148:151], v[194:197], v[36:39]
	v_mfma_f32_16x16x32_bf16 v[32:35], v[172:175], v[194:197], v[32:35]
	v_mfma_f32_16x16x32_bf16 v[20:23], v[148:151], v[202:205], v[20:23]
	v_mfma_f32_16x16x32_bf16 v[16:19], v[172:175], v[202:205], v[16:19]
	v_mfma_f32_16x16x32_bf16 v[4:7], v[148:151], v[210:213], v[4:7]
	v_mfma_f32_16x16x32_bf16 v[0:3], v[172:175], v[210:213], v[0:3]
	s_barrier
	s_setprio 0
	s_add_i32 s66, s66, 2
	s_add_u32 s46, s46, 0x100
	s_addc_u32 s47, s47, 0
	s_add_u32 s71, s71, 0x100
	s_addc_u32 s72, s72, 0
	s_cmp_gt_u32 s66, 13
	s_cbranch_scc0 .LBB0_801
	s_and_b64 vcc, exec, s[18:19]
	s_cbranch_vccz .LBB0_804
	s_barrier

; #define PG8_STAGE(bufoff, gbase, voff) do { _Pragma("unroll") for (int _i = 0; _i < 2; ++_i) \
;         __builtin_amdgcn_global_load_lds((const unsigned*)((const char*)(gbase) + (voff)[_i]), (PG8_LAS unsigned*)(lds + (bufoff) + ldsw + _i * 8192), 16, 0, 0); } while (0)
; #define PG8_LDA(dst, b, h) do { _Pragma("unroll") for (int m = 0; m < 4; ++m) _Pragma("unroll") for (int k = 0; k < 2; ++k) dst[m][k] = *(const PG8_LAS bf16x8*)(lds + PG8_SA(b, h) + aoff + m * 2048 + k * 1024); } while (0)
; #define PG8_LDB(dst, b, h) do { _Pragma("unroll") for (int n = 0; n < 2; ++n) _Pragma("unroll") for (int k = 0; k < 2; ++k) dst[n][k] = *(const PG8_LAS bf16x8*)(lds + PG8_SB(b, h) + boff + n * 2048 + k * 1024); } while (0)
; #define PG8_MMA(ai, bj, At, Bt) do { __builtin_amdgcn_s_setprio(1); _Pragma("unroll") for (int m = 0; m < 4; ++m) _Pragma("unroll") for (int n = 0; n < 2; ++n) _Pragma("unroll") for (int k = 0; k < 2; ++k) \
;         acc[ai][bj][m][n] = __builtin_amdgcn_mfma_f32_16x16x32_bf16(Bt[n][k], At[m][k], acc[ai][bj][m][n], 0, 0, 0); __builtin_amdgcn_s_setprio(0); } while (0)
; #define PG8_WAIT_V(n) asm volatile("s_waitcnt vmcnt(" #n ")" ::: "memory")
; #define PG8_WAIT_L(n) asm volatile("s_waitcnt lgkmcnt(" #n ")" ::: "memory")
; #define PG8_BAR __builtin_amdgcn_s_barrier()
; #define PG8_SCHED __builtin_amdgcn_sched_barrier(0)
; template <class Epi, class Sched, bool ALIGN_EPI = false, bool SP2 = false>
; __device__ __forceinline__ void gemm_phase(PG8_LAS unsigned char* lds, const Gemm g, const Sched& S, const Epi& E) {
;     ...
;             const bool last = (t == nt - 2);
;             const char* a1 = cA + (size_t)(t + 1) * kstep;
;             const char* a2 = last ? nA : cA + (size_t)(t + 2) * kstep; const char* b2 = last ? nB : cB + (size_t)(t + 2) * kstep;
;     ...
;             PG8_LDB(B0, 0, 0); PG8_LDB(B1, 0, 1); PG8_SCHED; PG8_LDA(At, 0, 0); PG8_STAGE(PG8_SA(1, 1), a1 + hstep, voffA);
;             PG8_WAIT_V(8); PG8_WAIT_L(0); PG8_BAR; PG8_MMA(0, 0, At, B0); PG8_MMA(0, 1, At, B1); PG8_BAR; PG8_SCHED;
;             PG8_LDA(At, 0, 1); PG8_STAGE(PG8_SB(0, 0), b2, voffB); PG8_STAGE(PG8_SB(0, 1), b2 + hstep, voffB); PG8_STAGE(PG8_SA(0, 0), a2, voffA);
;             PG8_WAIT_V(8); PG8_WAIT_L(0); PG8_BAR; PG8_MMA(1, 0, At, B0); PG8_MMA(1, 1, At, B1); PG8_BAR; PG8_SCHED;
.LBB0_876:
	ds_read_b128 v[128:131], v228
	ds_read_b128 v[132:135], v228 offset:1024
	ds_read_b128 v[136:139], v228 offset:2048
	ds_read_b128 v[140:143], v228 offset:3072
	ds_read_b128 v[144:147], v229
	ds_read_b128 v[148:151], v229 offset:1024
	ds_read_b128 v[152:155], v229 offset:2048
	ds_read_b128 v[156:159], v229 offset:3072
	s_add_u32 s48, s46, 0x100
	s_addc_u32 s49, s47, 0
	s_cmp_eq_u32 s66, 28
	s_cselect_b32 s75, s11, s49
	s_cselect_b32 s74, s12, s48
	s_cselect_b32 s51, s13, s72
	s_cselect_b32 s50, s29, s31
	v_lshl_add_u64 v[204:205], s[46:47], 0, v[192:193]
	s_add_i32 m0, s14, 0xc000
	ds_read_b128 v[160:163], v230
	ds_read_b128 v[164:167], v230 offset:1024
	ds_read_b128 v[168:171], v230 offset:2048
	ds_read_b128 v[172:175], v230 offset:3072
	ds_read_b128 v[176:179], v230 offset:4096
	ds_read_b128 v[180:183], v230 offset:5120
	ds_read_b128 v[184:187], v230 offset:6144
	ds_read_b128 v[200:203], v230 offset:7168
	global_load_lds_dwordx4 v[204:205], off
	v_lshl_add_u64 v[204:205], s[46:47], 0, v[194:195]
	s_add_i32 m0, s14, 0xe000
	s_nop 0
	global_load_lds_dwordx4 v[204:205], off
	s_waitcnt vmcnt(8)
	s_waitcnt lgkmcnt(0)
	s_setprio 1
	s_barrier
	v_mfma_f32_16x16x32_bf16 v[124:127], v[128:131], v[160:163], v[124:127]
	v_mfma_f32_16x16x32_bf16 v[120:123], v[136:139], v[160:163], v[120:123]
	v_mfma_f32_16x16x32_bf16 v[108:111], v[128:131], v[168:171], v[108:111]
	v_mfma_f32_16x16x32_bf16 v[104:107], v[136:139], v[168:171], v[104:107]
	v_mfma_f32_16x16x32_bf16 v[92:95], v[128:131], v[176:179], v[92:95]
	v_mfma_f32_16x16x32_bf16 v[88:91], v[136:139], v[176:179], v[88:91]
	v_mfma_f32_16x16x32_bf16 v[76:79], v[128:131], v[184:187], v[76:79]
	v_mfma_f32_16x16x32_bf16 v[72:75], v[136:139], v[184:187], v[72:75]
	v_mfma_f32_16x16x32_bf16 v[124:127], v[132:135], v[164:167], v[124:127]
	v_mfma_f32_16x16x32_bf16 v[120:123], v[140:143], v[164:167], v[120:123]
	v_mfma_f32_16x16x32_bf16 v[108:111], v[132:135], v[172:175], v[108:111]
	v_mfma_f32_16x16x32_bf16 v[104:107], v[140:143], v[172:175], v[104:107]
	v_mfma_f32_16x16x32_bf16 v[92:95], v[132:135], v[180:183], v[92:95]
	v_mfma_f32_16x16x32_bf16 v[88:91], v[140:143], v[180:183], v[88:91]
	v_mfma_f32_16x16x32_bf16 v[76:79], v[132:135], v[200:203], v[76:79]
	v_mfma_f32_16x16x32_bf16 v[72:75], v[140:143], v[200:203], v[72:75]
	v_mfma_f32_16x16x32_bf16 v[116:119], v[144:147], v[160:163], v[116:119]
	v_mfma_f32_16x16x32_bf16 v[112:115], v[152:155], v[160:163], v[112:115]
	v_mfma_f32_16x16x32_bf16 v[100:103], v[144:147], v[168:171], v[100:103]
	v_mfma_f32_16x16x32_bf16 v[96:99], v[152:155], v[168:171], v[96:99]
	v_mfma_f32_16x16x32_bf16 v[84:87], v[144:147], v[176:179], v[84:87]
	v_mfma_f32_16x16x32_bf16 v[80:83], v[152:155], v[176:179], v[80:83]
	v_mfma_f32_16x16x32_bf16 v[68:71], v[144:147], v[184:187], v[68:71]
	v_mfma_f32_16x16x32_bf16 v[64:67], v[152:155], v[184:187], v[64:67]
	v_mfma_f32_16x16x32_bf16 v[116:119], v[148:151], v[164:167], v[116:119]
	v_mfma_f32_16x16x32_bf16 v[112:115], v[156:159], v[164:167], v[112:115]
	v_mfma_f32_16x16x32_bf16 v[100:103], v[148:151], v[172:175], v[100:103]
	v_mfma_f32_16x16x32_bf16 v[96:99], v[156:159], v[172:175], v[96:99]
	v_mfma_f32_16x16x32_bf16 v[84:87], v[148:151], v[180:183], v[84:87]
	v_mfma_f32_16x16x32_bf16 v[80:83], v[156:159], v[180:183], v[80:83]
	v_mfma_f32_16x16x32_bf16 v[68:71], v[148:151], v[200:203], v[68:71]
	v_mfma_f32_16x16x32_bf16 v[64:67], v[156:159], v[200:203], v[64:67]
	s_barrier
	s_setprio 0
	s_add_i32 s46, s69, s3
	v_lshl_add_u64 v[204:205], s[50:51], 0, v[188:189]
	s_mov_b32 m0, s46
	ds_read_b128 v[160:163], v230 offset:16384
	ds_read_b128 v[164:167], v230 offset:17408
	ds_read_b128 v[168:171], v230 offset:18432
	ds_read_b128 v[172:175], v230 offset:19456
	ds_read_b128 v[176:179], v230 offset:20480
	ds_read_b128 v[180:183], v230 offset:21504
	ds_read_b128 v[184:187], v230 offset:22528
	ds_read_b128 v[200:203], v230 offset:23552
	global_load_lds_dwordx4 v[204:205], off
	s_add_i32 m0, s46, 0x2000
	s_add_u32 s46, s50, 0x80000
	v_lshl_add_u64 v[206:207], s[50:51], 0, v[190:191]
	s_addc_u32 s47, s51, 0
	s_add_i32 s67, s70, s3
	global_load_lds_dwordx4 v[206:207], off
	v_lshl_add_u64 v[208:209], s[46:47], 0, v[188:189]
	s_mov_b32 m0, s67
	v_lshl_add_u64 v[210:211], s[74:75], 0, v[190:191]
	global_load_lds_dwordx4 v[208:209], off
	v_lshl_add_u64 v[208:209], s[46:47], 0, v[190:191]
	s_add_i32 m0, s67, 0x2000
	s_nop 0
	global_load_lds_dwordx4 v[208:209], off
	v_lshl_add_u64 v[208:209], s[74:75], 0, v[188:189]
	s_mov_b32 m0, s14
	s_nop 0
	global_load_lds_dwordx4 v[208:209], off
	s_mov_b32 m0, s15
	s_nop 0
	global_load_lds_dwordx4 v[210:211], off
	s_waitcnt vmcnt(8)
	s_waitcnt lgkmcnt(0)
	s_setprio 1
	s_barrier
; #define PG8_STAGE(bufoff, gbase, voff) do { _Pragma("unroll") for (int _i = 0; _i < 2; ++_i) \
;         __builtin_amdgcn_global_load_lds((const unsigned*)((const char*)(gbase) + (voff)[_i]), (PG8_LAS unsigned*)(lds + (bufoff) + ldsw + _i * 8192), 16, 0, 0); } while (0)
; #define PG8_LDA(dst, b, h) do { _Pragma("unroll") for (int m = 0; m < 4; ++m) _Pragma("unroll") for (int k = 0; k < 2; ++k) dst[m][k] = *(const PG8_LAS bf16x8*)(lds + PG8_SA(b, h) + aoff + m * 2048 + k * 1024); } while (0)
; #define PG8_LDB(dst, b, h) do { _Pragma("unroll") for (int n = 0; n < 2; ++n) _Pragma("unroll") for (int k = 0; k < 2; ++k) dst[n][k] = *(const PG8_LAS bf16x8*)(lds + PG8_SB(b, h) + boff + n * 2048 + k * 1024); } while (0)
; #define PG8_MMA(ai, bj, At, Bt) do { __builtin_amdgcn_s_setprio(1); _Pragma("unroll") for (int m = 0; m < 4; ++m) _Pragma("unroll") for (int n = 0; n < 2; ++n) _Pragma("unroll") for (int k = 0; k < 2; ++k) \
;         acc[ai][bj][m][n] = __builtin_amdgcn_mfma_f32_16x16x32_bf16(Bt[n][k], At[m][k], acc[ai][bj][m][n], 0, 0, 0); __builtin_amdgcn_s_setprio(0); } while (0)
; #define PG8_WAIT_V(n) asm volatile("s_waitcnt vmcnt(" #n ")" ::: "memory")
; #define PG8_WAIT_L(n) asm volatile("s_waitcnt lgkmcnt(" #n ")" ::: "memory")
; #define PG8_BAR __builtin_amdgcn_s_barrier()
; #define PG8_SCHED __builtin_amdgcn_sched_barrier(0)
; template <class Epi, class Sched, bool ALIGN_EPI = false, bool SP2 = false>
; __device__ __forceinline__ void gemm_phase(PG8_LAS unsigned char* lds, const Gemm g, const Sched& S, const Epi& E) {
;     ...
;             PG8_WAIT_V(8); PG8_WAIT_L(0); PG8_BAR; PG8_MMA(1, 0, At, B0); PG8_MMA(1, 1, At, B1); PG8_BAR; PG8_SCHED;
;             PG8_LDB(B0, 1, 0); PG8_LDB(B1, 1, 1); PG8_SCHED; PG8_LDA(At, 1, 0); PG8_STAGE(PG8_SA(0, 1), a2 + hstep, voffA);
;             PG8_WAIT_V(8); PG8_WAIT_L(0); PG8_BAR; PG8_MMA(0, 0, At, B0); PG8_MMA(0, 1, At, B1); PG8_BAR; PG8_SCHED;
	v_mfma_f32_16x16x32_bf16 v[60:63], v[128:131], v[160:163], v[60:63]
	v_mfma_f32_16x16x32_bf16 v[56:59], v[136:139], v[160:163], v[56:59]
	v_mfma_f32_16x16x32_bf16 v[44:47], v[128:131], v[168:171], v[44:47]
	v_mfma_f32_16x16x32_bf16 v[40:43], v[136:139], v[168:171], v[40:43]
	v_mfma_f32_16x16x32_bf16 v[28:31], v[128:131], v[176:179], v[28:31]
	v_mfma_f32_16x16x32_bf16 v[24:27], v[136:139], v[176:179], v[24:27]
	v_mfma_f32_16x16x32_bf16 v[12:15], v[128:131], v[184:187], v[12:15]
	v_mfma_f32_16x16x32_bf16 v[8:11], v[136:139], v[184:187], v[8:11]
	v_mfma_f32_16x16x32_bf16 v[60:63], v[132:135], v[164:167], v[60:63]
	v_mfma_f32_16x16x32_bf16 v[56:59], v[140:143], v[164:167], v[56:59]
	v_mfma_f32_16x16x32_bf16 v[44:47], v[132:135], v[172:175], v[44:47]
	v_mfma_f32_16x16x32_bf16 v[40:43], v[140:143], v[172:175], v[40:43]
	v_mfma_f32_16x16x32_bf16 v[28:31], v[132:135], v[180:183], v[28:31]
	v_mfma_f32_16x16x32_bf16 v[24:27], v[140:143], v[180:183], v[24:27]
	v_mfma_f32_16x16x32_bf16 v[12:15], v[132:135], v[200:203], v[12:15]
	v_mfma_f32_16x16x32_bf16 v[8:11], v[140:143], v[200:203], v[8:11]
	v_mfma_f32_16x16x32_bf16 v[52:55], v[144:147], v[160:163], v[52:55]
	v_mfma_f32_16x16x32_bf16 v[48:51], v[152:155], v[160:163], v[48:51]
	v_mfma_f32_16x16x32_bf16 v[36:39], v[144:147], v[168:171], v[36:39]
	v_mfma_f32_16x16x32_bf16 v[32:35], v[152:155], v[168:171], v[32:35]
	v_mfma_f32_16x16x32_bf16 v[20:23], v[144:147], v[176:179], v[20:23]
	v_mfma_f32_16x16x32_bf16 v[16:19], v[152:155], v[176:179], v[16:19]
	v_mfma_f32_16x16x32_bf16 v[4:7], v[144:147], v[184:187], v[4:7]
	v_mfma_f32_16x16x32_bf16 v[0:3], v[152:155], v[184:187], v[0:3]
	v_mfma_f32_16x16x32_bf16 v[52:55], v[148:151], v[164:167], v[52:55]
	v_mfma_f32_16x16x32_bf16 v[48:51], v[156:159], v[164:167], v[48:51]
	v_mfma_f32_16x16x32_bf16 v[36:39], v[148:151], v[172:175], v[36:39]
	v_mfma_f32_16x16x32_bf16 v[32:35], v[156:159], v[172:175], v[32:35]
	v_mfma_f32_16x16x32_bf16 v[20:23], v[148:151], v[180:183], v[20:23]
	v_mfma_f32_16x16x32_bf16 v[16:19], v[156:159], v[180:183], v[16:19]
	v_mfma_f32_16x16x32_bf16 v[4:7], v[148:151], v[200:203], v[4:7]
	v_mfma_f32_16x16x32_bf16 v[0:3], v[156:159], v[200:203], v[0:3]
	s_barrier
	s_setprio 0
	s_add_i32 s67, 0, 0x18000
	s_add_i32 s76, 0, 0x1c000
	v_add_u32_e32 v140, s67, v226
	v_add_u32_e32 v156, s76, v226
	ds_read_b128 v[128:131], v140
	ds_read_b128 v[132:135], v140 offset:1024
	ds_read_b128 v[136:139], v140 offset:2048
	ds_read_b128 v[140:143], v140 offset:3072
	ds_read_b128 v[144:147], v156
	ds_read_b128 v[148:151], v156 offset:1024
	ds_read_b128 v[152:155], v156 offset:2048
	ds_read_b128 v[156:159], v156 offset:3072
	s_add_u32 s46, s74, 0x80000
	s_addc_u32 s47, s75, 0
	s_mov_b32 m0, s22
	v_lshl_add_u64 v[212:213], s[46:47], 0, v[188:189]
	ds_read_b128 v[160:163], v230 offset:32768
	ds_read_b128 v[164:167], v230 offset:33792
	ds_read_b128 v[168:171], v230 offset:34816
	ds_read_b128 v[172:175], v230 offset:35840
	ds_read_b128 v[176:179], v230 offset:36864
	ds_read_b128 v[180:183], v230 offset:37888
	ds_read_b128 v[184:187], v230 offset:38912
	ds_read_b128 v[200:203], v230 offset:39936
	global_load_lds_dwordx4 v[212:213], off
	v_lshl_add_u64 v[212:213], s[46:47], 0, v[190:191]
	s_mov_b32 m0, s23
	s_nop 0
	global_load_lds_dwordx4 v[212:213], off
	s_waitcnt vmcnt(8)
	s_waitcnt lgkmcnt(0)
	s_setprio 1
	s_barrier
	v_mfma_f32_16x16x32_bf16 v[124:127], v[128:131], v[160:163], v[124:127]
	v_mfma_f32_16x16x32_bf16 v[120:123], v[136:139], v[160:163], v[120:123]
	v_mfma_f32_16x16x32_bf16 v[108:111], v[128:131], v[168:171], v[108:111]
	v_mfma_f32_16x16x32_bf16 v[104:107], v[136:139], v[168:171], v[104:107]
	v_mfma_f32_16x16x32_bf16 v[92:95], v[128:131], v[176:179], v[92:95]
	v_mfma_f32_16x16x32_bf16 v[88:91], v[136:139], v[176:179], v[88:91]
	v_mfma_f32_16x16x32_bf16 v[76:79], v[128:131], v[184:187], v[76:79]
	v_mfma_f32_16x16x32_bf16 v[72:75], v[136:139], v[184:187], v[72:75]
	v_mfma_f32_16x16x32_bf16 v[124:127], v[132:135], v[164:167], v[124:127]
	v_mfma_f32_16x16x32_bf16 v[120:123], v[140:143], v[164:167], v[120:123]
	v_mfma_f32_16x16x32_bf16 v[108:111], v[132:135], v[172:175], v[108:111]
	v_mfma_f32_16x16x32_bf16 v[104:107], v[140:143], v[172:175], v[104:107]
	v_mfma_f32_16x16x32_bf16 v[92:95], v[132:135], v[180:183], v[92:95]
	v_mfma_f32_16x16x32_bf16 v[88:91], v[140:143], v[180:183], v[88:91]
	v_mfma_f32_16x16x32_bf16 v[76:79], v[132:135], v[200:203], v[76:79]
	v_mfma_f32_16x16x32_bf16 v[72:75], v[140:143], v[200:203], v[72:75]
	v_mfma_f32_16x16x32_bf16 v[116:119], v[144:147], v[160:163], v[116:119]
	v_mfma_f32_16x16x32_bf16 v[112:115], v[152:155], v[160:163], v[112:115]
	v_mfma_f32_16x16x32_bf16 v[100:103], v[144:147], v[168:171], v[100:103]
	v_mfma_f32_16x16x32_bf16 v[96:99], v[152:155], v[168:171], v[96:99]
	v_mfma_f32_16x16x32_bf16 v[84:87], v[144:147], v[176:179], v[84:87]
	v_mfma_f32_16x16x32_bf16 v[80:83], v[152:155], v[176:179], v[80:83]
	v_mfma_f32_16x16x32_bf16 v[68:71], v[144:147], v[184:187], v[68:71]
	v_mfma_f32_16x16x32_bf16 v[64:67], v[152:155], v[184:187], v[64:67]
	v_mfma_f32_16x16x32_bf16 v[116:119], v[148:151], v[164:167], v[116:119]
	v_mfma_f32_16x16x32_bf16 v[112:115], v[156:159], v[164:167], v[112:115]
	v_mfma_f32_16x16x32_bf16 v[100:103], v[148:151], v[172:175], v[100:103]
	v_mfma_f32_16x16x32_bf16 v[96:99], v[156:159], v[172:175], v[96:99]
	v_mfma_f32_16x16x32_bf16 v[84:87], v[148:151], v[180:183], v[84:87]
	v_mfma_f32_16x16x32_bf16 v[80:83], v[156:159], v[180:183], v[80:83]
	v_mfma_f32_16x16x32_bf16 v[68:71], v[148:151], v[200:203], v[68:71]
	v_mfma_f32_16x16x32_bf16 v[64:67], v[156:159], v[200:203], v[64:67]
	s_barrier
; #define PG8_STAGE(bufoff, gbase, voff) do { _Pragma("unroll") for (int _i = 0; _i < 2; ++_i) \
;         __builtin_amdgcn_global_load_lds((const unsigned*)((const char*)(gbase) + (voff)[_i]), (PG8_LAS unsigned*)(lds + (bufoff) + ldsw + _i * 8192), 16, 0, 0); } while (0)
; #define PG8_LDA(dst, b, h) do { _Pragma("unroll") for (int m = 0; m < 4; ++m) _Pragma("unroll") for (int k = 0; k < 2; ++k) dst[m][k] = *(const PG8_LAS bf16x8*)(lds + PG8_SA(b, h) + aoff + m * 2048 + k * 1024); } while (0)
; #define PG8_MMA(ai, bj, At, Bt) do { __builtin_amdgcn_s_setprio(1); _Pragma("unroll") for (int m = 0; m < 4; ++m) _Pragma("unroll") for (int n = 0; n < 2; ++n) _Pragma("unroll") for (int k = 0; k < 2; ++k) \
;         acc[ai][bj][m][n] = __builtin_amdgcn_mfma_f32_16x16x32_bf16(Bt[n][k], At[m][k], acc[ai][bj][m][n], 0, 0, 0); __builtin_amdgcn_s_setprio(0); } while (0)
; #define PG8_WAIT_V(n) asm volatile("s_waitcnt vmcnt(" #n ")" ::: "memory")
; #define PG8_WAIT_L(n) asm volatile("s_waitcnt lgkmcnt(" #n ")" ::: "memory")
; #define PG8_BAR __builtin_amdgcn_s_barrier()
; #define PG8_SCHED __builtin_amdgcn_sched_barrier(0)
; template <class Epi, class Sched, bool ALIGN_EPI = false, bool SP2 = false>
; __device__ __forceinline__ void gemm_phase(PG8_LAS unsigned char* lds, const Gemm g, const Sched& S, const Epi& E) {
;     ...
;             PG8_LDA(At, 1, 1); PG8_STAGE(PG8_SB(1, 0), b3, voffB); PG8_STAGE(PG8_SB(1, 1), b3 + hstep, voffB); PG8_STAGE(PG8_SA(1, 0), a3, voffA);
;             PG8_WAIT_V(8); PG8_WAIT_L(0); PG8_BAR; PG8_MMA(1, 0, At, B0); PG8_MMA(1, 1, At, B1); PG8_BAR; PG8_SCHED;
;     ...
;         }
;         if constexpr (ALIGN_EPI) { if (wr == 0) PG8_BAR; }
	s_setprio 0
	s_add_i32 s46, s67, s3
	v_lshl_add_u64 v[204:205], v[204:205], 0, s[20:21]
	s_mov_b32 m0, s46
	ds_read_b128 v[160:163], v230 offset:49152
	ds_read_b128 v[164:167], v230 offset:50176
	ds_read_b128 v[168:171], v230 offset:51200
	ds_read_b128 v[172:175], v230 offset:52224
	ds_read_b128 v[176:179], v230 offset:53248
	ds_read_b128 v[180:183], v230 offset:54272
	ds_read_b128 v[184:187], v230 offset:55296
	ds_read_b128 v[200:203], v230 offset:56320
	global_load_lds_dwordx4 v[204:205], off
	s_add_i32 m0, s46, 0x2000
	s_add_u32 s46, s50, 0x80080
	v_lshl_add_u64 v[204:205], v[206:207], 0, s[20:21]
	s_addc_u32 s47, s51, 0
	s_add_i32 s50, s76, s3
	global_load_lds_dwordx4 v[204:205], off
	v_lshl_add_u64 v[204:205], s[46:47], 0, v[188:189]
	s_mov_b32 m0, s50
	s_nop 0
	global_load_lds_dwordx4 v[204:205], off
	v_lshl_add_u64 v[204:205], s[46:47], 0, v[190:191]
	s_add_i32 m0, s50, 0x2000
	s_nop 0
	global_load_lds_dwordx4 v[204:205], off
	v_lshl_add_u64 v[204:205], v[208:209], 0, s[20:21]
	s_mov_b32 m0, s35
	s_nop 0
	global_load_lds_dwordx4 v[204:205], off
	v_lshl_add_u64 v[204:205], v[210:211], 0, s[20:21]
	s_mov_b32 m0, s68
	s_nop 0
	global_load_lds_dwordx4 v[204:205], off
	s_waitcnt vmcnt(8)
	s_waitcnt lgkmcnt(0)
	s_setprio 1
	s_barrier
	v_mfma_f32_16x16x32_bf16 v[60:63], v[128:131], v[160:163], v[60:63]
	v_mfma_f32_16x16x32_bf16 v[56:59], v[136:139], v[160:163], v[56:59]
	v_mfma_f32_16x16x32_bf16 v[44:47], v[128:131], v[168:171], v[44:47]
	v_mfma_f32_16x16x32_bf16 v[40:43], v[136:139], v[168:171], v[40:43]
	v_mfma_f32_16x16x32_bf16 v[28:31], v[128:131], v[176:179], v[28:31]
	v_mfma_f32_16x16x32_bf16 v[24:27], v[136:139], v[176:179], v[24:27]
	v_mfma_f32_16x16x32_bf16 v[12:15], v[128:131], v[184:187], v[12:15]
	v_mfma_f32_16x16x32_bf16 v[8:11], v[136:139], v[184:187], v[8:11]
	v_mfma_f32_16x16x32_bf16 v[60:63], v[132:135], v[164:167], v[60:63]
	v_mfma_f32_16x16x32_bf16 v[56:59], v[140:143], v[164:167], v[56:59]
	v_mfma_f32_16x16x32_bf16 v[44:47], v[132:135], v[172:175], v[44:47]
	v_mfma_f32_16x16x32_bf16 v[40:43], v[140:143], v[172:175], v[40:43]
	v_mfma_f32_16x16x32_bf16 v[28:31], v[132:135], v[180:183], v[28:31]
	v_mfma_f32_16x16x32_bf16 v[24:27], v[140:143], v[180:183], v[24:27]
	v_mfma_f32_16x16x32_bf16 v[12:15], v[132:135], v[200:203], v[12:15]
	v_mfma_f32_16x16x32_bf16 v[8:11], v[140:143], v[200:203], v[8:11]
	v_mfma_f32_16x16x32_bf16 v[52:55], v[144:147], v[160:163], v[52:55]
	v_mfma_f32_16x16x32_bf16 v[48:51], v[152:155], v[160:163], v[48:51]
	v_mfma_f32_16x16x32_bf16 v[36:39], v[144:147], v[168:171], v[36:39]
	v_mfma_f32_16x16x32_bf16 v[32:35], v[152:155], v[168:171], v[32:35]
	v_mfma_f32_16x16x32_bf16 v[20:23], v[144:147], v[176:179], v[20:23]
	v_mfma_f32_16x16x32_bf16 v[16:19], v[152:155], v[176:179], v[16:19]
	v_mfma_f32_16x16x32_bf16 v[4:7], v[144:147], v[184:187], v[4:7]
	v_mfma_f32_16x16x32_bf16 v[0:3], v[152:155], v[184:187], v[0:3]
	v_mfma_f32_16x16x32_bf16 v[52:55], v[148:151], v[164:167], v[52:55]
	v_mfma_f32_16x16x32_bf16 v[48:51], v[156:159], v[164:167], v[48:51]
	v_mfma_f32_16x16x32_bf16 v[36:39], v[148:151], v[172:175], v[36:39]
	v_mfma_f32_16x16x32_bf16 v[32:35], v[156:159], v[172:175], v[32:35]
	v_mfma_f32_16x16x32_bf16 v[20:23], v[148:151], v[180:183], v[20:23]
	v_mfma_f32_16x16x32_bf16 v[16:19], v[156:159], v[180:183], v[16:19]
	v_mfma_f32_16x16x32_bf16 v[4:7], v[148:151], v[200:203], v[4:7]
	v_mfma_f32_16x16x32_bf16 v[0:3], v[156:159], v[200:203], v[0:3]
	s_barrier
	s_setprio 0
	s_add_i32 s66, s66, 2
	s_add_u32 s31, s31, 0x100
	s_addc_u32 s72, s72, 0
	s_cmp_gt_u32 s66, 29
	s_mov_b64 s[46:47], s[48:49]
	s_cbranch_scc0 .LBB0_876
	s_and_b64 vcc, exec, s[26:27]
	s_cbranch_vccz .LBB0_879
	s_barrier

; #define PG8_STAGE(bufoff, gbase, voff) do { _Pragma("unroll") for (int _i = 0; _i < 2; ++_i) \
;         __builtin_amdgcn_global_load_lds((const unsigned*)((const char*)(gbase) + (voff)[_i]), (PG8_LAS unsigned*)(lds + (bufoff) + ldsw + _i * 8192), 16, 0, 0); } while (0)
; #define PG8_LDA(dst, b, h) do { _Pragma("unroll") for (int m = 0; m < 4; ++m) _Pragma("unroll") for (int k = 0; k < 2; ++k) dst[m][k] = *(const PG8_LAS bf16x8*)(lds + PG8_SA(b, h) + aoff + m * 2048 + k * 1024); } while (0)
; #define PG8_LDB(dst, b, h) do { _Pragma("unroll") for (int n = 0; n < 2; ++n) _Pragma("unroll") for (int k = 0; k < 2; ++k) dst[n][k] = *(const PG8_LAS bf16x8*)(lds + PG8_SB(b, h) + boff + n * 2048 + k * 1024); } while (0)
; #define PG8_MMA(ai, bj, At, Bt) do { __builtin_amdgcn_s_setprio(1); _Pragma("unroll") for (int m = 0; m < 4; ++m) _Pragma("unroll") for (int n = 0; n < 2; ++n) _Pragma("unroll") for (int k = 0; k < 2; ++k) \
;         acc[ai][bj][m][n] = __builtin_amdgcn_mfma_f32_16x16x32_bf16(Bt[n][k], At[m][k], acc[ai][bj][m][n], 0, 0, 0); __builtin_amdgcn_s_setprio(0); } while (0)
; #define PG8_WAIT_V(n) asm volatile("s_waitcnt vmcnt(" #n ")" ::: "memory")
; #define PG8_WAIT_L(n) asm volatile("s_waitcnt lgkmcnt(" #n ")" ::: "memory")
; #define PG8_BAR __builtin_amdgcn_s_barrier()
; #define PG8_SCHED __builtin_amdgcn_sched_barrier(0)
; template <class Epi, class Sched, bool ALIGN_EPI = false, bool SP2 = false>
; __device__ __forceinline__ void gemm_phase(PG8_LAS unsigned char* lds, const Gemm g, const Sched& S, const Epi& E) {
;     ...
;             const bool last = (t == nt - 2);
;             const char* a1 = cA + (size_t)(t + 1) * kstep;
;             const char* a2 = last ? nA : cA + (size_t)(t + 2) * kstep; const char* b2 = last ? nB : cB + (size_t)(t + 2) * kstep;
;     ...
;             PG8_LDB(B0, 0, 0); PG8_LDB(B1, 0, 1); PG8_SCHED; PG8_LDA(At, 0, 0); PG8_STAGE(PG8_SA(1, 1), a1 + hstep, voffA);
;             PG8_WAIT_V(8); PG8_WAIT_L(0); PG8_BAR; PG8_MMA(0, 0, At, B0); PG8_MMA(0, 1, At, B1); PG8_BAR; PG8_SCHED;
;             PG8_LDA(At, 0, 1); PG8_STAGE(PG8_SB(0, 0), b2, voffB); PG8_STAGE(PG8_SB(0, 1), b2 + hstep, voffB); PG8_STAGE(PG8_SA(0, 0), a2, voffA);
;             PG8_WAIT_V(8); PG8_WAIT_L(0); PG8_BAR; PG8_MMA(1, 0, At, B0); PG8_MMA(1, 1, At, B1); PG8_BAR; PG8_SCHED;
.LBB0_1025:
	ds_read_b128 v[146:149], v167
	ds_read_b128 v[150:153], v167 offset:1024
	ds_read_b128 v[178:181], v167 offset:2048
	ds_read_b128 v[182:185], v167 offset:3072
	ds_read_b128 v[186:189], v171
	ds_read_b128 v[190:193], v171 offset:1024
	ds_read_b128 v[194:197], v171 offset:2048
	ds_read_b128 v[198:201], v171 offset:3072
	s_add_u32 s30, s28, 0xfff80080
	s_addc_u32 s31, s29, -1
	s_cmp_eq_u32 s49, 28
	s_cselect_b32 s37, s12, s31
	s_cselect_b32 s36, s13, s30
	s_cselect_b32 s31, s1, s48
	s_cselect_b32 s30, s19, s47
	v_lshl_add_u64 v[156:157], s[28:29], 0, v[138:139]
	s_add_i32 m0, s15, 0xc000
	ds_read_b128 v[202:205], v175
	ds_read_b128 v[206:209], v175 offset:1024
	ds_read_b128 v[210:213], v175 offset:2048
	ds_read_b128 v[214:217], v175 offset:3072
	ds_read_b128 v[218:221], v175 offset:4096
	ds_read_b128 v[226:229], v175 offset:5120
	ds_read_b128 v[230:233], v175 offset:6144
	ds_read_b128 v[234:237], v175 offset:7168
	global_load_lds_dwordx4 v[156:157], off
	v_lshl_add_u64 v[156:157], s[28:29], 0, v[140:141]
	s_add_i32 m0, s15, 0xe000
	s_nop 0
	global_load_lds_dwordx4 v[156:157], off
	s_waitcnt vmcnt(8)
	s_waitcnt lgkmcnt(0)
	s_setprio 1
	s_barrier
	v_mfma_f32_16x16x32_bf16 v[124:127], v[146:149], v[202:205], v[124:127]
	v_mfma_f32_16x16x32_bf16 v[120:123], v[178:181], v[202:205], v[120:123]
	v_mfma_f32_16x16x32_bf16 v[108:111], v[146:149], v[210:213], v[108:111]
	v_mfma_f32_16x16x32_bf16 v[104:107], v[178:181], v[210:213], v[104:107]
	v_mfma_f32_16x16x32_bf16 v[92:95], v[146:149], v[218:221], v[92:95]
	v_mfma_f32_16x16x32_bf16 v[88:91], v[178:181], v[218:221], v[88:91]
	v_mfma_f32_16x16x32_bf16 v[76:79], v[146:149], v[230:233], v[76:79]
	v_mfma_f32_16x16x32_bf16 v[72:75], v[178:181], v[230:233], v[72:75]
	v_mfma_f32_16x16x32_bf16 v[124:127], v[150:153], v[206:209], v[124:127]
	v_mfma_f32_16x16x32_bf16 v[120:123], v[182:185], v[206:209], v[120:123]
	v_mfma_f32_16x16x32_bf16 v[108:111], v[150:153], v[214:217], v[108:111]
	v_mfma_f32_16x16x32_bf16 v[104:107], v[182:185], v[214:217], v[104:107]
	v_mfma_f32_16x16x32_bf16 v[92:95], v[150:153], v[226:229], v[92:95]
	v_mfma_f32_16x16x32_bf16 v[88:91], v[182:185], v[226:229], v[88:91]
	v_mfma_f32_16x16x32_bf16 v[76:79], v[150:153], v[234:237], v[76:79]
	v_mfma_f32_16x16x32_bf16 v[72:75], v[182:185], v[234:237], v[72:75]
	v_mfma_f32_16x16x32_bf16 v[116:119], v[186:189], v[202:205], v[116:119]
	v_mfma_f32_16x16x32_bf16 v[112:115], v[194:197], v[202:205], v[112:115]
	v_mfma_f32_16x16x32_bf16 v[100:103], v[186:189], v[210:213], v[100:103]
	v_mfma_f32_16x16x32_bf16 v[96:99], v[194:197], v[210:213], v[96:99]
	v_mfma_f32_16x16x32_bf16 v[84:87], v[186:189], v[218:221], v[84:87]
	v_mfma_f32_16x16x32_bf16 v[80:83], v[194:197], v[218:221], v[80:83]
	v_mfma_f32_16x16x32_bf16 v[68:71], v[186:189], v[230:233], v[68:71]
	v_mfma_f32_16x16x32_bf16 v[64:67], v[194:197], v[230:233], v[64:67]
	v_mfma_f32_16x16x32_bf16 v[116:119], v[190:193], v[206:209], v[116:119]
	v_mfma_f32_16x16x32_bf16 v[112:115], v[198:201], v[206:209], v[112:115]
	v_mfma_f32_16x16x32_bf16 v[100:103], v[190:193], v[214:217], v[100:103]
	v_mfma_f32_16x16x32_bf16 v[96:99], v[198:201], v[214:217], v[96:99]
	v_mfma_f32_16x16x32_bf16 v[84:87], v[190:193], v[226:229], v[84:87]
	v_mfma_f32_16x16x32_bf16 v[80:83], v[198:201], v[226:229], v[80:83]
	v_mfma_f32_16x16x32_bf16 v[68:71], v[190:193], v[234:237], v[68:71]
	v_mfma_f32_16x16x32_bf16 v[64:67], v[198:201], v[234:237], v[64:67]
	s_barrier
	s_setprio 0
	s_add_i32 s50, s43, s3
	v_lshl_add_u64 v[156:157], s[30:31], 0, v[132:133]
	s_mov_b32 m0, s50
	ds_read_b128 v[202:205], v175 offset:16384
	ds_read_b128 v[206:209], v175 offset:17408
	ds_read_b128 v[210:213], v175 offset:18432
	ds_read_b128 v[214:217], v175 offset:19456
	ds_read_b128 v[218:221], v175 offset:20480
	ds_read_b128 v[226:229], v175 offset:21504
	ds_read_b128 v[230:233], v175 offset:22528
	ds_read_b128 v[234:237], v175 offset:23552
	global_load_lds_dwordx4 v[156:157], off
	s_add_i32 m0, s50, 0x2000
	s_add_u32 s50, s30, 0x80000
	v_lshl_add_u64 v[160:161], s[30:31], 0, v[128:129]
	s_addc_u32 s51, s31, 0
	s_add_i32 s66, s44, s3
	global_load_lds_dwordx4 v[160:161], off
	v_lshl_add_u64 v[164:165], s[50:51], 0, v[132:133]
	s_mov_b32 m0, s66
	v_lshl_add_u64 v[168:169], s[36:37], 0, v[130:131]
	global_load_lds_dwordx4 v[164:165], off
	v_lshl_add_u64 v[164:165], s[50:51], 0, v[128:129]
	s_add_i32 m0, s66, 0x2000
	s_nop 0
	global_load_lds_dwordx4 v[164:165], off
	v_lshl_add_u64 v[164:165], s[36:37], 0, v[134:135]
	s_mov_b32 m0, s15
	s_nop 0
	global_load_lds_dwordx4 v[164:165], off
	s_mov_b32 m0, s22
	s_nop 0
	global_load_lds_dwordx4 v[168:169], off
	s_waitcnt vmcnt(8)
	s_waitcnt lgkmcnt(0)
	s_setprio 1
	s_barrier
; #define PG8_STAGE(bufoff, gbase, voff) do { _Pragma("unroll") for (int _i = 0; _i < 2; ++_i) \
;         __builtin_amdgcn_global_load_lds((const unsigned*)((const char*)(gbase) + (voff)[_i]), (PG8_LAS unsigned*)(lds + (bufoff) + ldsw + _i * 8192), 16, 0, 0); } while (0)
; #define PG8_LDA(dst, b, h) do { _Pragma("unroll") for (int m = 0; m < 4; ++m) _Pragma("unroll") for (int k = 0; k < 2; ++k) dst[m][k] = *(const PG8_LAS bf16x8*)(lds + PG8_SA(b, h) + aoff + m * 2048 + k * 1024); } while (0)
; #define PG8_LDB(dst, b, h) do { _Pragma("unroll") for (int n = 0; n < 2; ++n) _Pragma("unroll") for (int k = 0; k < 2; ++k) dst[n][k] = *(const PG8_LAS bf16x8*)(lds + PG8_SB(b, h) + boff + n * 2048 + k * 1024); } while (0)
; #define PG8_MMA(ai, bj, At, Bt) do { __builtin_amdgcn_s_setprio(1); _Pragma("unroll") for (int m = 0; m < 4; ++m) _Pragma("unroll") for (int n = 0; n < 2; ++n) _Pragma("unroll") for (int k = 0; k < 2; ++k) \
;         acc[ai][bj][m][n] = __builtin_amdgcn_mfma_f32_16x16x32_bf16(Bt[n][k], At[m][k], acc[ai][bj][m][n], 0, 0, 0); __builtin_amdgcn_s_setprio(0); } while (0)
; #define PG8_WAIT_V(n) asm volatile("s_waitcnt vmcnt(" #n ")" ::: "memory")
; #define PG8_WAIT_L(n) asm volatile("s_waitcnt lgkmcnt(" #n ")" ::: "memory")
; #define PG8_BAR __builtin_amdgcn_s_barrier()
; #define PG8_SCHED __builtin_amdgcn_sched_barrier(0)
; template <class Epi, class Sched, bool ALIGN_EPI = false, bool SP2 = false>
; __device__ __forceinline__ void gemm_phase(PG8_LAS unsigned char* lds, const Gemm g, const Sched& S, const Epi& E) {
;     ...
;             PG8_WAIT_V(8); PG8_WAIT_L(0); PG8_BAR; PG8_MMA(1, 0, At, B0); PG8_MMA(1, 1, At, B1); PG8_BAR; PG8_SCHED;
;             PG8_LDB(B0, 1, 0); PG8_LDB(B1, 1, 1); PG8_SCHED; PG8_LDA(At, 1, 0); PG8_STAGE(PG8_SA(0, 1), a2 + hstep, voffA);
;             PG8_WAIT_V(8); PG8_WAIT_L(0); PG8_BAR; PG8_MMA(0, 0, At, B0); PG8_MMA(0, 1, At, B1); PG8_BAR; PG8_SCHED;
	v_mfma_f32_16x16x32_bf16 v[60:63], v[146:149], v[202:205], v[60:63]
	v_mfma_f32_16x16x32_bf16 v[56:59], v[178:181], v[202:205], v[56:59]
	v_mfma_f32_16x16x32_bf16 v[44:47], v[146:149], v[210:213], v[44:47]
	v_mfma_f32_16x16x32_bf16 v[40:43], v[178:181], v[210:213], v[40:43]
	v_mfma_f32_16x16x32_bf16 v[28:31], v[146:149], v[218:221], v[28:31]
	v_mfma_f32_16x16x32_bf16 v[24:27], v[178:181], v[218:221], v[24:27]
	v_mfma_f32_16x16x32_bf16 v[12:15], v[146:149], v[230:233], v[12:15]
	v_mfma_f32_16x16x32_bf16 v[8:11], v[178:181], v[230:233], v[8:11]
	v_mfma_f32_16x16x32_bf16 v[60:63], v[150:153], v[206:209], v[60:63]
	v_mfma_f32_16x16x32_bf16 v[56:59], v[182:185], v[206:209], v[56:59]
	v_mfma_f32_16x16x32_bf16 v[44:47], v[150:153], v[214:217], v[44:47]
	v_mfma_f32_16x16x32_bf16 v[40:43], v[182:185], v[214:217], v[40:43]
	v_mfma_f32_16x16x32_bf16 v[28:31], v[150:153], v[226:229], v[28:31]
	v_mfma_f32_16x16x32_bf16 v[24:27], v[182:185], v[226:229], v[24:27]
	v_mfma_f32_16x16x32_bf16 v[12:15], v[150:153], v[234:237], v[12:15]
	v_mfma_f32_16x16x32_bf16 v[8:11], v[182:185], v[234:237], v[8:11]
	v_mfma_f32_16x16x32_bf16 v[52:55], v[186:189], v[202:205], v[52:55]
	v_mfma_f32_16x16x32_bf16 v[48:51], v[194:197], v[202:205], v[48:51]
	v_mfma_f32_16x16x32_bf16 v[36:39], v[186:189], v[210:213], v[36:39]
	v_mfma_f32_16x16x32_bf16 v[32:35], v[194:197], v[210:213], v[32:35]
	v_mfma_f32_16x16x32_bf16 v[20:23], v[186:189], v[218:221], v[20:23]
	v_mfma_f32_16x16x32_bf16 v[16:19], v[194:197], v[218:221], v[16:19]
	v_mfma_f32_16x16x32_bf16 v[4:7], v[186:189], v[230:233], v[4:7]
	v_mfma_f32_16x16x32_bf16 v[0:3], v[194:197], v[230:233], v[0:3]
	v_mfma_f32_16x16x32_bf16 v[52:55], v[190:193], v[206:209], v[52:55]
	v_mfma_f32_16x16x32_bf16 v[48:51], v[198:201], v[206:209], v[48:51]
	v_mfma_f32_16x16x32_bf16 v[36:39], v[190:193], v[214:217], v[36:39]
	v_mfma_f32_16x16x32_bf16 v[32:35], v[198:201], v[214:217], v[32:35]
	v_mfma_f32_16x16x32_bf16 v[20:23], v[190:193], v[226:229], v[20:23]
	v_mfma_f32_16x16x32_bf16 v[16:19], v[198:201], v[226:229], v[16:19]
	v_mfma_f32_16x16x32_bf16 v[4:7], v[190:193], v[234:237], v[4:7]
	v_mfma_f32_16x16x32_bf16 v[0:3], v[198:201], v[234:237], v[0:3]
	s_barrier
	s_setprio 0
	s_add_i32 s50, 0, 0x18000
	v_add_u32_e32 v154, s50, v159
	s_add_i32 s51, 0, 0x1c000
	ds_read_b128 v[146:149], v154
	ds_read_b128 v[150:153], v154 offset:1024
	ds_read_b128 v[178:181], v154 offset:2048
	ds_read_b128 v[182:185], v154 offset:3072
	v_add_u32_e32 v154, s51, v159
	ds_read_b128 v[186:189], v154
	ds_read_b128 v[190:193], v154 offset:1024
	ds_read_b128 v[194:197], v154 offset:2048
	ds_read_b128 v[198:201], v154 offset:3072
	s_add_u32 s36, s36, 0x80000
	s_addc_u32 s37, s37, 0
	s_mov_b32 m0, s23
	v_lshl_add_u64 v[172:173], s[36:37], 0, v[134:135]
	ds_read_b128 v[202:205], v175 offset:32768
	ds_read_b128 v[206:209], v175 offset:33792
	ds_read_b128 v[210:213], v175 offset:34816
	ds_read_b128 v[214:217], v175 offset:35840
	ds_read_b128 v[218:221], v175 offset:36864
	ds_read_b128 v[226:229], v175 offset:37888
	ds_read_b128 v[230:233], v175 offset:38912
	ds_read_b128 v[234:237], v175 offset:39936
	global_load_lds_dwordx4 v[172:173], off
	v_lshl_add_u64 v[172:173], s[36:37], 0, v[130:131]
	s_mov_b32 m0, s27
	s_nop 0
	global_load_lds_dwordx4 v[172:173], off
	s_waitcnt vmcnt(8)
	s_waitcnt lgkmcnt(0)
	s_setprio 1
	s_barrier
	v_mfma_f32_16x16x32_bf16 v[124:127], v[146:149], v[202:205], v[124:127]
	v_mfma_f32_16x16x32_bf16 v[120:123], v[178:181], v[202:205], v[120:123]
	v_mfma_f32_16x16x32_bf16 v[108:111], v[146:149], v[210:213], v[108:111]
	v_mfma_f32_16x16x32_bf16 v[104:107], v[178:181], v[210:213], v[104:107]
	v_mfma_f32_16x16x32_bf16 v[92:95], v[146:149], v[218:221], v[92:95]
	v_mfma_f32_16x16x32_bf16 v[88:91], v[178:181], v[218:221], v[88:91]
	v_mfma_f32_16x16x32_bf16 v[76:79], v[146:149], v[230:233], v[76:79]
	v_mfma_f32_16x16x32_bf16 v[72:75], v[178:181], v[230:233], v[72:75]
	v_mfma_f32_16x16x32_bf16 v[124:127], v[150:153], v[206:209], v[124:127]
	v_mfma_f32_16x16x32_bf16 v[120:123], v[182:185], v[206:209], v[120:123]
	v_mfma_f32_16x16x32_bf16 v[108:111], v[150:153], v[214:217], v[108:111]
	v_mfma_f32_16x16x32_bf16 v[104:107], v[182:185], v[214:217], v[104:107]
	v_mfma_f32_16x16x32_bf16 v[92:95], v[150:153], v[226:229], v[92:95]
	v_mfma_f32_16x16x32_bf16 v[88:91], v[182:185], v[226:229], v[88:91]
	v_mfma_f32_16x16x32_bf16 v[76:79], v[150:153], v[234:237], v[76:79]
	v_mfma_f32_16x16x32_bf16 v[72:75], v[182:185], v[234:237], v[72:75]
	v_mfma_f32_16x16x32_bf16 v[116:119], v[186:189], v[202:205], v[116:119]
	v_mfma_f32_16x16x32_bf16 v[112:115], v[194:197], v[202:205], v[112:115]
	v_mfma_f32_16x16x32_bf16 v[100:103], v[186:189], v[210:213], v[100:103]
	v_mfma_f32_16x16x32_bf16 v[96:99], v[194:197], v[210:213], v[96:99]
	v_mfma_f32_16x16x32_bf16 v[84:87], v[186:189], v[218:221], v[84:87]
	v_mfma_f32_16x16x32_bf16 v[80:83], v[194:197], v[218:221], v[80:83]
	v_mfma_f32_16x16x32_bf16 v[68:71], v[186:189], v[230:233], v[68:71]
	v_mfma_f32_16x16x32_bf16 v[64:67], v[194:197], v[230:233], v[64:67]
	v_mfma_f32_16x16x32_bf16 v[116:119], v[190:193], v[206:209], v[116:119]
	v_mfma_f32_16x16x32_bf16 v[112:115], v[198:201], v[206:209], v[112:115]
	v_mfma_f32_16x16x32_bf16 v[100:103], v[190:193], v[214:217], v[100:103]
	v_mfma_f32_16x16x32_bf16 v[96:99], v[198:201], v[214:217], v[96:99]
	v_mfma_f32_16x16x32_bf16 v[84:87], v[190:193], v[226:229], v[84:87]
	v_mfma_f32_16x16x32_bf16 v[80:83], v[198:201], v[226:229], v[80:83]
	v_mfma_f32_16x16x32_bf16 v[68:71], v[190:193], v[234:237], v[68:71]
	v_mfma_f32_16x16x32_bf16 v[64:67], v[198:201], v[234:237], v[64:67]
	s_barrier
; #define PG8_STAGE(bufoff, gbase, voff) do { _Pragma("unroll") for (int _i = 0; _i < 2; ++_i) \
;         __builtin_amdgcn_global_load_lds((const unsigned*)((const char*)(gbase) + (voff)[_i]), (PG8_LAS unsigned*)(lds + (bufoff) + ldsw + _i * 8192), 16, 0, 0); } while (0)
; #define PG8_LDA(dst, b, h) do { _Pragma("unroll") for (int m = 0; m < 4; ++m) _Pragma("unroll") for (int k = 0; k < 2; ++k) dst[m][k] = *(const PG8_LAS bf16x8*)(lds + PG8_SA(b, h) + aoff + m * 2048 + k * 1024); } while (0)
; #define PG8_MMA(ai, bj, At, Bt) do { __builtin_amdgcn_s_setprio(1); _Pragma("unroll") for (int m = 0; m < 4; ++m) _Pragma("unroll") for (int n = 0; n < 2; ++n) _Pragma("unroll") for (int k = 0; k < 2; ++k) \
;         acc[ai][bj][m][n] = __builtin_amdgcn_mfma_f32_16x16x32_bf16(Bt[n][k], At[m][k], acc[ai][bj][m][n], 0, 0, 0); __builtin_amdgcn_s_setprio(0); } while (0)
; #define PG8_WAIT_V(n) asm volatile("s_waitcnt vmcnt(" #n ")" ::: "memory")
; #define PG8_WAIT_L(n) asm volatile("s_waitcnt lgkmcnt(" #n ")" ::: "memory")
; #define PG8_BAR __builtin_amdgcn_s_barrier()
; #define PG8_SCHED __builtin_amdgcn_sched_barrier(0)
; template <class Epi, class Sched, bool ALIGN_EPI = false, bool SP2 = false>
; __device__ __forceinline__ void gemm_phase(PG8_LAS unsigned char* lds, const Gemm g, const Sched& S, const Epi& E) {
;     ...
;             PG8_LDA(At, 1, 1); PG8_STAGE(PG8_SB(1, 0), b3, voffB); PG8_STAGE(PG8_SB(1, 1), b3 + hstep, voffB); PG8_STAGE(PG8_SA(1, 0), a3, voffA);
;             PG8_WAIT_V(8); PG8_WAIT_L(0); PG8_BAR; PG8_MMA(1, 0, At, B0); PG8_MMA(1, 1, At, B1); PG8_BAR; PG8_SCHED;
;     ...
;         }
;         if constexpr (ALIGN_EPI) { if (wr == 0) PG8_BAR; }
	s_setprio 0
	s_add_i32 s36, s50, s3
	v_lshl_add_u64 v[156:157], v[156:157], 0, s[10:11]
	s_mov_b32 m0, s36
	ds_read_b128 v[202:205], v175 offset:49152
	ds_read_b128 v[206:209], v175 offset:50176
	ds_read_b128 v[210:213], v175 offset:51200
	ds_read_b128 v[214:217], v175 offset:52224
	ds_read_b128 v[218:221], v175 offset:53248
	ds_read_b128 v[226:229], v175 offset:54272
	ds_read_b128 v[230:233], v175 offset:55296
	ds_read_b128 v[234:237], v175 offset:56320
	global_load_lds_dwordx4 v[156:157], off
	s_add_i32 m0, s36, 0x2000
	s_add_u32 s30, s30, 0x80080
	v_lshl_add_u64 v[156:157], v[160:161], 0, s[10:11]
	s_addc_u32 s31, s31, 0
	s_add_i32 s36, s51, s3
	global_load_lds_dwordx4 v[156:157], off
	v_lshl_add_u64 v[156:157], s[30:31], 0, v[132:133]
	s_mov_b32 m0, s36
	s_nop 0
	global_load_lds_dwordx4 v[156:157], off
	v_lshl_add_u64 v[156:157], s[30:31], 0, v[128:129]
	s_add_i32 m0, s36, 0x2000
	s_nop 0
	global_load_lds_dwordx4 v[156:157], off
	v_lshl_add_u64 v[156:157], v[164:165], 0, s[10:11]
	s_mov_b32 m0, s35
	s_nop 0
	global_load_lds_dwordx4 v[156:157], off
	v_lshl_add_u64 v[156:157], v[168:169], 0, s[10:11]
	s_mov_b32 m0, s42
	s_nop 0
	global_load_lds_dwordx4 v[156:157], off
	s_waitcnt vmcnt(8)
	s_waitcnt lgkmcnt(0)
	s_setprio 1
	s_barrier
	v_mfma_f32_16x16x32_bf16 v[60:63], v[146:149], v[202:205], v[60:63]
	v_mfma_f32_16x16x32_bf16 v[56:59], v[178:181], v[202:205], v[56:59]
	v_mfma_f32_16x16x32_bf16 v[44:47], v[146:149], v[210:213], v[44:47]
	v_mfma_f32_16x16x32_bf16 v[40:43], v[178:181], v[210:213], v[40:43]
	v_mfma_f32_16x16x32_bf16 v[28:31], v[146:149], v[218:221], v[28:31]
	v_mfma_f32_16x16x32_bf16 v[24:27], v[178:181], v[218:221], v[24:27]
	v_mfma_f32_16x16x32_bf16 v[12:15], v[146:149], v[230:233], v[12:15]
	v_mfma_f32_16x16x32_bf16 v[8:11], v[178:181], v[230:233], v[8:11]
	v_mfma_f32_16x16x32_bf16 v[60:63], v[150:153], v[206:209], v[60:63]
	v_mfma_f32_16x16x32_bf16 v[56:59], v[182:185], v[206:209], v[56:59]
	v_mfma_f32_16x16x32_bf16 v[44:47], v[150:153], v[214:217], v[44:47]
	v_mfma_f32_16x16x32_bf16 v[40:43], v[182:185], v[214:217], v[40:43]
	v_mfma_f32_16x16x32_bf16 v[28:31], v[150:153], v[226:229], v[28:31]
	v_mfma_f32_16x16x32_bf16 v[24:27], v[182:185], v[226:229], v[24:27]
	v_mfma_f32_16x16x32_bf16 v[12:15], v[150:153], v[234:237], v[12:15]
	v_mfma_f32_16x16x32_bf16 v[8:11], v[182:185], v[234:237], v[8:11]
	v_mfma_f32_16x16x32_bf16 v[52:55], v[186:189], v[202:205], v[52:55]
	v_mfma_f32_16x16x32_bf16 v[48:51], v[194:197], v[202:205], v[48:51]
	v_mfma_f32_16x16x32_bf16 v[36:39], v[186:189], v[210:213], v[36:39]
	v_mfma_f32_16x16x32_bf16 v[32:35], v[194:197], v[210:213], v[32:35]
	v_mfma_f32_16x16x32_bf16 v[20:23], v[186:189], v[218:221], v[20:23]
	v_mfma_f32_16x16x32_bf16 v[16:19], v[194:197], v[218:221], v[16:19]
	v_mfma_f32_16x16x32_bf16 v[4:7], v[186:189], v[230:233], v[4:7]
	v_mfma_f32_16x16x32_bf16 v[0:3], v[194:197], v[230:233], v[0:3]
	v_mfma_f32_16x16x32_bf16 v[52:55], v[190:193], v[206:209], v[52:55]
	v_mfma_f32_16x16x32_bf16 v[48:51], v[198:201], v[206:209], v[48:51]
	v_mfma_f32_16x16x32_bf16 v[36:39], v[190:193], v[214:217], v[36:39]
	v_mfma_f32_16x16x32_bf16 v[32:35], v[198:201], v[214:217], v[32:35]
	v_mfma_f32_16x16x32_bf16 v[20:23], v[190:193], v[226:229], v[20:23]
	v_mfma_f32_16x16x32_bf16 v[16:19], v[198:201], v[226:229], v[16:19]
	v_mfma_f32_16x16x32_bf16 v[4:7], v[190:193], v[234:237], v[4:7]
	v_mfma_f32_16x16x32_bf16 v[0:3], v[198:201], v[234:237], v[0:3]
	s_barrier
	s_setprio 0
	s_add_i32 s49, s49, 2
	s_add_u32 s28, s28, 0x100
	s_addc_u32 s29, s29, 0
	s_add_u32 s47, s47, 0x100
	s_addc_u32 s48, s48, 0
	s_cmp_gt_u32 s49, 29
	s_cbranch_scc0 .LBB0_1025
	s_and_b64 vcc, exec, s[16:17]
	s_cbranch_vccz .LBB0_1028
	s_barrier

; #define PG8_STAGE(bufoff, gbase, voff) do { _Pragma("unroll") for (int _i = 0; _i < 2; ++_i) \
;         __builtin_amdgcn_global_load_lds((const unsigned*)((const char*)(gbase) + (voff)[_i]), (PG8_LAS unsigned*)(lds + (bufoff) + ldsw + _i * 8192), 16, 0, 0); } while (0)
; #define PG8_LDA(dst, b, h) do { _Pragma("unroll") for (int m = 0; m < 4; ++m) _Pragma("unroll") for (int k = 0; k < 2; ++k) dst[m][k] = *(const PG8_LAS bf16x8*)(lds + PG8_SA(b, h) + aoff + m * 2048 + k * 1024); } while (0)
; #define PG8_LDB(dst, b, h) do { _Pragma("unroll") for (int n = 0; n < 2; ++n) _Pragma("unroll") for (int k = 0; k < 2; ++k) dst[n][k] = *(const PG8_LAS bf16x8*)(lds + PG8_SB(b, h) + boff + n * 2048 + k * 1024); } while (0)
; #define PG8_MMA(ai, bj, At, Bt) do { __builtin_amdgcn_s_setprio(1); _Pragma("unroll") for (int m = 0; m < 4; ++m) _Pragma("unroll") for (int n = 0; n < 2; ++n) _Pragma("unroll") for (int k = 0; k < 2; ++k) \
;         acc[ai][bj][m][n] = __builtin_amdgcn_mfma_f32_16x16x32_bf16(Bt[n][k], At[m][k], acc[ai][bj][m][n], 0, 0, 0); __builtin_amdgcn_s_setprio(0); } while (0)
; #define PG8_WAIT_V(n) asm volatile("s_waitcnt vmcnt(" #n ")" ::: "memory")
; #define PG8_WAIT_L(n) asm volatile("s_waitcnt lgkmcnt(" #n ")" ::: "memory")
; #define PG8_BAR __builtin_amdgcn_s_barrier()
; #define PG8_SCHED __builtin_amdgcn_sched_barrier(0)
; template <class Epi, class Sched, bool ALIGN_EPI = false, bool SP2 = false>
; __device__ __forceinline__ void gemm_phase(PG8_LAS unsigned char* lds, const Gemm g, const Sched& S, const Epi& E) {
;     ...
;             const bool last = (t == nt - 2);
;             const char* a1 = cA + (size_t)(t + 1) * kstep;
;             const char* a2 = last ? nA : cA + (size_t)(t + 2) * kstep; const char* b2 = last ? nB : cB + (size_t)(t + 2) * kstep;
;     ...
;             PG8_LDB(B0, 0, 0); PG8_LDB(B1, 0, 1); PG8_SCHED; PG8_LDA(At, 0, 0); PG8_STAGE(PG8_SA(1, 1), a1 + hstep, voffA);
;             PG8_WAIT_V(8); PG8_WAIT_L(0); PG8_BAR; PG8_MMA(0, 0, At, B0); PG8_MMA(0, 1, At, B1); PG8_BAR; PG8_SCHED;
;             PG8_LDA(At, 0, 1); PG8_STAGE(PG8_SB(0, 0), b2, voffB); PG8_STAGE(PG8_SB(0, 1), b2 + hstep, voffB); PG8_STAGE(PG8_SA(0, 0), a2, voffA);
;             PG8_WAIT_V(8); PG8_WAIT_L(0); PG8_BAR; PG8_MMA(1, 0, At, B0); PG8_MMA(1, 1, At, B1); PG8_BAR; PG8_SCHED;
.LBB0_1108:
	ds_read_b128 v[128:131], v209
	ds_read_b128 v[132:135], v209 offset:1024
	ds_read_b128 v[136:139], v209 offset:2048
	ds_read_b128 v[140:143], v209 offset:3072
	ds_read_b128 v[144:147], v210
	ds_read_b128 v[148:151], v210 offset:1024
	ds_read_b128 v[152:155], v210 offset:2048
	ds_read_b128 v[156:159], v210 offset:3072
	s_add_u32 s30, s28, 0x100
	s_addc_u32 s31, s29, 0
	s_cmpk_eq_i32 s50, 0x54
	s_cselect_b32 s41, s11, s31
	s_cselect_b32 s40, s10, s30
	s_cselect_b32 s37, s27, s49
	s_cselect_b32 s36, s26, s13
	v_lshl_add_u64 v[204:205], s[28:29], 0, v[180:181]
	s_add_i32 m0, s15, 0xc000
	ds_read_b128 v[160:163], v211
	ds_read_b128 v[164:167], v211 offset:1024
	ds_read_b128 v[168:171], v211 offset:2048
	ds_read_b128 v[172:175], v211 offset:3072
	ds_read_b128 v[188:191], v211 offset:4096
	ds_read_b128 v[192:195], v211 offset:5120
	ds_read_b128 v[196:199], v211 offset:6144
	ds_read_b128 v[200:203], v211 offset:7168
	global_load_lds_dwordx4 v[204:205], off
	v_lshl_add_u64 v[204:205], s[28:29], 0, v[182:183]
	s_add_i32 m0, s15, 0xe000
	s_nop 0
	global_load_lds_dwordx4 v[204:205], off
	s_waitcnt vmcnt(8)
	s_waitcnt lgkmcnt(0)
	s_setprio 1
	s_barrier
	v_mfma_f32_16x16x32_bf16 v[124:127], v[128:131], v[160:163], v[124:127]
	v_mfma_f32_16x16x32_bf16 v[120:123], v[136:139], v[160:163], v[120:123]
	v_mfma_f32_16x16x32_bf16 v[108:111], v[128:131], v[168:171], v[108:111]
	v_mfma_f32_16x16x32_bf16 v[104:107], v[136:139], v[168:171], v[104:107]
	v_mfma_f32_16x16x32_bf16 v[92:95], v[128:131], v[188:191], v[92:95]
	v_mfma_f32_16x16x32_bf16 v[88:91], v[136:139], v[188:191], v[88:91]
	v_mfma_f32_16x16x32_bf16 v[76:79], v[128:131], v[196:199], v[76:79]
	v_mfma_f32_16x16x32_bf16 v[72:75], v[136:139], v[196:199], v[72:75]
	v_mfma_f32_16x16x32_bf16 v[124:127], v[132:135], v[164:167], v[124:127]
	v_mfma_f32_16x16x32_bf16 v[120:123], v[140:143], v[164:167], v[120:123]
	v_mfma_f32_16x16x32_bf16 v[108:111], v[132:135], v[172:175], v[108:111]
	v_mfma_f32_16x16x32_bf16 v[104:107], v[140:143], v[172:175], v[104:107]
	v_mfma_f32_16x16x32_bf16 v[92:95], v[132:135], v[192:195], v[92:95]
	v_mfma_f32_16x16x32_bf16 v[88:91], v[140:143], v[192:195], v[88:91]
	v_mfma_f32_16x16x32_bf16 v[76:79], v[132:135], v[200:203], v[76:79]
	v_mfma_f32_16x16x32_bf16 v[72:75], v[140:143], v[200:203], v[72:75]
	v_mfma_f32_16x16x32_bf16 v[116:119], v[144:147], v[160:163], v[116:119]
	v_mfma_f32_16x16x32_bf16 v[112:115], v[152:155], v[160:163], v[112:115]
	v_mfma_f32_16x16x32_bf16 v[100:103], v[144:147], v[168:171], v[100:103]
	v_mfma_f32_16x16x32_bf16 v[96:99], v[152:155], v[168:171], v[96:99]
	v_mfma_f32_16x16x32_bf16 v[84:87], v[144:147], v[188:191], v[84:87]
	v_mfma_f32_16x16x32_bf16 v[80:83], v[152:155], v[188:191], v[80:83]
	v_mfma_f32_16x16x32_bf16 v[68:71], v[144:147], v[196:199], v[68:71]
	v_mfma_f32_16x16x32_bf16 v[64:67], v[152:155], v[196:199], v[64:67]
	v_mfma_f32_16x16x32_bf16 v[116:119], v[148:151], v[164:167], v[116:119]
	v_mfma_f32_16x16x32_bf16 v[112:115], v[156:159], v[164:167], v[112:115]
	v_mfma_f32_16x16x32_bf16 v[100:103], v[148:151], v[172:175], v[100:103]
	v_mfma_f32_16x16x32_bf16 v[96:99], v[156:159], v[172:175], v[96:99]
	v_mfma_f32_16x16x32_bf16 v[84:87], v[148:151], v[192:195], v[84:87]
	v_mfma_f32_16x16x32_bf16 v[80:83], v[156:159], v[192:195], v[80:83]
	v_mfma_f32_16x16x32_bf16 v[68:71], v[148:151], v[200:203], v[68:71]
	v_mfma_f32_16x16x32_bf16 v[64:67], v[156:159], v[200:203], v[64:67]
	s_barrier
	s_setprio 0
	s_add_i32 s28, s44, s14
	v_lshl_add_u64 v[204:205], s[36:37], 0, v[176:177]
	s_mov_b32 m0, s28
	ds_read_b128 v[160:163], v211 offset:16384
	ds_read_b128 v[164:167], v211 offset:17408
	ds_read_b128 v[168:171], v211 offset:18432
	ds_read_b128 v[172:175], v211 offset:19456
	ds_read_b128 v[188:191], v211 offset:20480
	ds_read_b128 v[192:195], v211 offset:21504
	ds_read_b128 v[196:199], v211 offset:22528
	ds_read_b128 v[200:203], v211 offset:23552
	global_load_lds_dwordx4 v[204:205], off
	s_add_i32 m0, s28, 0x2000
	s_add_u32 s28, s36, 0x160000
	v_lshl_add_u64 v[212:213], s[36:37], 0, v[178:179]
	s_addc_u32 s29, s37, 0
	s_add_i32 s51, s45, s14
	global_load_lds_dwordx4 v[212:213], off
	v_lshl_add_u64 v[214:215], s[28:29], 0, v[176:177]
	s_mov_b32 m0, s51
	v_lshl_add_u64 v[216:217], s[40:41], 0, v[178:179]
	global_load_lds_dwordx4 v[214:215], off
	v_lshl_add_u64 v[214:215], s[28:29], 0, v[178:179]
	s_add_i32 m0, s51, 0x2000
	s_nop 0
	global_load_lds_dwordx4 v[214:215], off
	v_lshl_add_u64 v[214:215], s[40:41], 0, v[176:177]
	s_mov_b32 m0, s15
	s_nop 0
	global_load_lds_dwordx4 v[214:215], off
	s_mov_b32 m0, s22
	s_nop 0
	global_load_lds_dwordx4 v[216:217], off
	s_waitcnt vmcnt(8)
	s_waitcnt lgkmcnt(0)
	s_setprio 1
	s_barrier
; #define PG8_STAGE(bufoff, gbase, voff) do { _Pragma("unroll") for (int _i = 0; _i < 2; ++_i) \
;         __builtin_amdgcn_global_load_lds((const unsigned*)((const char*)(gbase) + (voff)[_i]), (PG8_LAS unsigned*)(lds + (bufoff) + ldsw + _i * 8192), 16, 0, 0); } while (0)
; #define PG8_LDA(dst, b, h) do { _Pragma("unroll") for (int m = 0; m < 4; ++m) _Pragma("unroll") for (int k = 0; k < 2; ++k) dst[m][k] = *(const PG8_LAS bf16x8*)(lds + PG8_SA(b, h) + aoff + m * 2048 + k * 1024); } while (0)
; #define PG8_LDB(dst, b, h) do { _Pragma("unroll") for (int n = 0; n < 2; ++n) _Pragma("unroll") for (int k = 0; k < 2; ++k) dst[n][k] = *(const PG8_LAS bf16x8*)(lds + PG8_SB(b, h) + boff + n * 2048 + k * 1024); } while (0)
; #define PG8_MMA(ai, bj, At, Bt) do { __builtin_amdgcn_s_setprio(1); _Pragma("unroll") for (int m = 0; m < 4; ++m) _Pragma("unroll") for (int n = 0; n < 2; ++n) _Pragma("unroll") for (int k = 0; k < 2; ++k) \
;         acc[ai][bj][m][n] = __builtin_amdgcn_mfma_f32_16x16x32_bf16(Bt[n][k], At[m][k], acc[ai][bj][m][n], 0, 0, 0); __builtin_amdgcn_s_setprio(0); } while (0)
; #define PG8_WAIT_V(n) asm volatile("s_waitcnt vmcnt(" #n ")" ::: "memory")
; #define PG8_WAIT_L(n) asm volatile("s_waitcnt lgkmcnt(" #n ")" ::: "memory")
; #define PG8_BAR __builtin_amdgcn_s_barrier()
; #define PG8_SCHED __builtin_amdgcn_sched_barrier(0)
; template <class Epi, class Sched, bool ALIGN_EPI = false, bool SP2 = false>
; __device__ __forceinline__ void gemm_phase(PG8_LAS unsigned char* lds, const Gemm g, const Sched& S, const Epi& E) {
;     ...
;             PG8_WAIT_V(8); PG8_WAIT_L(0); PG8_BAR; PG8_MMA(1, 0, At, B0); PG8_MMA(1, 1, At, B1); PG8_BAR; PG8_SCHED;
;             PG8_LDB(B0, 1, 0); PG8_LDB(B1, 1, 1); PG8_SCHED; PG8_LDA(At, 1, 0); PG8_STAGE(PG8_SA(0, 1), a2 + hstep, voffA);
;             PG8_WAIT_V(8); PG8_WAIT_L(0); PG8_BAR; PG8_MMA(0, 0, At, B0); PG8_MMA(0, 1, At, B1); PG8_BAR; PG8_SCHED;
	v_mfma_f32_16x16x32_bf16 v[60:63], v[128:131], v[160:163], v[60:63]
	v_mfma_f32_16x16x32_bf16 v[56:59], v[136:139], v[160:163], v[56:59]
	v_mfma_f32_16x16x32_bf16 v[44:47], v[128:131], v[168:171], v[44:47]
	v_mfma_f32_16x16x32_bf16 v[40:43], v[136:139], v[168:171], v[40:43]
	v_mfma_f32_16x16x32_bf16 v[28:31], v[128:131], v[188:191], v[28:31]
	v_mfma_f32_16x16x32_bf16 v[24:27], v[136:139], v[188:191], v[24:27]
	v_mfma_f32_16x16x32_bf16 v[12:15], v[128:131], v[196:199], v[12:15]
	v_mfma_f32_16x16x32_bf16 v[8:11], v[136:139], v[196:199], v[8:11]
	v_mfma_f32_16x16x32_bf16 v[60:63], v[132:135], v[164:167], v[60:63]
	v_mfma_f32_16x16x32_bf16 v[56:59], v[140:143], v[164:167], v[56:59]
	v_mfma_f32_16x16x32_bf16 v[44:47], v[132:135], v[172:175], v[44:47]
	v_mfma_f32_16x16x32_bf16 v[40:43], v[140:143], v[172:175], v[40:43]
	v_mfma_f32_16x16x32_bf16 v[28:31], v[132:135], v[192:195], v[28:31]
	v_mfma_f32_16x16x32_bf16 v[24:27], v[140:143], v[192:195], v[24:27]
	v_mfma_f32_16x16x32_bf16 v[12:15], v[132:135], v[200:203], v[12:15]
	v_mfma_f32_16x16x32_bf16 v[8:11], v[140:143], v[200:203], v[8:11]
	v_mfma_f32_16x16x32_bf16 v[52:55], v[144:147], v[160:163], v[52:55]
	v_mfma_f32_16x16x32_bf16 v[48:51], v[152:155], v[160:163], v[48:51]
	v_mfma_f32_16x16x32_bf16 v[36:39], v[144:147], v[168:171], v[36:39]
	v_mfma_f32_16x16x32_bf16 v[32:35], v[152:155], v[168:171], v[32:35]
	v_mfma_f32_16x16x32_bf16 v[20:23], v[144:147], v[188:191], v[20:23]
	v_mfma_f32_16x16x32_bf16 v[16:19], v[152:155], v[188:191], v[16:19]
	v_mfma_f32_16x16x32_bf16 v[4:7], v[144:147], v[196:199], v[4:7]
	v_mfma_f32_16x16x32_bf16 v[0:3], v[152:155], v[196:199], v[0:3]
	v_mfma_f32_16x16x32_bf16 v[52:55], v[148:151], v[164:167], v[52:55]
	v_mfma_f32_16x16x32_bf16 v[48:51], v[156:159], v[164:167], v[48:51]
	v_mfma_f32_16x16x32_bf16 v[36:39], v[148:151], v[172:175], v[36:39]
	v_mfma_f32_16x16x32_bf16 v[32:35], v[156:159], v[172:175], v[32:35]
	v_mfma_f32_16x16x32_bf16 v[20:23], v[148:151], v[192:195], v[20:23]
	v_mfma_f32_16x16x32_bf16 v[16:19], v[156:159], v[192:195], v[16:19]
	v_mfma_f32_16x16x32_bf16 v[4:7], v[148:151], v[200:203], v[4:7]
	v_mfma_f32_16x16x32_bf16 v[0:3], v[156:159], v[200:203], v[0:3]
	s_barrier
	s_setprio 0
	s_add_i32 s51, 0, 0x18000
	s_add_i32 s52, 0, 0x1c000
	v_add_u32_e32 v140, s51, v207
	v_add_u32_e32 v156, s52, v207
	ds_read_b128 v[128:131], v140
	ds_read_b128 v[132:135], v140 offset:1024
	ds_read_b128 v[136:139], v140 offset:2048
	ds_read_b128 v[140:143], v140 offset:3072
	ds_read_b128 v[144:147], v156
	ds_read_b128 v[148:151], v156 offset:1024
	ds_read_b128 v[152:155], v156 offset:2048
	ds_read_b128 v[156:159], v156 offset:3072
	s_add_u32 s28, s40, 0x160000
	s_addc_u32 s29, s41, 0
	s_mov_b32 m0, s23
	v_lshl_add_u64 v[218:219], s[28:29], 0, v[176:177]
	ds_read_b128 v[160:163], v211 offset:32768
	ds_read_b128 v[164:167], v211 offset:33792
	ds_read_b128 v[168:171], v211 offset:34816
	ds_read_b128 v[172:175], v211 offset:35840
	ds_read_b128 v[188:191], v211 offset:36864
	ds_read_b128 v[192:195], v211 offset:37888
	ds_read_b128 v[196:199], v211 offset:38912
	ds_read_b128 v[200:203], v211 offset:39936
	global_load_lds_dwordx4 v[218:219], off
	v_lshl_add_u64 v[218:219], s[28:29], 0, v[178:179]
	s_mov_b32 m0, s34
	s_nop 0
	global_load_lds_dwordx4 v[218:219], off
	s_waitcnt vmcnt(8)
	s_waitcnt lgkmcnt(0)
	s_setprio 1
	s_barrier
	v_mfma_f32_16x16x32_bf16 v[124:127], v[128:131], v[160:163], v[124:127]
	v_mfma_f32_16x16x32_bf16 v[120:123], v[136:139], v[160:163], v[120:123]
	v_mfma_f32_16x16x32_bf16 v[108:111], v[128:131], v[168:171], v[108:111]
	v_mfma_f32_16x16x32_bf16 v[104:107], v[136:139], v[168:171], v[104:107]
	v_mfma_f32_16x16x32_bf16 v[92:95], v[128:131], v[188:191], v[92:95]
	v_mfma_f32_16x16x32_bf16 v[88:91], v[136:139], v[188:191], v[88:91]
	v_mfma_f32_16x16x32_bf16 v[76:79], v[128:131], v[196:199], v[76:79]
	v_mfma_f32_16x16x32_bf16 v[72:75], v[136:139], v[196:199], v[72:75]
	v_mfma_f32_16x16x32_bf16 v[124:127], v[132:135], v[164:167], v[124:127]
	v_mfma_f32_16x16x32_bf16 v[120:123], v[140:143], v[164:167], v[120:123]
	v_mfma_f32_16x16x32_bf16 v[108:111], v[132:135], v[172:175], v[108:111]
	v_mfma_f32_16x16x32_bf16 v[104:107], v[140:143], v[172:175], v[104:107]
	v_mfma_f32_16x16x32_bf16 v[92:95], v[132:135], v[192:195], v[92:95]
	v_mfma_f32_16x16x32_bf16 v[88:91], v[140:143], v[192:195], v[88:91]
	v_mfma_f32_16x16x32_bf16 v[76:79], v[132:135], v[200:203], v[76:79]
	v_mfma_f32_16x16x32_bf16 v[72:75], v[140:143], v[200:203], v[72:75]
	v_mfma_f32_16x16x32_bf16 v[116:119], v[144:147], v[160:163], v[116:119]
	v_mfma_f32_16x16x32_bf16 v[112:115], v[152:155], v[160:163], v[112:115]
	v_mfma_f32_16x16x32_bf16 v[100:103], v[144:147], v[168:171], v[100:103]
	v_mfma_f32_16x16x32_bf16 v[96:99], v[152:155], v[168:171], v[96:99]
	v_mfma_f32_16x16x32_bf16 v[84:87], v[144:147], v[188:191], v[84:87]
	v_mfma_f32_16x16x32_bf16 v[80:83], v[152:155], v[188:191], v[80:83]
	v_mfma_f32_16x16x32_bf16 v[68:71], v[144:147], v[196:199], v[68:71]
	v_mfma_f32_16x16x32_bf16 v[64:67], v[152:155], v[196:199], v[64:67]
	v_mfma_f32_16x16x32_bf16 v[116:119], v[148:151], v[164:167], v[116:119]
	v_mfma_f32_16x16x32_bf16 v[112:115], v[156:159], v[164:167], v[112:115]
	v_mfma_f32_16x16x32_bf16 v[100:103], v[148:151], v[172:175], v[100:103]
	v_mfma_f32_16x16x32_bf16 v[96:99], v[156:159], v[172:175], v[96:99]
	v_mfma_f32_16x16x32_bf16 v[84:87], v[148:151], v[192:195], v[84:87]
	v_mfma_f32_16x16x32_bf16 v[80:83], v[156:159], v[192:195], v[80:83]
	v_mfma_f32_16x16x32_bf16 v[68:71], v[148:151], v[200:203], v[68:71]
	v_mfma_f32_16x16x32_bf16 v[64:67], v[156:159], v[200:203], v[64:67]
	s_barrier
; #define PG8_STAGE(bufoff, gbase, voff) do { _Pragma("unroll") for (int _i = 0; _i < 2; ++_i) \
;         __builtin_amdgcn_global_load_lds((const unsigned*)((const char*)(gbase) + (voff)[_i]), (PG8_LAS unsigned*)(lds + (bufoff) + ldsw + _i * 8192), 16, 0, 0); } while (0)
; #define PG8_LDA(dst, b, h) do { _Pragma("unroll") for (int m = 0; m < 4; ++m) _Pragma("unroll") for (int k = 0; k < 2; ++k) dst[m][k] = *(const PG8_LAS bf16x8*)(lds + PG8_SA(b, h) + aoff + m * 2048 + k * 1024); } while (0)
; #define PG8_MMA(ai, bj, At, Bt) do { __builtin_amdgcn_s_setprio(1); _Pragma("unroll") for (int m = 0; m < 4; ++m) _Pragma("unroll") for (int n = 0; n < 2; ++n) _Pragma("unroll") for (int k = 0; k < 2; ++k) \
;         acc[ai][bj][m][n] = __builtin_amdgcn_mfma_f32_16x16x32_bf16(Bt[n][k], At[m][k], acc[ai][bj][m][n], 0, 0, 0); __builtin_amdgcn_s_setprio(0); } while (0)
; #define PG8_WAIT_V(n) asm volatile("s_waitcnt vmcnt(" #n ")" ::: "memory")
; #define PG8_WAIT_L(n) asm volatile("s_waitcnt lgkmcnt(" #n ")" ::: "memory")
; #define PG8_BAR __builtin_amdgcn_s_barrier()
; #define PG8_SCHED __builtin_amdgcn_sched_barrier(0)
; template <class Epi, class Sched, bool ALIGN_EPI = false, bool SP2 = false>
; __device__ __forceinline__ void gemm_phase(PG8_LAS unsigned char* lds, const Gemm g, const Sched& S, const Epi& E) {
;     ...
;             PG8_LDA(At, 1, 1); PG8_STAGE(PG8_SB(1, 0), b3, voffB); PG8_STAGE(PG8_SB(1, 1), b3 + hstep, voffB); PG8_STAGE(PG8_SA(1, 0), a3, voffA);
;             PG8_WAIT_V(8); PG8_WAIT_L(0); PG8_BAR; PG8_MMA(1, 0, At, B0); PG8_MMA(1, 1, At, B1); PG8_BAR; PG8_SCHED;
;     ...
;         }
;         if constexpr (ALIGN_EPI) { if (wr == 0) PG8_BAR; }
	s_setprio 0
	s_add_i32 s28, s51, s14
	v_lshl_add_u64 v[204:205], v[204:205], 0, s[20:21]
	s_mov_b32 m0, s28
	ds_read_b128 v[160:163], v211 offset:49152
	ds_read_b128 v[164:167], v211 offset:50176
	ds_read_b128 v[168:171], v211 offset:51200
	ds_read_b128 v[172:175], v211 offset:52224
	ds_read_b128 v[188:191], v211 offset:53248
	ds_read_b128 v[192:195], v211 offset:54272
	ds_read_b128 v[196:199], v211 offset:55296
	ds_read_b128 v[200:203], v211 offset:56320
	global_load_lds_dwordx4 v[204:205], off
	s_add_i32 m0, s28, 0x2000
	s_add_u32 s28, s36, 0x160080
	v_lshl_add_u64 v[204:205], v[212:213], 0, s[20:21]
	s_addc_u32 s29, s37, 0
	s_add_i32 s36, s52, s14
	global_load_lds_dwordx4 v[204:205], off
	v_lshl_add_u64 v[204:205], s[28:29], 0, v[176:177]
	s_mov_b32 m0, s36
	s_nop 0
	global_load_lds_dwordx4 v[204:205], off
	v_lshl_add_u64 v[204:205], s[28:29], 0, v[178:179]
	s_add_i32 m0, s36, 0x2000
	s_nop 0
	global_load_lds_dwordx4 v[204:205], off
	v_lshl_add_u64 v[204:205], v[214:215], 0, s[20:21]
	s_mov_b32 m0, s42
	s_nop 0
	global_load_lds_dwordx4 v[204:205], off
	v_lshl_add_u64 v[204:205], v[216:217], 0, s[20:21]
	s_mov_b32 m0, s43
	s_nop 0
	global_load_lds_dwordx4 v[204:205], off
	s_waitcnt vmcnt(8)
	s_waitcnt lgkmcnt(0)
	s_setprio 1
	s_barrier
	v_mfma_f32_16x16x32_bf16 v[60:63], v[128:131], v[160:163], v[60:63]
	v_mfma_f32_16x16x32_bf16 v[56:59], v[136:139], v[160:163], v[56:59]
	v_mfma_f32_16x16x32_bf16 v[44:47], v[128:131], v[168:171], v[44:47]
	v_mfma_f32_16x16x32_bf16 v[40:43], v[136:139], v[168:171], v[40:43]
	v_mfma_f32_16x16x32_bf16 v[28:31], v[128:131], v[188:191], v[28:31]
	v_mfma_f32_16x16x32_bf16 v[24:27], v[136:139], v[188:191], v[24:27]
	v_mfma_f32_16x16x32_bf16 v[12:15], v[128:131], v[196:199], v[12:15]
	v_mfma_f32_16x16x32_bf16 v[8:11], v[136:139], v[196:199], v[8:11]
	v_mfma_f32_16x16x32_bf16 v[60:63], v[132:135], v[164:167], v[60:63]
	v_mfma_f32_16x16x32_bf16 v[56:59], v[140:143], v[164:167], v[56:59]
	v_mfma_f32_16x16x32_bf16 v[44:47], v[132:135], v[172:175], v[44:47]
	v_mfma_f32_16x16x32_bf16 v[40:43], v[140:143], v[172:175], v[40:43]
	v_mfma_f32_16x16x32_bf16 v[28:31], v[132:135], v[192:195], v[28:31]
	v_mfma_f32_16x16x32_bf16 v[24:27], v[140:143], v[192:195], v[24:27]
	v_mfma_f32_16x16x32_bf16 v[12:15], v[132:135], v[200:203], v[12:15]
	v_mfma_f32_16x16x32_bf16 v[8:11], v[140:143], v[200:203], v[8:11]
	v_mfma_f32_16x16x32_bf16 v[52:55], v[144:147], v[160:163], v[52:55]
	v_mfma_f32_16x16x32_bf16 v[48:51], v[152:155], v[160:163], v[48:51]
	v_mfma_f32_16x16x32_bf16 v[36:39], v[144:147], v[168:171], v[36:39]
	v_mfma_f32_16x16x32_bf16 v[32:35], v[152:155], v[168:171], v[32:35]
	v_mfma_f32_16x16x32_bf16 v[20:23], v[144:147], v[188:191], v[20:23]
	v_mfma_f32_16x16x32_bf16 v[16:19], v[152:155], v[188:191], v[16:19]
	v_mfma_f32_16x16x32_bf16 v[4:7], v[144:147], v[196:199], v[4:7]
	v_mfma_f32_16x16x32_bf16 v[0:3], v[152:155], v[196:199], v[0:3]
	v_mfma_f32_16x16x32_bf16 v[52:55], v[148:151], v[164:167], v[52:55]
	v_mfma_f32_16x16x32_bf16 v[48:51], v[156:159], v[164:167], v[48:51]
	v_mfma_f32_16x16x32_bf16 v[36:39], v[148:151], v[172:175], v[36:39]
	v_mfma_f32_16x16x32_bf16 v[32:35], v[156:159], v[172:175], v[32:35]
	v_mfma_f32_16x16x32_bf16 v[20:23], v[148:151], v[192:195], v[20:23]
	v_mfma_f32_16x16x32_bf16 v[16:19], v[156:159], v[192:195], v[16:19]
	v_mfma_f32_16x16x32_bf16 v[4:7], v[148:151], v[200:203], v[4:7]
	v_mfma_f32_16x16x32_bf16 v[0:3], v[156:159], v[200:203], v[0:3]
	s_barrier
	s_setprio 0
	s_add_i32 s50, s50, 2
	s_add_u32 s13, s13, 0x100
	s_addc_u32 s49, s49, 0
	s_cmpk_gt_u32 s50, 0x55
	s_mov_b64 s[28:29], s[30:31]
	s_cbranch_scc0 .LBB0_1108
	s_and_b64 vcc, exec, s[24:25]
	s_cbranch_vccz .LBB0_1111
	s_barrier

; #define PG8_STAGE(bufoff, gbase, voff) do { _Pragma("unroll") for (int _i = 0; _i < 2; ++_i) \
;         __builtin_amdgcn_global_load_lds((const unsigned*)((const char*)(gbase) + (voff)[_i]), (PG8_LAS unsigned*)(lds + (bufoff) + ldsw + _i * 8192), 16, 0, 0); } while (0)
; #define PG8_LDA(dst, b, h) do { _Pragma("unroll") for (int m = 0; m < 4; ++m) _Pragma("unroll") for (int k = 0; k < 2; ++k) dst[m][k] = *(const PG8_LAS bf16x8*)(lds + PG8_SA(b, h) + aoff + m * 2048 + k * 1024); } while (0)
; #define PG8_LDB(dst, b, h) do { _Pragma("unroll") for (int n = 0; n < 2; ++n) _Pragma("unroll") for (int k = 0; k < 2; ++k) dst[n][k] = *(const PG8_LAS bf16x8*)(lds + PG8_SB(b, h) + boff + n * 2048 + k * 1024); } while (0)
; #define PG8_MMA(ai, bj, At, Bt) do { __builtin_amdgcn_s_setprio(1); _Pragma("unroll") for (int m = 0; m < 4; ++m) _Pragma("unroll") for (int n = 0; n < 2; ++n) _Pragma("unroll") for (int k = 0; k < 2; ++k) \
;         acc[ai][bj][m][n] = __builtin_amdgcn_mfma_f32_16x16x32_bf16(Bt[n][k], At[m][k], acc[ai][bj][m][n], 0, 0, 0); __builtin_amdgcn_s_setprio(0); } while (0)
; #define PG8_WAIT_V(n) asm volatile("s_waitcnt vmcnt(" #n ")" ::: "memory")
; #define PG8_WAIT_L(n) asm volatile("s_waitcnt lgkmcnt(" #n ")" ::: "memory")
; #define PG8_BAR __builtin_amdgcn_s_barrier()
; #define PG8_SCHED __builtin_amdgcn_sched_barrier(0)
; template <class Epi, class Sched, bool ALIGN_EPI = false, bool SP2 = false>
; __device__ __forceinline__ void gemm_phase(PG8_LAS unsigned char* lds, const Gemm g, const Sched& S, const Epi& E) {
;     ...
;             const bool last = (t == nt - 2);
;             const char* a1 = cA + (size_t)(t + 1) * kstep;
;             const char* a2 = last ? nA : cA + (size_t)(t + 2) * kstep; const char* b2 = last ? nB : cB + (size_t)(t + 2) * kstep;
;     ...
;             PG8_LDB(B0, 0, 0); PG8_LDB(B1, 0, 1); PG8_SCHED; PG8_LDA(At, 0, 0); PG8_STAGE(PG8_SA(1, 1), a1 + hstep, voffA);
;             PG8_WAIT_V(8); PG8_WAIT_L(0); PG8_BAR; PG8_MMA(0, 0, At, B0); PG8_MMA(0, 1, At, B1); PG8_BAR; PG8_SCHED;
;             PG8_LDA(At, 0, 1); PG8_STAGE(PG8_SB(0, 0), b2, voffB); PG8_STAGE(PG8_SB(0, 1), b2 + hstep, voffB); PG8_STAGE(PG8_SA(0, 0), a2, voffA);
;             PG8_WAIT_V(8); PG8_WAIT_L(0); PG8_BAR; PG8_MMA(1, 0, At, B0); PG8_MMA(1, 1, At, B1); PG8_BAR; PG8_SCHED;
.LBB0_1205:
	v_add_u32_e32 v147, s40, v145
	ds_read_b128 v[148:151], v147
	ds_read_b128 v[152:155], v147 offset:1024
	ds_read_b128 v[156:159], v147 offset:2048
	ds_read_b128 v[160:163], v147 offset:3072
	v_add_u32_e32 v147, s41, v145
	s_add_u32 s20, s10, s18
	ds_read_b128 v[164:167], v147
	ds_read_b128 v[168:171], v147 offset:1024
	ds_read_b128 v[172:175], v147 offset:2048
	ds_read_b128 v[176:179], v147 offset:3072
	s_addc_u32 s21, s11, s19
	s_add_u32 s20, s20, 0x100
	s_addc_u32 s21, s21, 0
	s_add_u32 s46, s15, s18
	s_addc_u32 s47, s44, s19
	s_cmpk_eq_i32 s18, 0x2b00
	s_cselect_b32 s23, s17, s21
	s_cselect_b32 s22, s16, s20
	s_cselect_b32 s21, s7, s47
	s_cselect_b32 s20, s6, s46
	v_lshl_add_u64 v[180:181], v[140:141], 0, s[18:19]
	s_add_i32 m0, s28, 0xc000
	ds_read_b128 v[184:187], v146
	ds_read_b128 v[188:191], v146 offset:1024
	ds_read_b128 v[192:195], v146 offset:2048
	ds_read_b128 v[196:199], v146 offset:3072
	ds_read_b128 v[200:203], v146 offset:4096
	ds_read_b128 v[204:207], v146 offset:5120
	ds_read_b128 v[208:211], v146 offset:6144
	ds_read_b128 v[212:215], v146 offset:7168
	global_load_lds_dwordx4 v[180:181], off
	v_lshl_add_u64 v[180:181], v[142:143], 0, s[18:19]
	s_add_i32 m0, s28, 0xe000
	s_nop 0
	global_load_lds_dwordx4 v[180:181], off
	s_waitcnt vmcnt(8)
	s_waitcnt lgkmcnt(0)
	s_setprio 1
	s_barrier
	v_mfma_f32_16x16x32_bf16 v[124:127], v[148:151], v[184:187], v[124:127]
	v_mfma_f32_16x16x32_bf16 v[120:123], v[156:159], v[184:187], v[120:123]
	v_mfma_f32_16x16x32_bf16 v[108:111], v[148:151], v[192:195], v[108:111]
	v_mfma_f32_16x16x32_bf16 v[104:107], v[156:159], v[192:195], v[104:107]
	v_mfma_f32_16x16x32_bf16 v[96:99], v[148:151], v[200:203], v[96:99]
	v_mfma_f32_16x16x32_bf16 v[88:91], v[156:159], v[200:203], v[88:91]
	v_mfma_f32_16x16x32_bf16 v[80:83], v[148:151], v[208:211], v[80:83]
	v_mfma_f32_16x16x32_bf16 v[72:75], v[156:159], v[208:211], v[72:75]
	v_mfma_f32_16x16x32_bf16 v[124:127], v[152:155], v[188:191], v[124:127]
	v_mfma_f32_16x16x32_bf16 v[120:123], v[160:163], v[188:191], v[120:123]
	v_mfma_f32_16x16x32_bf16 v[108:111], v[152:155], v[196:199], v[108:111]
	v_mfma_f32_16x16x32_bf16 v[104:107], v[160:163], v[196:199], v[104:107]
	v_mfma_f32_16x16x32_bf16 v[96:99], v[152:155], v[204:207], v[96:99]
	v_mfma_f32_16x16x32_bf16 v[88:91], v[160:163], v[204:207], v[88:91]
	v_mfma_f32_16x16x32_bf16 v[80:83], v[152:155], v[212:215], v[80:83]
	v_mfma_f32_16x16x32_bf16 v[72:75], v[160:163], v[212:215], v[72:75]
	v_mfma_f32_16x16x32_bf16 v[116:119], v[164:167], v[184:187], v[116:119]
	v_mfma_f32_16x16x32_bf16 v[112:115], v[172:175], v[184:187], v[112:115]
	v_mfma_f32_16x16x32_bf16 v[100:103], v[164:167], v[192:195], v[100:103]
	v_mfma_f32_16x16x32_bf16 v[92:95], v[172:175], v[192:195], v[92:95]
	v_mfma_f32_16x16x32_bf16 v[84:87], v[164:167], v[200:203], v[84:87]
	v_mfma_f32_16x16x32_bf16 v[76:79], v[172:175], v[200:203], v[76:79]
	v_mfma_f32_16x16x32_bf16 v[68:71], v[164:167], v[208:211], v[68:71]
	v_mfma_f32_16x16x32_bf16 v[64:67], v[172:175], v[208:211], v[64:67]
	v_mfma_f32_16x16x32_bf16 v[116:119], v[168:171], v[188:191], v[116:119]
	v_mfma_f32_16x16x32_bf16 v[112:115], v[176:179], v[188:191], v[112:115]
	v_mfma_f32_16x16x32_bf16 v[100:103], v[168:171], v[196:199], v[100:103]
	v_mfma_f32_16x16x32_bf16 v[92:95], v[176:179], v[196:199], v[92:95]
	v_mfma_f32_16x16x32_bf16 v[84:87], v[168:171], v[204:207], v[84:87]
	v_mfma_f32_16x16x32_bf16 v[76:79], v[176:179], v[204:207], v[76:79]
	v_mfma_f32_16x16x32_bf16 v[68:71], v[168:171], v[212:215], v[68:71]
	v_mfma_f32_16x16x32_bf16 v[64:67], v[176:179], v[212:215], v[64:67]
	s_barrier
	s_setprio 0
	s_add_i32 s46, s40, s27
	v_lshl_add_u64 v[180:181], s[20:21], 0, v[130:131]
	s_mov_b32 m0, s46
	ds_read_b128 v[184:187], v146 offset:16384
	ds_read_b128 v[188:191], v146 offset:17408
	ds_read_b128 v[192:195], v146 offset:18432
	ds_read_b128 v[196:199], v146 offset:19456
	ds_read_b128 v[200:203], v146 offset:20480
	ds_read_b128 v[204:207], v146 offset:21504
	ds_read_b128 v[208:211], v146 offset:22528
	ds_read_b128 v[212:215], v146 offset:23552
	global_load_lds_dwordx4 v[180:181], off
	s_add_i32 m0, s46, 0x2000
	s_add_u32 s46, s20, 0x160000
	v_lshl_add_u64 v[216:217], s[20:21], 0, v[128:129]
	s_addc_u32 s47, s21, 0
	s_add_i32 s48, s41, s27
	global_load_lds_dwordx4 v[216:217], off
	v_lshl_add_u64 v[218:219], s[46:47], 0, v[130:131]
	s_mov_b32 m0, s48
	v_lshl_add_u64 v[220:221], s[22:23], 0, v[128:129]
	global_load_lds_dwordx4 v[218:219], off
	v_lshl_add_u64 v[218:219], s[46:47], 0, v[128:129]
	s_add_i32 m0, s48, 0x2000
	s_nop 0
	global_load_lds_dwordx4 v[218:219], off
	v_lshl_add_u64 v[218:219], s[22:23], 0, v[130:131]
	s_mov_b32 m0, s28
	s_nop 0
	global_load_lds_dwordx4 v[218:219], off
	s_mov_b32 m0, s29
	s_nop 0
	global_load_lds_dwordx4 v[220:221], off
	s_waitcnt vmcnt(8)
	s_waitcnt lgkmcnt(0)
	s_setprio 1
	s_barrier
; #define PG8_STAGE(bufoff, gbase, voff) do { _Pragma("unroll") for (int _i = 0; _i < 2; ++_i) \
;         __builtin_amdgcn_global_load_lds((const unsigned*)((const char*)(gbase) + (voff)[_i]), (PG8_LAS unsigned*)(lds + (bufoff) + ldsw + _i * 8192), 16, 0, 0); } while (0)
; #define PG8_LDA(dst, b, h) do { _Pragma("unroll") for (int m = 0; m < 4; ++m) _Pragma("unroll") for (int k = 0; k < 2; ++k) dst[m][k] = *(const PG8_LAS bf16x8*)(lds + PG8_SA(b, h) + aoff + m * 2048 + k * 1024); } while (0)
; #define PG8_LDB(dst, b, h) do { _Pragma("unroll") for (int n = 0; n < 2; ++n) _Pragma("unroll") for (int k = 0; k < 2; ++k) dst[n][k] = *(const PG8_LAS bf16x8*)(lds + PG8_SB(b, h) + boff + n * 2048 + k * 1024); } while (0)
; #define PG8_MMA(ai, bj, At, Bt) do { __builtin_amdgcn_s_setprio(1); _Pragma("unroll") for (int m = 0; m < 4; ++m) _Pragma("unroll") for (int n = 0; n < 2; ++n) _Pragma("unroll") for (int k = 0; k < 2; ++k) \
;         acc[ai][bj][m][n] = __builtin_amdgcn_mfma_f32_16x16x32_bf16(Bt[n][k], At[m][k], acc[ai][bj][m][n], 0, 0, 0); __builtin_amdgcn_s_setprio(0); } while (0)
; #define PG8_WAIT_V(n) asm volatile("s_waitcnt vmcnt(" #n ")" ::: "memory")
; #define PG8_WAIT_L(n) asm volatile("s_waitcnt lgkmcnt(" #n ")" ::: "memory")
; #define PG8_BAR __builtin_amdgcn_s_barrier()
; #define PG8_SCHED __builtin_amdgcn_sched_barrier(0)
; template <class Epi, class Sched, bool ALIGN_EPI = false, bool SP2 = false>
; __device__ __forceinline__ void gemm_phase(PG8_LAS unsigned char* lds, const Gemm g, const Sched& S, const Epi& E) {
;     ...
;             PG8_WAIT_V(8); PG8_WAIT_L(0); PG8_BAR; PG8_MMA(1, 0, At, B0); PG8_MMA(1, 1, At, B1); PG8_BAR; PG8_SCHED;
;             PG8_LDB(B0, 1, 0); PG8_LDB(B1, 1, 1); PG8_SCHED; PG8_LDA(At, 1, 0); PG8_STAGE(PG8_SA(0, 1), a2 + hstep, voffA);
;             PG8_WAIT_V(8); PG8_WAIT_L(0); PG8_BAR; PG8_MMA(0, 0, At, B0); PG8_MMA(0, 1, At, B1); PG8_BAR; PG8_SCHED;
	v_mfma_f32_16x16x32_bf16 v[56:59], v[148:151], v[184:187], v[56:59]
	v_mfma_f32_16x16x32_bf16 v[60:63], v[156:159], v[184:187], v[60:63]
	v_mfma_f32_16x16x32_bf16 v[44:47], v[148:151], v[192:195], v[44:47]
	v_mfma_f32_16x16x32_bf16 v[40:43], v[156:159], v[192:195], v[40:43]
	v_mfma_f32_16x16x32_bf16 v[32:35], v[148:151], v[200:203], v[32:35]
	v_mfma_f32_16x16x32_bf16 v[24:27], v[156:159], v[200:203], v[24:27]
	v_mfma_f32_16x16x32_bf16 v[16:19], v[148:151], v[208:211], v[16:19]
	v_mfma_f32_16x16x32_bf16 v[8:11], v[156:159], v[208:211], v[8:11]
	v_mfma_f32_16x16x32_bf16 v[56:59], v[152:155], v[188:191], v[56:59]
	v_mfma_f32_16x16x32_bf16 v[60:63], v[160:163], v[188:191], v[60:63]
	v_mfma_f32_16x16x32_bf16 v[44:47], v[152:155], v[196:199], v[44:47]
	v_mfma_f32_16x16x32_bf16 v[40:43], v[160:163], v[196:199], v[40:43]
	v_mfma_f32_16x16x32_bf16 v[32:35], v[152:155], v[204:207], v[32:35]
	v_mfma_f32_16x16x32_bf16 v[24:27], v[160:163], v[204:207], v[24:27]
	v_mfma_f32_16x16x32_bf16 v[16:19], v[152:155], v[212:215], v[16:19]
	v_mfma_f32_16x16x32_bf16 v[8:11], v[160:163], v[212:215], v[8:11]
	v_mfma_f32_16x16x32_bf16 v[52:55], v[164:167], v[184:187], v[52:55]
	v_mfma_f32_16x16x32_bf16 v[48:51], v[172:175], v[184:187], v[48:51]
	v_mfma_f32_16x16x32_bf16 v[36:39], v[164:167], v[192:195], v[36:39]
	v_mfma_f32_16x16x32_bf16 v[28:31], v[172:175], v[192:195], v[28:31]
	v_mfma_f32_16x16x32_bf16 v[20:23], v[164:167], v[200:203], v[20:23]
	v_mfma_f32_16x16x32_bf16 v[12:15], v[172:175], v[200:203], v[12:15]
	v_mfma_f32_16x16x32_bf16 v[4:7], v[164:167], v[208:211], v[4:7]
	v_mfma_f32_16x16x32_bf16 v[0:3], v[172:175], v[208:211], v[0:3]
	v_mfma_f32_16x16x32_bf16 v[52:55], v[168:171], v[188:191], v[52:55]
	v_mfma_f32_16x16x32_bf16 v[48:51], v[176:179], v[188:191], v[48:51]
	v_mfma_f32_16x16x32_bf16 v[36:39], v[168:171], v[196:199], v[36:39]
	v_mfma_f32_16x16x32_bf16 v[28:31], v[176:179], v[196:199], v[28:31]
	v_mfma_f32_16x16x32_bf16 v[20:23], v[168:171], v[204:207], v[20:23]
	v_mfma_f32_16x16x32_bf16 v[12:15], v[176:179], v[204:207], v[12:15]
	v_mfma_f32_16x16x32_bf16 v[4:7], v[168:171], v[212:215], v[4:7]
	v_mfma_f32_16x16x32_bf16 v[0:3], v[176:179], v[212:215], v[0:3]
	s_barrier
	s_setprio 0
	s_add_i32 s46, 0, 0x18000
	v_add_u32_e32 v147, s46, v145
	s_add_i32 s47, 0, 0x1c000
	ds_read_b128 v[148:151], v147
	ds_read_b128 v[152:155], v147 offset:1024
	ds_read_b128 v[156:159], v147 offset:2048
	ds_read_b128 v[160:163], v147 offset:3072
	v_add_u32_e32 v147, s47, v145
	ds_read_b128 v[164:167], v147
	ds_read_b128 v[168:171], v147 offset:1024
	ds_read_b128 v[172:175], v147 offset:2048
	ds_read_b128 v[176:179], v147 offset:3072
	s_add_u32 s22, s22, 0x160000
	s_addc_u32 s23, s23, 0
	s_mov_b32 m0, s30
	v_lshl_add_u64 v[226:227], s[22:23], 0, v[130:131]
	ds_read_b128 v[184:187], v146 offset:32768
	ds_read_b128 v[188:191], v146 offset:33792
	ds_read_b128 v[192:195], v146 offset:34816
	ds_read_b128 v[196:199], v146 offset:35840
	ds_read_b128 v[200:203], v146 offset:36864
	ds_read_b128 v[204:207], v146 offset:37888
	ds_read_b128 v[208:211], v146 offset:38912
	ds_read_b128 v[212:215], v146 offset:39936
	global_load_lds_dwordx4 v[226:227], off
	v_lshl_add_u64 v[226:227], s[22:23], 0, v[128:129]
	s_mov_b32 m0, s31
	s_nop 0
	global_load_lds_dwordx4 v[226:227], off
	s_waitcnt vmcnt(8)
	s_waitcnt lgkmcnt(0)
	s_setprio 1
	s_barrier
	v_mfma_f32_16x16x32_bf16 v[124:127], v[148:151], v[184:187], v[124:127]
	v_mfma_f32_16x16x32_bf16 v[120:123], v[156:159], v[184:187], v[120:123]
	v_mfma_f32_16x16x32_bf16 v[108:111], v[148:151], v[192:195], v[108:111]
	v_mfma_f32_16x16x32_bf16 v[104:107], v[156:159], v[192:195], v[104:107]
	v_mfma_f32_16x16x32_bf16 v[96:99], v[148:151], v[200:203], v[96:99]
	v_mfma_f32_16x16x32_bf16 v[88:91], v[156:159], v[200:203], v[88:91]
	v_mfma_f32_16x16x32_bf16 v[80:83], v[148:151], v[208:211], v[80:83]
	v_mfma_f32_16x16x32_bf16 v[72:75], v[156:159], v[208:211], v[72:75]
	v_mfma_f32_16x16x32_bf16 v[124:127], v[152:155], v[188:191], v[124:127]
	v_mfma_f32_16x16x32_bf16 v[120:123], v[160:163], v[188:191], v[120:123]
	v_mfma_f32_16x16x32_bf16 v[108:111], v[152:155], v[196:199], v[108:111]
	v_mfma_f32_16x16x32_bf16 v[104:107], v[160:163], v[196:199], v[104:107]
	v_mfma_f32_16x16x32_bf16 v[96:99], v[152:155], v[204:207], v[96:99]
	v_mfma_f32_16x16x32_bf16 v[88:91], v[160:163], v[204:207], v[88:91]
	v_mfma_f32_16x16x32_bf16 v[80:83], v[152:155], v[212:215], v[80:83]
	v_mfma_f32_16x16x32_bf16 v[72:75], v[160:163], v[212:215], v[72:75]
	v_mfma_f32_16x16x32_bf16 v[116:119], v[164:167], v[184:187], v[116:119]
	v_mfma_f32_16x16x32_bf16 v[112:115], v[172:175], v[184:187], v[112:115]
	v_mfma_f32_16x16x32_bf16 v[100:103], v[164:167], v[192:195], v[100:103]
	v_mfma_f32_16x16x32_bf16 v[92:95], v[172:175], v[192:195], v[92:95]
	v_mfma_f32_16x16x32_bf16 v[84:87], v[164:167], v[200:203], v[84:87]
	v_mfma_f32_16x16x32_bf16 v[76:79], v[172:175], v[200:203], v[76:79]
	v_mfma_f32_16x16x32_bf16 v[68:71], v[164:167], v[208:211], v[68:71]
	v_mfma_f32_16x16x32_bf16 v[64:67], v[172:175], v[208:211], v[64:67]
	v_mfma_f32_16x16x32_bf16 v[116:119], v[168:171], v[188:191], v[116:119]
	v_mfma_f32_16x16x32_bf16 v[112:115], v[176:179], v[188:191], v[112:115]
	v_mfma_f32_16x16x32_bf16 v[100:103], v[168:171], v[196:199], v[100:103]
	v_mfma_f32_16x16x32_bf16 v[92:95], v[176:179], v[196:199], v[92:95]
	v_mfma_f32_16x16x32_bf16 v[84:87], v[168:171], v[204:207], v[84:87]
	v_mfma_f32_16x16x32_bf16 v[76:79], v[176:179], v[204:207], v[76:79]
	v_mfma_f32_16x16x32_bf16 v[68:71], v[168:171], v[212:215], v[68:71]
	v_mfma_f32_16x16x32_bf16 v[64:67], v[176:179], v[212:215], v[64:67]
	s_barrier
; #define PG8_STAGE(bufoff, gbase, voff) do { _Pragma("unroll") for (int _i = 0; _i < 2; ++_i) \
;         __builtin_amdgcn_global_load_lds((const unsigned*)((const char*)(gbase) + (voff)[_i]), (PG8_LAS unsigned*)(lds + (bufoff) + ldsw + _i * 8192), 16, 0, 0); } while (0)
; #define PG8_LDA(dst, b, h) do { _Pragma("unroll") for (int m = 0; m < 4; ++m) _Pragma("unroll") for (int k = 0; k < 2; ++k) dst[m][k] = *(const PG8_LAS bf16x8*)(lds + PG8_SA(b, h) + aoff + m * 2048 + k * 1024); } while (0)
; #define PG8_MMA(ai, bj, At, Bt) do { __builtin_amdgcn_s_setprio(1); _Pragma("unroll") for (int m = 0; m < 4; ++m) _Pragma("unroll") for (int n = 0; n < 2; ++n) _Pragma("unroll") for (int k = 0; k < 2; ++k) \
;         acc[ai][bj][m][n] = __builtin_amdgcn_mfma_f32_16x16x32_bf16(Bt[n][k], At[m][k], acc[ai][bj][m][n], 0, 0, 0); __builtin_amdgcn_s_setprio(0); } while (0)
; #define PG8_WAIT_V(n) asm volatile("s_waitcnt vmcnt(" #n ")" ::: "memory")
; #define PG8_WAIT_L(n) asm volatile("s_waitcnt lgkmcnt(" #n ")" ::: "memory")
; #define PG8_BAR __builtin_amdgcn_s_barrier()
; #define PG8_SCHED __builtin_amdgcn_sched_barrier(0)
; template <class Epi, class Sched, bool ALIGN_EPI = false, bool SP2 = false>
; __device__ __forceinline__ void gemm_phase(PG8_LAS unsigned char* lds, const Gemm g, const Sched& S, const Epi& E) {
;     ...
;             PG8_LDA(At, 1, 1); PG8_STAGE(PG8_SB(1, 0), b3, voffB); PG8_STAGE(PG8_SB(1, 1), b3 + hstep, voffB); PG8_STAGE(PG8_SA(1, 0), a3, voffA);
;             PG8_WAIT_V(8); PG8_WAIT_L(0); PG8_BAR; PG8_MMA(1, 0, At, B0); PG8_MMA(1, 1, At, B1); PG8_BAR; PG8_SCHED;
;     ...
;         if (!has_next) break;
; #pragma unroll
;         for (int a = 0; a < 2; ++a)
; #pragma unroll
;             for (int b = 0; b < 2; ++b)
; #pragma unroll
;                 for (int m = 0; m < 4; ++m)
; #pragma unroll
;                     for (int n = 0; n < 2; ++n) acc[a][b][m][n] = (f32x4){0.f, 0.f, 0.f, 0.f};
;         cur = nxt; cA = nA; cB = nB; ++ui;
	s_setprio 0
	s_add_i32 s22, s46, s27
	v_lshl_add_u64 v[180:181], v[180:181], 0, s[12:13]
	s_mov_b32 m0, s22
	ds_read_b128 v[184:187], v146 offset:49152
	ds_read_b128 v[188:191], v146 offset:50176
	ds_read_b128 v[192:195], v146 offset:51200
	ds_read_b128 v[196:199], v146 offset:52224
	ds_read_b128 v[200:203], v146 offset:53248
	ds_read_b128 v[204:207], v146 offset:54272
	ds_read_b128 v[208:211], v146 offset:55296
	ds_read_b128 v[212:215], v146 offset:56320
	global_load_lds_dwordx4 v[180:181], off
	s_add_i32 m0, s22, 0x2000
	s_add_u32 s20, s20, 0x160080
	v_lshl_add_u64 v[180:181], v[216:217], 0, s[12:13]
	s_addc_u32 s21, s21, 0
	s_add_i32 s22, s47, s27
	global_load_lds_dwordx4 v[180:181], off
	v_lshl_add_u64 v[180:181], s[20:21], 0, v[130:131]
	s_mov_b32 m0, s22
	s_nop 0
	global_load_lds_dwordx4 v[180:181], off
	v_lshl_add_u64 v[180:181], s[20:21], 0, v[128:129]
	s_add_i32 m0, s22, 0x2000
	s_nop 0
	global_load_lds_dwordx4 v[180:181], off
	v_lshl_add_u64 v[180:181], v[218:219], 0, s[12:13]
	s_mov_b32 m0, s35
	s_nop 0
	global_load_lds_dwordx4 v[180:181], off
	v_lshl_add_u64 v[180:181], v[220:221], 0, s[12:13]
	s_mov_b32 m0, s36
	s_nop 0
	global_load_lds_dwordx4 v[180:181], off
	s_waitcnt vmcnt(8)
	s_waitcnt lgkmcnt(0)
	s_setprio 1
	s_barrier
	v_mfma_f32_16x16x32_bf16 v[56:59], v[148:151], v[184:187], v[56:59]
	v_mfma_f32_16x16x32_bf16 v[60:63], v[156:159], v[184:187], v[60:63]
	v_mfma_f32_16x16x32_bf16 v[44:47], v[148:151], v[192:195], v[44:47]
	v_mfma_f32_16x16x32_bf16 v[40:43], v[156:159], v[192:195], v[40:43]
	v_mfma_f32_16x16x32_bf16 v[32:35], v[148:151], v[200:203], v[32:35]
	v_mfma_f32_16x16x32_bf16 v[24:27], v[156:159], v[200:203], v[24:27]
	v_mfma_f32_16x16x32_bf16 v[16:19], v[148:151], v[208:211], v[16:19]
	v_mfma_f32_16x16x32_bf16 v[8:11], v[156:159], v[208:211], v[8:11]
	v_mfma_f32_16x16x32_bf16 v[56:59], v[152:155], v[188:191], v[56:59]
	v_mfma_f32_16x16x32_bf16 v[60:63], v[160:163], v[188:191], v[60:63]
	v_mfma_f32_16x16x32_bf16 v[44:47], v[152:155], v[196:199], v[44:47]
	v_mfma_f32_16x16x32_bf16 v[40:43], v[160:163], v[196:199], v[40:43]
	v_mfma_f32_16x16x32_bf16 v[32:35], v[152:155], v[204:207], v[32:35]
	v_mfma_f32_16x16x32_bf16 v[24:27], v[160:163], v[204:207], v[24:27]
	v_mfma_f32_16x16x32_bf16 v[16:19], v[152:155], v[212:215], v[16:19]
	v_mfma_f32_16x16x32_bf16 v[8:11], v[160:163], v[212:215], v[8:11]
	v_mfma_f32_16x16x32_bf16 v[52:55], v[164:167], v[184:187], v[52:55]
	v_mfma_f32_16x16x32_bf16 v[48:51], v[172:175], v[184:187], v[48:51]
	v_mfma_f32_16x16x32_bf16 v[36:39], v[164:167], v[192:195], v[36:39]
	v_mfma_f32_16x16x32_bf16 v[28:31], v[172:175], v[192:195], v[28:31]
	v_mfma_f32_16x16x32_bf16 v[20:23], v[164:167], v[200:203], v[20:23]
	v_mfma_f32_16x16x32_bf16 v[12:15], v[172:175], v[200:203], v[12:15]
	v_mfma_f32_16x16x32_bf16 v[4:7], v[164:167], v[208:211], v[4:7]
	v_mfma_f32_16x16x32_bf16 v[0:3], v[172:175], v[208:211], v[0:3]
	v_mfma_f32_16x16x32_bf16 v[52:55], v[168:171], v[188:191], v[52:55]
	v_mfma_f32_16x16x32_bf16 v[48:51], v[176:179], v[188:191], v[48:51]
	v_mfma_f32_16x16x32_bf16 v[36:39], v[168:171], v[196:199], v[36:39]
	v_mfma_f32_16x16x32_bf16 v[28:31], v[176:179], v[196:199], v[28:31]
	v_mfma_f32_16x16x32_bf16 v[20:23], v[168:171], v[204:207], v[20:23]
	v_mfma_f32_16x16x32_bf16 v[12:15], v[176:179], v[204:207], v[12:15]
	v_mfma_f32_16x16x32_bf16 v[4:7], v[168:171], v[212:215], v[4:7]
	v_mfma_f32_16x16x32_bf16 v[0:3], v[176:179], v[212:215], v[0:3]
	s_barrier
	s_setprio 0
	s_add_i32 s45, s45, 2
	s_add_u32 s18, s18, 0x100
	s_addc_u32 s19, s19, 0
	s_cmpk_gt_u32 s45, 0x55
	s_cbranch_scc0 .LBB0_1205
	s_add_u32 s18, s15, 0xffffff00
	s_addc_u32 s19, s44, -1
	s_and_b64 vcc, exec, s[4:5]
	s_cbranch_vccnz .LBB0_1192
	v_mov_b32_e32 v0, 0
	s_mov_b32 s8, s42
	s_mov_b32 s25, s43
	s_mov_b64 s[10:11], s[16:17]
	s_mov_b32 s37, s14
	v_mov_b32_e32 v1, v0
	v_mov_b32_e32 v2, v0
	v_mov_b32_e32 v3, v0
	v_mov_b32_e32 v4, v0
	v_mov_b32_e32 v5, v0
	v_mov_b32_e32 v6, v0
	v_mov_b32_e32 v7, v0
	v_mov_b32_e32 v12, v0
	v_mov_b32_e32 v13, v0
	v_mov_b32_e32 v14, v0
	v_mov_b32_e32 v15, v0
	v_mov_b32_e32 v20, v0
	v_mov_b32_e32 v21, v0
	v_mov_b32_e32 v22, v0
	v_mov_b32_e32 v23, v0
	v_mov_b32_e32 v28, v0
	v_mov_b32_e32 v29, v0
	v_mov_b32_e32 v30, v0
	v_mov_b32_e32 v31, v0
	v_mov_b32_e32 v36, v0
	v_mov_b32_e32 v37, v0
	v_mov_b32_e32 v38, v0
	v_mov_b32_e32 v39, v0
	v_mov_b32_e32 v48, v0
	v_mov_b32_e32 v49, v0
	v_mov_b32_e32 v50, v0
	v_mov_b32_e32 v51, v0
	v_mov_b32_e32 v52, v0
	v_mov_b32_e32 v53, v0
	v_mov_b32_e32 v54, v0
	v_mov_b32_e32 v55, v0
	v_mov_b32_e32 v8, v0
	v_mov_b32_e32 v9, v0
	v_mov_b32_e32 v10, v0
	v_mov_b32_e32 v11, v0
	v_mov_b32_e32 v16, v0
	v_mov_b32_e32 v17, v0
	v_mov_b32_e32 v18, v0
	v_mov_b32_e32 v19, v0
	v_mov_b32_e32 v24, v0
	v_mov_b32_e32 v25, v0
	v_mov_b32_e32 v26, v0
	v_mov_b32_e32 v27, v0
	v_mov_b32_e32 v32, v0
	v_mov_b32_e32 v33, v0
	v_mov_b32_e32 v34, v0
	v_mov_b32_e32 v35, v0
	v_mov_b32_e32 v40, v0
	v_mov_b32_e32 v41, v0
	v_mov_b32_e32 v42, v0
	v_mov_b32_e32 v43, v0
	v_mov_b32_e32 v44, v0
	v_mov_b32_e32 v45, v0
	v_mov_b32_e32 v46, v0
	v_mov_b32_e32 v47, v0
	v_mov_b32_e32 v60, v0
	v_mov_b32_e32 v61, v0
	v_mov_b32_e32 v62, v0
	v_mov_b32_e32 v63, v0
	v_mov_b32_e32 v56, v0
	v_mov_b32_e32 v57, v0
	v_mov_b32_e32 v58, v0
	v_mov_b32_e32 v59, v0
	v_mov_b32_e32 v64, v0
	v_mov_b32_e32 v65, v0
	v_mov_b32_e32 v66, v0
	v_mov_b32_e32 v67, v0
	v_mov_b32_e32 v68, v0
	v_mov_b32_e32 v69, v0
	v_mov_b32_e32 v70, v0
	v_mov_b32_e32 v71, v0
	v_mov_b32_e32 v76, v0
	v_mov_b32_e32 v77, v0
	v_mov_b32_e32 v78, v0
	v_mov_b32_e32 v79, v0
	v_mov_b32_e32 v84, v0
	v_mov_b32_e32 v85, v0
	v_mov_b32_e32 v86, v0
	v_mov_b32_e32 v87, v0
	v_mov_b32_e32 v92, v0
	v_mov_b32_e32 v93, v0
	v_mov_b32_e32 v94, v0
	v_mov_b32_e32 v95, v0
	v_mov_b32_e32 v100, v0
	v_mov_b32_e32 v101, v0
	v_mov_b32_e32 v102, v0
	v_mov_b32_e32 v103, v0
	v_mov_b32_e32 v112, v0
	v_mov_b32_e32 v113, v0
	v_mov_b32_e32 v114, v0
	v_mov_b32_e32 v115, v0
	v_mov_b32_e32 v116, v0
	v_mov_b32_e32 v117, v0
	v_mov_b32_e32 v118, v0
	v_mov_b32_e32 v119, v0
	v_mov_b32_e32 v72, v0
	v_mov_b32_e32 v73, v0
	v_mov_b32_e32 v74, v0
	v_mov_b32_e32 v75, v0
	v_mov_b32_e32 v80, v0
	v_mov_b32_e32 v81, v0
	v_mov_b32_e32 v82, v0
	v_mov_b32_e32 v83, v0
	v_mov_b32_e32 v88, v0
	v_mov_b32_e32 v89, v0
	v_mov_b32_e32 v90, v0
	v_mov_b32_e32 v91, v0
	v_mov_b32_e32 v96, v0
	v_mov_b32_e32 v97, v0
	v_mov_b32_e32 v98, v0
	v_mov_b32_e32 v99, v0
	v_mov_b32_e32 v104, v0
	v_mov_b32_e32 v105, v0
	v_mov_b32_e32 v106, v0
	v_mov_b32_e32 v107, v0
	v_mov_b32_e32 v108, v0
	v_mov_b32_e32 v109, v0
	v_mov_b32_e32 v110, v0
	v_mov_b32_e32 v111, v0
	v_mov_b32_e32 v120, v0
	v_mov_b32_e32 v121, v0
	v_mov_b32_e32 v122, v0
	v_mov_b32_e32 v123, v0
	v_mov_b32_e32 v124, v0
	v_mov_b32_e32 v125, v0
	v_mov_b32_e32 v126, v0
	v_mov_b32_e32 v127, v0
	s_andn2_b64 vcc, exec, s[0:1]
	s_cbranch_vccnz .LBB0_1193
